# q-up epilogue rewritten (batched ssq/rope-table loads, batched lane exchanges); retention scan loop no longer waits for its state store; grid-size guards on the CU remap and the deferred-conversion dr
# baseline (speedup 1.0000x reference)
; #define G_STAGE(bufoff, gbase, voff) do { _Pragma("unroll") for (int _i = 0; _i < 2; ++_i) \
;         __builtin_amdgcn_global_load_lds((const unsigned*)((const char*)(gbase) + (voff)[_i]), (LAS unsigned*)(lds + (bufoff) + ldsw + _i * 8192), 16, 0, 0); } while (0)
; #define G_WAIT_V(n) asm volatile("s_waitcnt vmcnt(" #n ")" ::: "memory")
; #define G_BAR __builtin_amdgcn_s_barrier()
; template <class Epi, bool PERMROWS = false>
; DI void gemm_phase(LAS unsigned char* lds, const bf16_t* A, int lda, const bf16_t* Bt, int K, const Sched& S, const Epi& E) {
;     int tid = threadIdx.x; asm volatile("" : "+v"(tid));
;     const int wid = __builtin_amdgcn_readfirstlane(tid >> 6), lane = tid & 63, wr = wid >> 2, wc = wid & 3, fr = lane & 15, fq = lane >> 4;
;     const int ntF = K / BK, ntQ = K / (4 * BK); const size_t qstep = (size_t)(K / 4) * 2;
;     unsigned voffA[2], voffB[2];
; #pragma unroll
;     for (int i = 0; i < 2; ++i) { int R, C; stage_rc(tid * 16 + i * 8192, R, C); const int Ra = PERMROWS ? (((R >> 6) * 16 + (R & 15)) * 8 + ((R >> 4) & 3)) : R;
;         voffA[i] = (unsigned)(Ra * lda + C) * 2u; voffB[i] = (unsigned)(R * K + C) * 2u; }
;     const size_t kstep = (size_t)(BK * 2);
;     const size_t hstepA = (size_t)(PERMROWS ? 4 : HALF) * lda * 2, hstepB = (size_t)HALF * K * 2;
;     const size_t tstepA = (size_t)BM * lda * 2, tstepB = 2 * hstepB;
;     const unsigned ldsw = (unsigned)wid * 1024u;
;     const int aoff = lds_byte(wr * 64 + fr, fq * 8), boff = lds_byte(wc * 32 + fr, fq * 8);
;     ...
;     G_STAGE(G_SB(0, 0), cB, voffB); G_STAGE(G_SA(0, 0), cA, voffA); G_STAGE(G_SB(0, 1), cB + hstepB, voffB); G_STAGE(G_SA(0, 1), cA + hstepA, voffA);
;     if (wr == 1) G_BAR;
;     G_WAIT_V(4); G_BAR;
;     G_STAGE(G_SB(1, 0), cB + kstep, voffB); G_STAGE(G_SA(1, 0), cA + kstep, voffA); G_STAGE(G_SB(1, 1), cB + hstepB + kstep, voffB);
;     G_WAIT_V(6); G_BAR;
;     for (;;) {
;         const bool has_next = S.next(ui + 1, nxt);
;         const char* nA = has_next ? (const char*)A + (size_t)nxt.pm * tstepA + (nxt.kq >= 0 ? nxt.kq * qstep : 0) : cA; const char* nB = has_next ? (const char*)Bt + (size_t)nxt.pn * tstepB + (nxt.kq >= 0 ? nxt.kq * qstep : 0) : cB;
.LBB0_979:
	s_lshl_b32 s8, s8, 5
	s_mov_b64 s[16:17], 0x80
	s_and_b32 s57, s8, 0x60
	s_add_i32 m0, s31, 0x18000
	v_lshl_add_u64 v[6:7], v[6:7], 0, s[16:17]
	s_lshl_b32 s1, s7, 13
	s_lshl_b32 s18, s57, 7
	s_waitcnt vmcnt(4)
	s_barrier
	global_load_lds_dwordx4 v[6:7], off
	v_lshl_add_u64 v[4:5], v[4:5], 0, s[16:17]
	s_add_i32 m0, s31, 0x1a000
	s_add_i32 s62, s31, 0x8000
	s_add_i32 s63, s31, 0xa000
	global_load_lds_dwordx4 v[4:5], off
	v_lshl_add_u64 v[2:3], v[2:3], 0, s[16:17]
	s_mov_b32 m0, s62
	s_add_u32 s8, s12, 0x20080
	global_load_lds_dwordx4 v[2:3], off
	v_lshl_add_u64 v[0:1], v[0:1], 0, s[16:17]
	s_mov_b32 m0, s63
	s_addc_u32 s9, s13, 0
	global_load_lds_dwordx4 v[0:1], off
	s_add_i32 m0, s31, 0x1c000
	v_lshl_add_u64 v[0:1], s[8:9], 0, v[130:131]
	global_load_lds_dwordx4 v[0:1], off
	v_lshl_add_u64 v[0:1], s[8:9], 0, v[134:135]
	s_add_i32 m0, s31, 0x1e000
	v_bfe_u32 v2, v8, 4, 2
	global_load_lds_dwordx4 v[0:1], off
	v_and_b32_e32 v1, 15, v8
	v_lshlrev_b32_e32 v0, 4, v2
	v_lshlrev_b32_e32 v3, 2, v8
	v_lshl_or_b32 v139, s7, 6, v1
	v_lshl_or_b32 v1, v1, 6, v0
	v_and_b32_e32 v3, 32, v3
	v_lshlrev_b32_e32 v136, 3, v2
	v_bitop3_b32 v4, v1, s1, v3 bitop3:0xde
	v_bitop3_b32 v160, v1, s18, v3 bitop3:0xde
	v_lshlrev_b32_e32 v138, 2, v2
	v_lshl_add_u64 v[2:3], s[52:53], 0, v[136:137]
	s_mov_b64 s[8:9], 0x1a3a0000
	v_mov_b32_e32 v1, v137
	v_lshl_add_u64 v[140:141], v[2:3], 0, s[8:9]
	v_lshl_add_u64 v[0:1], s[52:53], 0, v[0:1]
	s_mov_b64 s[8:9], 0x200000
	s_mov_b32 s1, 0x18000
	v_lshl_add_u64 v[142:143], v[0:1], 0, s[8:9]
	v_lshrrev_b32_e32 v1, 1, v13
	v_mul_lo_u32 v0, v14, s6
	v_mad_u64_u32 v[0:1], s[8:9], v1, s1, v[0:1]
	v_or_b32_e32 v0, v0, v15
	v_add_lshl_u32 v136, v0, v16, 1
	v_lshrrev_b32_e32 v1, 1, v9
	v_mul_lo_u32 v0, v10, s6
	v_mad_u64_u32 v[0:1], s[6:7], v1, s1, v[0:1]
	s_waitcnt vmcnt(6)
	s_add_u32 s18, s52, 0x80000
	s_mov_b64 s[8:9], 0x180080
	v_or_b32_e32 v0, v0, v11
	s_addc_u32 s19, s53, 0
	v_lshl_add_u64 v[144:145], v[136:137], 0, s[8:9]
	v_add_lshl_u32 v136, v0, v12, 1
	s_add_i32 s70, 0, 0x10000
	s_add_i32 s71, 0, 0x14000
	v_mbcnt_lo_u32_b32 v0, -1, 0
	s_ashr_i32 s68, s33, 31
	s_ashr_i32 s69, s26, 31
	v_lshl_add_u64 v[146:147], v[136:137], 0, s[8:9]
	v_mov_b64_e32 v[148:149], 0x90
	v_mov_b64_e32 v[150:151], 0x8f
	v_add_u32_e32 v161, s70, v160
	v_add_u32_e32 v162, 0, v4
	v_add_u32_e32 v163, s71, v160
	v_mbcnt_hi_u32_b32 v164, -1, v0
	s_movk_i32 s72, 0xff
	v_mov_b32_e32 v165, 0x358637bd
	s_mov_b32 s73, 0x800000
	s_movk_i32 s74, 0x780
	s_mov_b32 s75, 0
	s_barrier
	s_branch .LBB0_982
.LBB0_981:
	s_and_b64 vcc, exec, s[6:7]
	s_mov_b32 s0, s20
	s_mov_b32 s14, s76
	s_mov_b64 s[12:13], s[34:35]
	s_mov_b64 s[10:11], s[22:23]
	s_cbranch_vccnz .LBB0_1051

; #define G_STAGE(bufoff, gbase, voff) do { _Pragma("unroll") for (int _i = 0; _i < 2; ++_i) \
;         __builtin_amdgcn_global_load_lds((const unsigned*)((const char*)(gbase) + (voff)[_i]), (LAS unsigned*)(lds + (bufoff) + ldsw + _i * 8192), 16, 0, 0); } while (0)
; #define G_LDA(dst, b, h) do { _Pragma("unroll") for (int m = 0; m < 4; ++m) _Pragma("unroll") for (int k = 0; k < 2; ++k) dst[m][k] = *(const LAS bf16x8*)(lds + G_SA(b, h) + aoff + m * 2048 + k * 1024); } while (0)
; #define G_LDB(dst, b, h) do { _Pragma("unroll") for (int n = 0; n < 2; ++n) _Pragma("unroll") for (int k = 0; k < 2; ++k) dst[n][k] = *(const LAS bf16x8*)(lds + G_SB(b, h) + boff + n * 2048 + k * 1024); } while (0)
; #define G_MMA(ai, bj, At, Bt_) do { __builtin_amdgcn_s_setprio(1); _Pragma("unroll") for (int m = 0; m < 4; ++m) _Pragma("unroll") for (int n = 0; n < 2; ++n) _Pragma("unroll") for (int k = 0; k < 2; ++k) \
;         acc[ai][bj][m][n] = __builtin_amdgcn_mfma_f32_16x16x32_bf16(Bt_[n][k], At[m][k], acc[ai][bj][m][n], 0, 0, 0); __builtin_amdgcn_s_setprio(0); } while (0)
; #define G_WAIT_V(n) asm volatile("s_waitcnt vmcnt(" #n ")" ::: "memory")
; #define G_WAIT_L(n) asm volatile("s_waitcnt lgkmcnt(" #n ")" ::: "memory")
; #define G_BAR __builtin_amdgcn_s_barrier()
; #define G_SCHED __builtin_amdgcn_sched_barrier(0)
; template <class Epi, bool PERMROWS = false>
; DI void gemm_phase(LAS unsigned char* lds, const bf16_t* A, int lda, const bf16_t* Bt, int K, const Sched& S, const Epi& E) {
;     ...
;             G_LDB(B0, 0, 0); G_SCHED; G_LDA(At, 0, 0); G_STAGE(G_SA(1, 1), a1 + hstepA, voffA);
;             G_WAIT_L(8); G_BAR; G_WAIT_L(0); G_MMA(0, 0, At, B0); G_BAR; G_SCHED;
;             G_LDB(B1, 0, 1); G_STAGE(G_SB(0, 0), b2, voffB);
;             G_BAR; G_WAIT_L(0); G_MMA(0, 1, At, B1); G_BAR;
;             G_LDA(At, 0, 1); G_STAGE(G_SA(0, 0), a2, voffA);
;             G_BAR; G_WAIT_L(0); G_MMA(1, 0, At, B0); G_BAR; G_SCHED;
;             G_STAGE(G_SB(0, 1), b2 + hstepB, voffB);
;             G_WAIT_V(6); G_BAR; G_MMA(1, 1, At, B1); G_BAR;
.LBB0_987:
	ds_read_b128 v[152:155], v161
	ds_read_b128 v[156:159], v161 offset:1024
	ds_read_b128 v[166:169], v161 offset:2048
	ds_read_b128 v[170:173], v161 offset:3072
	s_add_u32 s8, s10, 0x100
	s_addc_u32 s9, s11, 0
	s_cmp_eq_u32 s28, 4
	s_cselect_b32 s37, s23, s9
	s_cselect_b32 s36, s22, s8
	s_cselect_b32 s13, s1, s43
	s_cselect_b32 s12, s21, s42
	v_lshl_add_u64 v[208:209], s[10:11], 0, v[146:147]
	s_add_i32 m0, s31, 0xc000
	ds_read_b128 v[174:177], v162
	ds_read_b128 v[178:181], v162 offset:1024
	ds_read_b128 v[182:185], v162 offset:2048
	ds_read_b128 v[186:189], v162 offset:3072
	ds_read_b128 v[190:193], v162 offset:4096
	ds_read_b128 v[194:197], v162 offset:5120
	ds_read_b128 v[198:201], v162 offset:6144
	ds_read_b128 v[204:207], v162 offset:7168
	global_load_lds_dwordx4 v[208:209], off
	v_lshl_add_u64 v[208:209], s[10:11], 0, v[144:145]
	s_add_i32 m0, s31, 0xe000
	s_nop 0
	global_load_lds_dwordx4 v[208:209], off
	s_waitcnt lgkmcnt(8)
	s_barrier
	s_waitcnt lgkmcnt(0)
	s_setprio 1
	s_waitcnt lgkmcnt(0)
	v_mfma_f32_16x16x32_bf16 v[124:127], v[152:155], v[174:177], v[124:127]
	v_mfma_f32_16x16x32_bf16 v[120:123], v[166:169], v[174:177], v[120:123]
	v_mfma_f32_16x16x32_bf16 v[108:111], v[152:155], v[182:185], v[108:111]
	v_mfma_f32_16x16x32_bf16 v[104:107], v[166:169], v[182:185], v[104:107]
	v_mfma_f32_16x16x32_bf16 v[92:95], v[152:155], v[190:193], v[92:95]
	v_mfma_f32_16x16x32_bf16 v[88:91], v[166:169], v[190:193], v[88:91]
	v_mfma_f32_16x16x32_bf16 v[76:79], v[152:155], v[198:201], v[76:79]
	v_mfma_f32_16x16x32_bf16 v[72:75], v[166:169], v[198:201], v[72:75]
	v_mfma_f32_16x16x32_bf16 v[124:127], v[156:159], v[178:181], v[124:127]
	v_mfma_f32_16x16x32_bf16 v[120:123], v[170:173], v[178:181], v[120:123]
	v_mfma_f32_16x16x32_bf16 v[108:111], v[156:159], v[186:189], v[108:111]
	v_mfma_f32_16x16x32_bf16 v[104:107], v[170:173], v[186:189], v[104:107]
	v_mfma_f32_16x16x32_bf16 v[92:95], v[156:159], v[194:197], v[92:95]
	v_mfma_f32_16x16x32_bf16 v[88:91], v[170:173], v[194:197], v[88:91]
	v_mfma_f32_16x16x32_bf16 v[76:79], v[156:159], v[204:207], v[76:79]
	v_mfma_f32_16x16x32_bf16 v[72:75], v[170:173], v[204:207], v[72:75]
	s_setprio 0
	s_barrier
	s_add_i32 s10, s70, s30
	v_lshl_add_u64 v[224:225], s[12:13], 0, v[130:131]
	s_mov_b32 m0, s10
	ds_read_b128 v[208:211], v163
	ds_read_b128 v[212:215], v163 offset:1024
	ds_read_b128 v[216:219], v163 offset:2048
	ds_read_b128 v[220:223], v163 offset:3072
	global_load_lds_dwordx4 v[224:225], off
	v_lshl_add_u64 v[226:227], s[12:13], 0, v[134:135]
	s_add_i32 m0, s10, 0x2000
	s_nop 0
	global_load_lds_dwordx4 v[226:227], off
	s_barrier
	s_waitcnt lgkmcnt(0)
	s_setprio 1
	s_waitcnt lgkmcnt(0)
	v_mfma_f32_16x16x32_bf16 v[116:119], v[208:211], v[174:177], v[116:119]
	v_mfma_f32_16x16x32_bf16 v[112:115], v[216:219], v[174:177], v[112:115]
	v_mfma_f32_16x16x32_bf16 v[100:103], v[208:211], v[182:185], v[100:103]
	v_mfma_f32_16x16x32_bf16 v[96:99], v[216:219], v[182:185], v[96:99]
	v_mfma_f32_16x16x32_bf16 v[84:87], v[208:211], v[190:193], v[84:87]
	v_mfma_f32_16x16x32_bf16 v[80:83], v[216:219], v[190:193], v[80:83]
	v_mfma_f32_16x16x32_bf16 v[68:71], v[208:211], v[198:201], v[68:71]
	v_mfma_f32_16x16x32_bf16 v[64:67], v[216:219], v[198:201], v[64:67]
	v_mfma_f32_16x16x32_bf16 v[116:119], v[212:215], v[178:181], v[116:119]
	v_mfma_f32_16x16x32_bf16 v[112:115], v[220:223], v[178:181], v[112:115]
	v_mfma_f32_16x16x32_bf16 v[100:103], v[212:215], v[186:189], v[100:103]
	v_mfma_f32_16x16x32_bf16 v[96:99], v[220:223], v[186:189], v[96:99]
	v_mfma_f32_16x16x32_bf16 v[84:87], v[212:215], v[194:197], v[84:87]
	v_mfma_f32_16x16x32_bf16 v[80:83], v[220:223], v[194:197], v[80:83]
	v_mfma_f32_16x16x32_bf16 v[68:71], v[212:215], v[204:207], v[68:71]
	v_mfma_f32_16x16x32_bf16 v[64:67], v[220:223], v[204:207], v[64:67]
	s_setprio 0
	s_mov_b32 m0, s31
	v_lshl_add_u64 v[228:229], s[36:37], 0, v[128:129]
	s_barrier
	ds_read_b128 v[174:177], v162 offset:16384
	ds_read_b128 v[178:181], v162 offset:17408
	ds_read_b128 v[182:185], v162 offset:18432
	ds_read_b128 v[186:189], v162 offset:19456
	ds_read_b128 v[190:193], v162 offset:20480
	ds_read_b128 v[194:197], v162 offset:21504
	ds_read_b128 v[198:201], v162 offset:22528
	ds_read_b128 v[204:207], v162 offset:23552
	global_load_lds_dwordx4 v[228:229], off
	v_lshl_add_u64 v[230:231], s[36:37], 0, v[132:133]
	s_mov_b32 m0, s54
	s_nop 0
	global_load_lds_dwordx4 v[230:231], off
	s_barrier
	s_waitcnt lgkmcnt(0)
	s_setprio 1
	s_waitcnt lgkmcnt(0)
	v_mfma_f32_16x16x32_bf16 v[60:63], v[152:155], v[174:177], v[60:63]
	v_mfma_f32_16x16x32_bf16 v[56:59], v[166:169], v[174:177], v[56:59]
	v_mfma_f32_16x16x32_bf16 v[44:47], v[152:155], v[182:185], v[44:47]
	v_mfma_f32_16x16x32_bf16 v[40:43], v[166:169], v[182:185], v[40:43]
	v_mfma_f32_16x16x32_bf16 v[28:31], v[152:155], v[190:193], v[28:31]
	v_mfma_f32_16x16x32_bf16 v[24:27], v[166:169], v[190:193], v[24:27]
	v_mfma_f32_16x16x32_bf16 v[12:15], v[152:155], v[198:201], v[12:15]
	v_mfma_f32_16x16x32_bf16 v[8:11], v[166:169], v[198:201], v[8:11]
	v_mfma_f32_16x16x32_bf16 v[60:63], v[156:159], v[178:181], v[60:63]
	v_mfma_f32_16x16x32_bf16 v[56:59], v[170:173], v[178:181], v[56:59]
	v_mfma_f32_16x16x32_bf16 v[44:47], v[156:159], v[186:189], v[44:47]
	v_mfma_f32_16x16x32_bf16 v[40:43], v[170:173], v[186:189], v[40:43]
	v_mfma_f32_16x16x32_bf16 v[28:31], v[156:159], v[194:197], v[28:31]
	v_mfma_f32_16x16x32_bf16 v[24:27], v[170:173], v[194:197], v[24:27]
	v_mfma_f32_16x16x32_bf16 v[12:15], v[156:159], v[204:207], v[12:15]
	v_mfma_f32_16x16x32_bf16 v[8:11], v[170:173], v[204:207], v[8:11]
	s_setprio 0
	s_barrier
; #define G_STAGE(bufoff, gbase, voff) do { _Pragma("unroll") for (int _i = 0; _i < 2; ++_i) \
;         __builtin_amdgcn_global_load_lds((const unsigned*)((const char*)(gbase) + (voff)[_i]), (LAS unsigned*)(lds + (bufoff) + ldsw + _i * 8192), 16, 0, 0); } while (0)
; #define G_LDA(dst, b, h) do { _Pragma("unroll") for (int m = 0; m < 4; ++m) _Pragma("unroll") for (int k = 0; k < 2; ++k) dst[m][k] = *(const LAS bf16x8*)(lds + G_SA(b, h) + aoff + m * 2048 + k * 1024); } while (0)
; #define G_LDB(dst, b, h) do { _Pragma("unroll") for (int n = 0; n < 2; ++n) _Pragma("unroll") for (int k = 0; k < 2; ++k) dst[n][k] = *(const LAS bf16x8*)(lds + G_SB(b, h) + boff + n * 2048 + k * 1024); } while (0)
; #define G_MMA(ai, bj, At, Bt_) do { __builtin_amdgcn_s_setprio(1); _Pragma("unroll") for (int m = 0; m < 4; ++m) _Pragma("unroll") for (int n = 0; n < 2; ++n) _Pragma("unroll") for (int k = 0; k < 2; ++k) \
;         acc[ai][bj][m][n] = __builtin_amdgcn_mfma_f32_16x16x32_bf16(Bt_[n][k], At[m][k], acc[ai][bj][m][n], 0, 0, 0); __builtin_amdgcn_s_setprio(0); } while (0)
; #define G_WAIT_V(n) asm volatile("s_waitcnt vmcnt(" #n ")" ::: "memory")
; #define G_WAIT_L(n) asm volatile("s_waitcnt lgkmcnt(" #n ")" ::: "memory")
; #define G_BAR __builtin_amdgcn_s_barrier()
; #define G_SCHED __builtin_amdgcn_sched_barrier(0)
; template <class Epi, bool PERMROWS = false>
; DI void gemm_phase(LAS unsigned char* lds, const bf16_t* A, int lda, const bf16_t* Bt, int K, const Sched& S, const Epi& E) {
;     ...
;             G_STAGE(G_SB(0, 1), b2 + hstepB, voffB);
;             G_WAIT_V(6); G_BAR; G_MMA(1, 1, At, B1); G_BAR;
;             G_LDB(B0, 1, 0); G_SCHED; G_LDA(At, 1, 0); G_STAGE(G_SA(0, 1), a2 + hstepA, voffA);
;             G_WAIT_L(8); G_BAR; G_WAIT_L(0); G_MMA(0, 0, At, B0); G_BAR; G_SCHED;
;             G_LDB(B1, 1, 1); G_STAGE(G_SB(1, 0), b3, voffB);
;             G_BAR; G_WAIT_L(0); G_MMA(0, 1, At, B1); G_BAR;
;             G_LDA(At, 1, 1); G_STAGE(G_SA(1, 0), a3, voffA);
;             G_BAR; G_WAIT_L(0); G_MMA(1, 0, At, B0); G_BAR; G_SCHED;
	s_add_u32 s10, s12, 0x20000
	s_addc_u32 s11, s13, 0
	s_add_i32 s29, s71, s30
	v_lshl_add_u64 v[152:153], s[10:11], 0, v[130:131]
	s_mov_b32 m0, s29
	s_nop 0
	global_load_lds_dwordx4 v[152:153], off
	v_lshl_add_u64 v[152:153], s[10:11], 0, v[134:135]
	s_add_i32 m0, s29, 0x2000
	s_nop 0
	global_load_lds_dwordx4 v[152:153], off
	s_waitcnt vmcnt(6)
	s_barrier
	s_setprio 1
	v_mfma_f32_16x16x32_bf16 v[52:55], v[208:211], v[174:177], v[52:55]
	v_mfma_f32_16x16x32_bf16 v[48:51], v[216:219], v[174:177], v[48:51]
	v_mfma_f32_16x16x32_bf16 v[36:39], v[208:211], v[182:185], v[36:39]
	v_mfma_f32_16x16x32_bf16 v[32:35], v[216:219], v[182:185], v[32:35]
	v_mfma_f32_16x16x32_bf16 v[20:23], v[208:211], v[190:193], v[20:23]
	v_mfma_f32_16x16x32_bf16 v[16:19], v[216:219], v[190:193], v[16:19]
	v_mfma_f32_16x16x32_bf16 v[4:7], v[208:211], v[198:201], v[4:7]
	v_mfma_f32_16x16x32_bf16 v[0:3], v[216:219], v[198:201], v[0:3]
	v_mfma_f32_16x16x32_bf16 v[52:55], v[212:215], v[178:181], v[52:55]
	v_mfma_f32_16x16x32_bf16 v[48:51], v[220:223], v[178:181], v[48:51]
	v_mfma_f32_16x16x32_bf16 v[36:39], v[212:215], v[186:189], v[36:39]
	v_mfma_f32_16x16x32_bf16 v[32:35], v[220:223], v[186:189], v[32:35]
	v_mfma_f32_16x16x32_bf16 v[20:23], v[212:215], v[194:197], v[20:23]
	v_mfma_f32_16x16x32_bf16 v[16:19], v[220:223], v[194:197], v[16:19]
	v_mfma_f32_16x16x32_bf16 v[4:7], v[212:215], v[204:207], v[4:7]
	v_mfma_f32_16x16x32_bf16 v[0:3], v[220:223], v[204:207], v[0:3]
	s_setprio 0
	s_add_i32 s29, 0, 0x18000
	v_add_u32_e32 v136, s29, v160
	s_barrier
	ds_read_b128 v[152:155], v136
	ds_read_b128 v[156:159], v136 offset:1024
	ds_read_b128 v[166:169], v136 offset:2048
	ds_read_b128 v[170:173], v136 offset:3072
	s_add_u32 s10, s36, 0x180000
	s_addc_u32 s11, s37, 0
	s_mov_b32 m0, s55
	v_lshl_add_u64 v[208:209], s[10:11], 0, v[128:129]
	ds_read_b128 v[174:177], v162 offset:32768
	ds_read_b128 v[178:181], v162 offset:33792
	ds_read_b128 v[182:185], v162 offset:34816
	ds_read_b128 v[186:189], v162 offset:35840
	ds_read_b128 v[190:193], v162 offset:36864
	ds_read_b128 v[194:197], v162 offset:37888
	ds_read_b128 v[198:201], v162 offset:38912
	ds_read_b128 v[204:207], v162 offset:39936
	global_load_lds_dwordx4 v[208:209], off
	v_lshl_add_u64 v[208:209], s[10:11], 0, v[132:133]
	s_mov_b32 m0, s56
	s_nop 0
	global_load_lds_dwordx4 v[208:209], off
	s_waitcnt lgkmcnt(8)
	s_barrier
	s_waitcnt lgkmcnt(0)
	s_setprio 1
	s_waitcnt lgkmcnt(0)
	v_mfma_f32_16x16x32_bf16 v[124:127], v[152:155], v[174:177], v[124:127]
	v_mfma_f32_16x16x32_bf16 v[120:123], v[166:169], v[174:177], v[120:123]
	v_mfma_f32_16x16x32_bf16 v[108:111], v[152:155], v[182:185], v[108:111]
	v_mfma_f32_16x16x32_bf16 v[104:107], v[166:169], v[182:185], v[104:107]
	v_mfma_f32_16x16x32_bf16 v[92:95], v[152:155], v[190:193], v[92:95]
	v_mfma_f32_16x16x32_bf16 v[88:91], v[166:169], v[190:193], v[88:91]
	v_mfma_f32_16x16x32_bf16 v[76:79], v[152:155], v[198:201], v[76:79]
	v_mfma_f32_16x16x32_bf16 v[72:75], v[166:169], v[198:201], v[72:75]
	v_mfma_f32_16x16x32_bf16 v[124:127], v[156:159], v[178:181], v[124:127]
	v_mfma_f32_16x16x32_bf16 v[120:123], v[170:173], v[178:181], v[120:123]
	v_mfma_f32_16x16x32_bf16 v[108:111], v[156:159], v[186:189], v[108:111]
	v_mfma_f32_16x16x32_bf16 v[104:107], v[170:173], v[186:189], v[104:107]
	v_mfma_f32_16x16x32_bf16 v[92:95], v[156:159], v[194:197], v[92:95]
	v_mfma_f32_16x16x32_bf16 v[88:91], v[170:173], v[194:197], v[88:91]
	v_mfma_f32_16x16x32_bf16 v[76:79], v[156:159], v[204:207], v[76:79]
	v_mfma_f32_16x16x32_bf16 v[72:75], v[170:173], v[204:207], v[72:75]
	s_setprio 0
	s_barrier
	s_add_i32 s36, 0, 0x1c000
	s_add_i32 s10, s29, s30
	v_add_u32_e32 v136, s36, v160
	v_lshl_add_u64 v[224:225], v[224:225], 0, s[16:17]
	s_mov_b32 m0, s10
	ds_read_b128 v[208:211], v136
	ds_read_b128 v[212:215], v136 offset:1024
	ds_read_b128 v[216:219], v136 offset:2048
	ds_read_b128 v[220:223], v136 offset:3072
	global_load_lds_dwordx4 v[224:225], off
	v_lshl_add_u64 v[224:225], v[226:227], 0, s[16:17]
	s_add_i32 m0, s10, 0x2000
	s_nop 0
	global_load_lds_dwordx4 v[224:225], off
	s_barrier
	s_waitcnt lgkmcnt(0)
	s_setprio 1
	s_waitcnt lgkmcnt(0)
	v_mfma_f32_16x16x32_bf16 v[116:119], v[208:211], v[174:177], v[116:119]
	v_mfma_f32_16x16x32_bf16 v[112:115], v[216:219], v[174:177], v[112:115]
	v_mfma_f32_16x16x32_bf16 v[100:103], v[208:211], v[182:185], v[100:103]
	v_mfma_f32_16x16x32_bf16 v[96:99], v[216:219], v[182:185], v[96:99]
	v_mfma_f32_16x16x32_bf16 v[84:87], v[208:211], v[190:193], v[84:87]
	v_mfma_f32_16x16x32_bf16 v[80:83], v[216:219], v[190:193], v[80:83]
	v_mfma_f32_16x16x32_bf16 v[68:71], v[208:211], v[198:201], v[68:71]
	v_mfma_f32_16x16x32_bf16 v[64:67], v[216:219], v[198:201], v[64:67]
	v_mfma_f32_16x16x32_bf16 v[116:119], v[212:215], v[178:181], v[116:119]
	v_mfma_f32_16x16x32_bf16 v[112:115], v[220:223], v[178:181], v[112:115]
	v_mfma_f32_16x16x32_bf16 v[100:103], v[212:215], v[186:189], v[100:103]
	v_mfma_f32_16x16x32_bf16 v[96:99], v[220:223], v[186:189], v[96:99]
	v_mfma_f32_16x16x32_bf16 v[84:87], v[212:215], v[194:197], v[84:87]
	v_mfma_f32_16x16x32_bf16 v[80:83], v[220:223], v[194:197], v[80:83]
	v_mfma_f32_16x16x32_bf16 v[68:71], v[212:215], v[204:207], v[68:71]
	v_mfma_f32_16x16x32_bf16 v[64:67], v[220:223], v[204:207], v[64:67]
	s_setprio 0
	s_mov_b32 m0, s62
	v_lshl_add_u64 v[224:225], v[228:229], 0, s[16:17]
	s_barrier
	ds_read_b128 v[174:177], v162 offset:49152
	ds_read_b128 v[178:181], v162 offset:50176
	ds_read_b128 v[182:185], v162 offset:51200
	ds_read_b128 v[186:189], v162 offset:52224
	ds_read_b128 v[190:193], v162 offset:53248
	ds_read_b128 v[194:197], v162 offset:54272
	ds_read_b128 v[198:201], v162 offset:55296
	ds_read_b128 v[204:207], v162 offset:56320
	global_load_lds_dwordx4 v[224:225], off
	v_lshl_add_u64 v[224:225], v[230:231], 0, s[16:17]
	s_mov_b32 m0, s63
	s_nop 0
	global_load_lds_dwordx4 v[224:225], off
	s_barrier
; #define G_STAGE(bufoff, gbase, voff) do { _Pragma("unroll") for (int _i = 0; _i < 2; ++_i) \
;         __builtin_amdgcn_global_load_lds((const unsigned*)((const char*)(gbase) + (voff)[_i]), (LAS unsigned*)(lds + (bufoff) + ldsw + _i * 8192), 16, 0, 0); } while (0)
; #define G_MMA(ai, bj, At, Bt_) do { __builtin_amdgcn_s_setprio(1); _Pragma("unroll") for (int m = 0; m < 4; ++m) _Pragma("unroll") for (int n = 0; n < 2; ++n) _Pragma("unroll") for (int k = 0; k < 2; ++k) \
;         acc[ai][bj][m][n] = __builtin_amdgcn_mfma_f32_16x16x32_bf16(Bt_[n][k], At[m][k], acc[ai][bj][m][n], 0, 0, 0); __builtin_amdgcn_s_setprio(0); } while (0)
; #define G_WAIT_V(n) asm volatile("s_waitcnt vmcnt(" #n ")" ::: "memory")
; #define G_BAR __builtin_amdgcn_s_barrier()
; template <class Epi, bool PERMROWS = false>
; DI void gemm_phase(LAS unsigned char* lds, const bf16_t* A, int lda, const bf16_t* Bt, int K, const Sched& S, const Epi& E) {
;     ...
;             G_STAGE(G_SB(1, 1), b3 + hstepB, voffB);
;             G_WAIT_V(6); G_BAR; G_MMA(1, 1, At, B1); G_BAR;
; DI float row_rstd(const unsigned char* ws, int row, int which, int fq) {
;     const f32x4 s4 = *(const f32x4*)((const float*)(ws + WS_SSQ) + (size_t)row * 32 + which * 16 + fq * 4);
;     float ss = s4[0] + s4[1] + s4[2] + s4[3];
;     ss += __shfl_xor(ss, 16); ss += __shfl_xor(ss, 32);
;     return rsqrtf(ss * (1.f / 512.f) + 1e-6f);
;     DI void operator()(const f32x4 (&acc)[2][2][4][2], const Unit& u, int wr, int wc, int fr, int fq) const {
;     ...
;                 const int row = u.pm * BM + ai * HALF + wr * 64 + m * 16 + fr;
;                 const int r = row - b * RB; const bool lat = r >= CL; const int t = r - CL;
;                 const float rs = row_rstd(ws, row, 0, fq);
; #pragma unroll
;                 for (int bj = 0; bj < 2; ++bj) {
;                     const int colg = u.pn * BM + bj * HALF + wc * 32;
;                     if (colg >= 960) continue;
;                     f32x4 v0 = acc[ai][bj][m][0] * rs, v1 = acc[ai][bj][m][1] * rs;
;                     const int hc = colg % 192;
;                     if (hc >= 128 && lat) rope4(v0, v1, (const float*)(ws + WS_TABM) + ((size_t)t * 32 + ((hc - 128) >> 5) * 16 + 4 * fq) * 2);
	s_waitcnt lgkmcnt(0)
	s_setprio 1
	s_waitcnt lgkmcnt(0)
	v_mfma_f32_16x16x32_bf16 v[60:63], v[152:155], v[174:177], v[60:63]
	v_mfma_f32_16x16x32_bf16 v[56:59], v[166:169], v[174:177], v[56:59]
	v_mfma_f32_16x16x32_bf16 v[44:47], v[152:155], v[182:185], v[44:47]
	v_mfma_f32_16x16x32_bf16 v[40:43], v[166:169], v[182:185], v[40:43]
	v_mfma_f32_16x16x32_bf16 v[28:31], v[152:155], v[190:193], v[28:31]
	v_mfma_f32_16x16x32_bf16 v[24:27], v[166:169], v[190:193], v[24:27]
	v_mfma_f32_16x16x32_bf16 v[12:15], v[152:155], v[198:201], v[12:15]
	v_mfma_f32_16x16x32_bf16 v[8:11], v[166:169], v[198:201], v[8:11]
	v_mfma_f32_16x16x32_bf16 v[60:63], v[156:159], v[178:181], v[60:63]
	v_mfma_f32_16x16x32_bf16 v[56:59], v[170:173], v[178:181], v[56:59]
	v_mfma_f32_16x16x32_bf16 v[44:47], v[156:159], v[186:189], v[44:47]
	v_mfma_f32_16x16x32_bf16 v[40:43], v[170:173], v[186:189], v[40:43]
	v_mfma_f32_16x16x32_bf16 v[28:31], v[156:159], v[194:197], v[28:31]
	v_mfma_f32_16x16x32_bf16 v[24:27], v[170:173], v[194:197], v[24:27]
	v_mfma_f32_16x16x32_bf16 v[12:15], v[156:159], v[204:207], v[12:15]
	v_mfma_f32_16x16x32_bf16 v[8:11], v[170:173], v[204:207], v[8:11]
	s_setprio 0
	s_barrier
	s_add_u32 s10, s12, 0x20080
	s_addc_u32 s11, s13, 0
	s_add_i32 s12, s36, s30
	v_lshl_add_u64 v[152:153], s[10:11], 0, v[130:131]
	s_mov_b32 m0, s12
	s_nop 0
	global_load_lds_dwordx4 v[152:153], off
	v_lshl_add_u64 v[152:153], s[10:11], 0, v[134:135]
	s_add_i32 m0, s12, 0x2000
	s_nop 0
	global_load_lds_dwordx4 v[152:153], off
	s_waitcnt vmcnt(6)
	s_barrier
	s_setprio 1
	v_mfma_f32_16x16x32_bf16 v[52:55], v[208:211], v[174:177], v[52:55]
	v_mfma_f32_16x16x32_bf16 v[48:51], v[216:219], v[174:177], v[48:51]
	v_mfma_f32_16x16x32_bf16 v[36:39], v[208:211], v[182:185], v[36:39]
	v_mfma_f32_16x16x32_bf16 v[32:35], v[216:219], v[182:185], v[32:35]
	v_mfma_f32_16x16x32_bf16 v[20:23], v[208:211], v[190:193], v[20:23]
	v_mfma_f32_16x16x32_bf16 v[16:19], v[216:219], v[190:193], v[16:19]
	v_mfma_f32_16x16x32_bf16 v[4:7], v[208:211], v[198:201], v[4:7]
	v_mfma_f32_16x16x32_bf16 v[0:3], v[216:219], v[198:201], v[0:3]
	v_mfma_f32_16x16x32_bf16 v[52:55], v[212:215], v[178:181], v[52:55]
	v_mfma_f32_16x16x32_bf16 v[48:51], v[220:223], v[178:181], v[48:51]
	v_mfma_f32_16x16x32_bf16 v[36:39], v[212:215], v[186:189], v[36:39]
	v_mfma_f32_16x16x32_bf16 v[32:35], v[220:223], v[186:189], v[32:35]
	v_mfma_f32_16x16x32_bf16 v[20:23], v[212:215], v[194:197], v[20:23]
	v_mfma_f32_16x16x32_bf16 v[16:19], v[220:223], v[194:197], v[16:19]
	v_mfma_f32_16x16x32_bf16 v[4:7], v[212:215], v[204:207], v[4:7]
	v_mfma_f32_16x16x32_bf16 v[0:3], v[220:223], v[204:207], v[0:3]
	s_setprio 0
	s_add_i32 s28, s28, 2
	s_add_u32 s42, s42, 0x100
	s_addc_u32 s43, s43, 0
	s_cmp_gt_u32 s28, 5
	s_mov_b64 s[10:11], s[8:9]
	s_barrier
	s_cbranch_scc0 .LBB0_987
	v_and_b32_e32 v156, 15, v202
	v_bfe_u32 v157, v202, 8, 1
	v_lshl_add_u32 v252, v157, 6, v156
	v_bfe_u32 v136, v202, 4, 2
	v_bfe_u32 v157, v202, 6, 2
	v_and_b32_e32 v156, 63, v202
	v_readfirstlane_b32 s32, v157
	v_xor_b32_e32 v158, 16, v156
	v_xor_b32_e32 v159, 32, v156
	v_lshlrev_b32_e32 v158, 2, v158
	v_lshlrev_b32_e32 v159, 2, v159
	v_lshlrev_b32_e32 v156, 4, v136
	v_lshl_add_u32 v182, v252, 7, v156
	v_add_u32_e32 v183, 0x800, v182
	v_add_u32_e32 v184, 0x1000, v182
	v_add_u32_e32 v185, 0x1800, v182
	v_add_u32_e32 v186, 0x4000, v182
	v_add_u32_e32 v187, 0x4800, v182
	v_add_u32_e32 v188, 0x5000, v182
	v_add_u32_e32 v189, 0x5800, v182
	s_lshl_b32 s1, s14, 15
	s_add_u32 s8, s50, 0x200000
	s_addc_u32 s9, s51, 0
	s_add_u32 s8, s8, s1
	s_addc_u32 s9, s9, 0
	global_load_dwordx4 v[204:207], v182, s[8:9]
	global_load_dwordx4 v[208:211], v183, s[8:9]
	global_load_dwordx4 v[212:215], v184, s[8:9]
	global_load_dwordx4 v[216:219], v185, s[8:9]
	global_load_dwordx4 v[220:223], v186, s[8:9]
	global_load_dwordx4 v[224:227], v187, s[8:9]
	global_load_dwordx4 v[228:231], v188, s[8:9]
	global_load_dwordx4 v[232:235], v189, s[8:9]
	s_mul_i32 s1, s14, 57
	s_lshr_b32 s1, s1, 9
	s_mul_i32 s1, s1, 9
	s_sub_u32 s81, s14, s1
	s_lshl_b32 s1, s0, 8
	s_lshl_b32 s29, s32, 5
	s_add_u32 s1, s1, s29
	s_mov_b32 s82, -1
	s_mul_i32 s29, s1, 0xaaab
	s_lshr_b32 s29, s29, 23
	s_mul_i32 s29, s29, 0xc0
	s_sub_u32 s29, s1, s29
	s_cmpk_lt_u32 s29, 0x80
	s_cbranch_scc1 .Lqu0_nr0
	s_mov_b32 s82, 0
	s_sub_u32 s83, s29, 0x80
	s_lshr_b32 s83, s83, 5
.Lqu0_nr0:
	s_add_u32 s1, s1, 0x80
	s_mul_i32 s29, s1, 0xaaab
	s_lshr_b32 s29, s29, 23
	s_mul_i32 s29, s29, 0xc0
	s_sub_u32 s29, s1, s29
	s_cmpk_lt_u32 s29, 0x80
	s_cbranch_scc1 .Lqu0_nr1
	s_mov_b32 s82, 1
	s_sub_u32 s83, s29, 0x80
	s_lshr_b32 s83, s83, 5
.Lqu0_nr1:
	s_sub_u32 s1, s1, 0x80
	s_cmp_eq_u32 s81, 0
	s_cbranch_scc0 .Lqu0_lat
	s_mov_b32 s82, -1
.Lqu0_lat:
	v_mul_u32_u24_e32 v156, 0x780, v252
	v_lshl_add_u32 v198, v136, 3, v156
	s_lshl_b32 s29, s1, 1
	v_add_u32_e32 v198, s29, v198
	v_add_u32_e32 v199, 0x7800, v198
	v_add_u32_e32 v200, 0xf000, v198
	v_add_u32_e32 v201, 0x16800, v198
	v_add_u32_e32 v152, 0x3c000, v198
	v_add_u32_e32 v153, 0x43800, v198
	v_add_u32_e32 v154, 0x4b000, v198
	v_add_u32_e32 v155, 0x52800, v198
	s_cmp_lt_i32 s82, 0
	s_cbranch_scc1 .Lqu0_norope_a
	s_sub_u32 s29, s81, 1
	s_lshl_b32 s29, s29, 16
	s_lshl_b32 s83, s83, 7
	s_add_u32 s29, s29, s83
	v_lshlrev_b32_e32 v156, 5, v136
	v_lshl_add_u32 v190, v252, 8, v156
	v_add_u32_e32 v190, s29, v190
	v_add_u32_e32 v191, 0x1000, v190
	v_add_u32_e32 v192, 0x2000, v190
	v_add_u32_e32 v193, 0x3000, v190
	v_add_u32_e32 v194, 0x8000, v190
	v_add_u32_e32 v195, 0x9000, v190
	v_add_u32_e32 v196, 0xa000, v190
	v_add_u32_e32 v197, 0xb000, v190
	s_add_u32 s10, s50, 0x80000
	s_addc_u32 s11, s51, 0
	global_load_dwordx4 v[236:239], v190, s[10:11]
	global_load_dwordx4 v[240:243], v190, s[10:11] offset:16
	global_load_dwordx4 v[244:247], v191, s[10:11]
	global_load_dwordx4 v[248:251], v191, s[10:11] offset:16
	global_load_dwordx4 v[166:169], v192, s[10:11]
	global_load_dwordx4 v[170:173], v192, s[10:11] offset:16
	global_load_dwordx4 v[174:177], v193, s[10:11]
	global_load_dwordx4 v[178:181], v193, s[10:11] offset:16
	s_waitcnt vmcnt(8)
	s_branch .Lqu0_ssq

; DI float row_rstd(const unsigned char* ws, int row, int which, int fq) {
;     const f32x4 s4 = *(const f32x4*)((const float*)(ws + WS_SSQ) + (size_t)row * 32 + which * 16 + fq * 4);
;     float ss = s4[0] + s4[1] + s4[2] + s4[3];
;     ss += __shfl_xor(ss, 16); ss += __shfl_xor(ss, 32);
;     return rsqrtf(ss * (1.f / 512.f) + 1e-6f);
;     DI void operator()(const f32x4 (&acc)[2][2][4][2], const Unit& u, int wr, int wc, int fr, int fq) const {
;     ...
;                 const float rs = row_rstd(ws, row, 0, fq);
;     ...
;                     f32x4 v0 = acc[ai][bj][m][0] * rs, v1 = acc[ai][bj][m][1] * rs;
.Lqu0_ssq:
	v_add_f32_e32 v204, v204, v205
	v_add_f32_e32 v206, v206, v207
	v_add_f32_e32 v204, v204, v206
	v_add_f32_e32 v208, v208, v209
	v_add_f32_e32 v210, v210, v211
	v_add_f32_e32 v208, v208, v210
	v_add_f32_e32 v212, v212, v213
	v_add_f32_e32 v214, v214, v215
	v_add_f32_e32 v212, v212, v214
	v_add_f32_e32 v216, v216, v217
	v_add_f32_e32 v218, v218, v219
	v_add_f32_e32 v216, v216, v218
	v_add_f32_e32 v220, v220, v221
	v_add_f32_e32 v222, v222, v223
	v_add_f32_e32 v220, v220, v222
	v_add_f32_e32 v224, v224, v225
	v_add_f32_e32 v226, v226, v227
	v_add_f32_e32 v224, v224, v226
	v_add_f32_e32 v228, v228, v229
	v_add_f32_e32 v230, v230, v231
	v_add_f32_e32 v228, v228, v230
	v_add_f32_e32 v232, v232, v233
	v_add_f32_e32 v234, v234, v235
	v_add_f32_e32 v232, v232, v234
	ds_bpermute_b32 v205, v158, v204
	ds_bpermute_b32 v209, v158, v208
	ds_bpermute_b32 v213, v158, v212
	ds_bpermute_b32 v217, v158, v216
	ds_bpermute_b32 v221, v158, v220
	ds_bpermute_b32 v225, v158, v224
	ds_bpermute_b32 v229, v158, v228
	ds_bpermute_b32 v233, v158, v232
	s_waitcnt lgkmcnt(0)
	v_add_f32_e32 v204, v204, v205
	v_add_f32_e32 v208, v208, v209
	v_add_f32_e32 v212, v212, v213
	v_add_f32_e32 v216, v216, v217
	v_add_f32_e32 v220, v220, v221
	v_add_f32_e32 v224, v224, v225
	v_add_f32_e32 v228, v228, v229
	v_add_f32_e32 v232, v232, v233
	ds_bpermute_b32 v205, v159, v204
	ds_bpermute_b32 v209, v159, v208
	ds_bpermute_b32 v213, v159, v212
	ds_bpermute_b32 v217, v159, v216
	ds_bpermute_b32 v221, v159, v220
	ds_bpermute_b32 v225, v159, v224
	ds_bpermute_b32 v229, v159, v228
	ds_bpermute_b32 v233, v159, v232
	s_waitcnt lgkmcnt(0)
	s_mov_b32 s29, 0x3b000000
	v_mov_b32_e32 v156, 0x358637bd
	v_add_f32_e32 v204, v204, v205
	v_fma_f32 v204, v204, s29, v156
	v_add_f32_e32 v208, v208, v209
	v_fma_f32 v208, v208, s29, v156
	v_add_f32_e32 v212, v212, v213
	v_fma_f32 v212, v212, s29, v156
	v_add_f32_e32 v216, v216, v217
	v_fma_f32 v216, v216, s29, v156
	v_add_f32_e32 v220, v220, v221
	v_fma_f32 v220, v220, s29, v156
	v_add_f32_e32 v224, v224, v225
	v_fma_f32 v224, v224, s29, v156
	v_add_f32_e32 v228, v228, v229
	v_fma_f32 v228, v228, s29, v156
	v_add_f32_e32 v232, v232, v233
	v_fma_f32 v232, v232, s29, v156
	v_rsq_f32_e32 v182, v204
	v_rsq_f32_e32 v183, v208
	v_rsq_f32_e32 v184, v212
	v_rsq_f32_e32 v185, v216
	v_rsq_f32_e32 v186, v220
	v_rsq_f32_e32 v187, v224
	v_rsq_f32_e32 v188, v228
	v_rsq_f32_e32 v189, v232
	s_nop 0
	v_mul_f32_e32 v124, v124, v182
	v_mul_f32_e32 v125, v125, v182
	v_mul_f32_e32 v126, v126, v182
	v_mul_f32_e32 v127, v127, v182
	v_mul_f32_e32 v120, v120, v182
	v_mul_f32_e32 v121, v121, v182
	v_mul_f32_e32 v122, v122, v182
	v_mul_f32_e32 v123, v123, v182
	v_mul_f32_e32 v116, v116, v182
	v_mul_f32_e32 v117, v117, v182
	v_mul_f32_e32 v118, v118, v182
	v_mul_f32_e32 v119, v119, v182
	v_mul_f32_e32 v112, v112, v182
	v_mul_f32_e32 v113, v113, v182
	v_mul_f32_e32 v114, v114, v182
	v_mul_f32_e32 v115, v115, v182
	v_mul_f32_e32 v108, v108, v183
	v_mul_f32_e32 v109, v109, v183
	v_mul_f32_e32 v110, v110, v183
	v_mul_f32_e32 v111, v111, v183
	v_mul_f32_e32 v104, v104, v183
	v_mul_f32_e32 v105, v105, v183
	v_mul_f32_e32 v106, v106, v183
	v_mul_f32_e32 v107, v107, v183
	v_mul_f32_e32 v100, v100, v183
	v_mul_f32_e32 v101, v101, v183
	v_mul_f32_e32 v102, v102, v183
	v_mul_f32_e32 v103, v103, v183
	v_mul_f32_e32 v96, v96, v183
	v_mul_f32_e32 v97, v97, v183
	v_mul_f32_e32 v98, v98, v183
	v_mul_f32_e32 v99, v99, v183
	v_mul_f32_e32 v92, v92, v184
	v_mul_f32_e32 v93, v93, v184
	v_mul_f32_e32 v94, v94, v184
	v_mul_f32_e32 v95, v95, v184
	v_mul_f32_e32 v88, v88, v184
	v_mul_f32_e32 v89, v89, v184
	v_mul_f32_e32 v90, v90, v184
	v_mul_f32_e32 v91, v91, v184
	v_mul_f32_e32 v84, v84, v184
	v_mul_f32_e32 v85, v85, v184
	v_mul_f32_e32 v86, v86, v184
	v_mul_f32_e32 v87, v87, v184
	v_mul_f32_e32 v80, v80, v184
	v_mul_f32_e32 v81, v81, v184
	v_mul_f32_e32 v82, v82, v184
	v_mul_f32_e32 v83, v83, v184
	v_mul_f32_e32 v76, v76, v185
	v_mul_f32_e32 v77, v77, v185
	v_mul_f32_e32 v78, v78, v185
	v_mul_f32_e32 v79, v79, v185
	v_mul_f32_e32 v72, v72, v185
	v_mul_f32_e32 v73, v73, v185
	v_mul_f32_e32 v74, v74, v185
	v_mul_f32_e32 v75, v75, v185
	v_mul_f32_e32 v68, v68, v185
	v_mul_f32_e32 v69, v69, v185
	v_mul_f32_e32 v70, v70, v185
	v_mul_f32_e32 v71, v71, v185
	v_mul_f32_e32 v64, v64, v185
	v_mul_f32_e32 v65, v65, v185
	v_mul_f32_e32 v66, v66, v185
	v_mul_f32_e32 v67, v67, v185
	v_mul_f32_e32 v60, v60, v186
	v_mul_f32_e32 v61, v61, v186
	v_mul_f32_e32 v62, v62, v186
	v_mul_f32_e32 v63, v63, v186
	v_mul_f32_e32 v56, v56, v186
	v_mul_f32_e32 v57, v57, v186
	v_mul_f32_e32 v58, v58, v186
	v_mul_f32_e32 v59, v59, v186
	v_mul_f32_e32 v52, v52, v186
	v_mul_f32_e32 v53, v53, v186
	v_mul_f32_e32 v54, v54, v186
	v_mul_f32_e32 v55, v55, v186
	v_mul_f32_e32 v48, v48, v186
	v_mul_f32_e32 v49, v49, v186
	v_mul_f32_e32 v50, v50, v186
	v_mul_f32_e32 v51, v51, v186
	v_mul_f32_e32 v44, v44, v187
	v_mul_f32_e32 v45, v45, v187
	v_mul_f32_e32 v46, v46, v187
	v_mul_f32_e32 v47, v47, v187
	v_mul_f32_e32 v40, v40, v187
	v_mul_f32_e32 v41, v41, v187
	v_mul_f32_e32 v42, v42, v187
	v_mul_f32_e32 v43, v43, v187
	v_mul_f32_e32 v36, v36, v187
	v_mul_f32_e32 v37, v37, v187
	v_mul_f32_e32 v38, v38, v187
	v_mul_f32_e32 v39, v39, v187
	v_mul_f32_e32 v32, v32, v187
	v_mul_f32_e32 v33, v33, v187
	v_mul_f32_e32 v34, v34, v187
	v_mul_f32_e32 v35, v35, v187
	v_mul_f32_e32 v28, v28, v188
	v_mul_f32_e32 v29, v29, v188
	v_mul_f32_e32 v30, v30, v188
	v_mul_f32_e32 v31, v31, v188
	v_mul_f32_e32 v24, v24, v188
	v_mul_f32_e32 v25, v25, v188
	v_mul_f32_e32 v26, v26, v188
	v_mul_f32_e32 v27, v27, v188
	v_mul_f32_e32 v20, v20, v188
	v_mul_f32_e32 v21, v21, v188
	v_mul_f32_e32 v22, v22, v188
	v_mul_f32_e32 v23, v23, v188
	v_mul_f32_e32 v16, v16, v188
	v_mul_f32_e32 v17, v17, v188
	v_mul_f32_e32 v18, v18, v188
	v_mul_f32_e32 v19, v19, v188
	v_mul_f32_e32 v12, v12, v189
	v_mul_f32_e32 v13, v13, v189
	v_mul_f32_e32 v14, v14, v189
	v_mul_f32_e32 v15, v15, v189
	v_mul_f32_e32 v8, v8, v189
	v_mul_f32_e32 v9, v9, v189
	v_mul_f32_e32 v10, v10, v189
	v_mul_f32_e32 v11, v11, v189
	v_mul_f32_e32 v4, v4, v189
	v_mul_f32_e32 v5, v5, v189
	v_mul_f32_e32 v6, v6, v189
	v_mul_f32_e32 v7, v7, v189
	v_mul_f32_e32 v0, v0, v189
	v_mul_f32_e32 v1, v1, v189
	v_mul_f32_e32 v2, v2, v189
	v_mul_f32_e32 v3, v3, v189
	s_add_u32 s8, s50, 0x1a3a0000
	s_addc_u32 s9, s51, 0
	s_lshl_b32 s29, s14, 8
	s_mul_i32 s29, s29, 0x780
	s_add_u32 s8, s8, s29
	s_addc_u32 s9, s9, 0
	s_cmp_eq_u32 s82, 0
	s_cbranch_scc0 .Lqu0_nrp0
; DI void rope4(f32x4& v0, f32x4& v1, const float* tab  ) {
;     const f32x4 t0 = *(const f32x4*)tab, t1 = *(const f32x4*)(tab + 4);
;     const float c[4] = {t0[0], t0[2], t1[0], t1[2]}, s[4] = {t0[1], t0[3], t1[1], t1[3]};
; #pragma unroll
;     for (int j = 0; j < 4; ++j) { const float a = v0[j], b = v1[j]; v0[j] = a * c[j] - b * s[j]; v1[j] = b * c[j] + a * s[j]; }
; }
;     DI void operator()(const f32x4 (&acc)[2][2][4][2], const Unit& u, int wr, int wc, int fr, int fq) const {
;     ...
;                     if (hc >= 128 && lat) rope4(v0, v1, (const float*)(ws + WS_TABM) + ((size_t)t * 32 + ((hc - 128) >> 5) * 16 + 4 * fq) * 2);
	global_load_dwordx4 v[204:207], v194, s[10:11]
	global_load_dwordx4 v[208:211], v194, s[10:11] offset:16
	global_load_dwordx4 v[212:215], v195, s[10:11]
	global_load_dwordx4 v[216:219], v195, s[10:11] offset:16
	global_load_dwordx4 v[220:223], v196, s[10:11]
	global_load_dwordx4 v[224:227], v196, s[10:11] offset:16
	global_load_dwordx4 v[228:231], v197, s[10:11]
	global_load_dwordx4 v[232:235], v197, s[10:11] offset:16
	s_waitcnt vmcnt(8)
	v_mul_f32_e32 v156, v124, v237
	v_mul_f32_e32 v124, v124, v236
	v_fma_f32 v124, -v120, v237, v124
	v_fma_f32 v120, v120, v236, v156
	v_mul_f32_e32 v156, v125, v239
	v_mul_f32_e32 v125, v125, v238
	v_fma_f32 v125, -v121, v239, v125
	v_fma_f32 v121, v121, v238, v156
	v_mul_f32_e32 v156, v126, v241
	v_mul_f32_e32 v126, v126, v240
	v_fma_f32 v126, -v122, v241, v126
	v_fma_f32 v122, v122, v240, v156
	v_mul_f32_e32 v156, v127, v243
	v_mul_f32_e32 v127, v127, v242
	v_fma_f32 v127, -v123, v243, v127
	v_fma_f32 v123, v123, v242, v156
	v_mul_f32_e32 v156, v108, v245
	v_mul_f32_e32 v108, v108, v244
	v_fma_f32 v108, -v104, v245, v108
	v_fma_f32 v104, v104, v244, v156
	v_mul_f32_e32 v156, v109, v247
	v_mul_f32_e32 v109, v109, v246
	v_fma_f32 v109, -v105, v247, v109
	v_fma_f32 v105, v105, v246, v156
	v_mul_f32_e32 v156, v110, v249
	v_mul_f32_e32 v110, v110, v248
	v_fma_f32 v110, -v106, v249, v110
	v_fma_f32 v106, v106, v248, v156
	v_mul_f32_e32 v156, v111, v251
	v_mul_f32_e32 v111, v111, v250
	v_fma_f32 v111, -v107, v251, v111
	v_fma_f32 v107, v107, v250, v156
	v_mul_f32_e32 v156, v92, v167
	v_mul_f32_e32 v92, v92, v166
	v_fma_f32 v92, -v88, v167, v92
	v_fma_f32 v88, v88, v166, v156
	v_mul_f32_e32 v156, v93, v169
	v_mul_f32_e32 v93, v93, v168
	v_fma_f32 v93, -v89, v169, v93
	v_fma_f32 v89, v89, v168, v156
	v_mul_f32_e32 v156, v94, v171
	v_mul_f32_e32 v94, v94, v170
	v_fma_f32 v94, -v90, v171, v94
	v_fma_f32 v90, v90, v170, v156
	v_mul_f32_e32 v156, v95, v173
	v_mul_f32_e32 v95, v95, v172
	v_fma_f32 v95, -v91, v173, v95
	v_fma_f32 v91, v91, v172, v156
	v_mul_f32_e32 v156, v76, v175
	v_mul_f32_e32 v76, v76, v174
	v_fma_f32 v76, -v72, v175, v76
	v_fma_f32 v72, v72, v174, v156
	v_mul_f32_e32 v156, v77, v177
	v_mul_f32_e32 v77, v77, v176
	v_fma_f32 v77, -v73, v177, v77
	v_fma_f32 v73, v73, v176, v156
	v_mul_f32_e32 v156, v78, v179
	v_mul_f32_e32 v78, v78, v178
	v_fma_f32 v78, -v74, v179, v78
	v_fma_f32 v74, v74, v178, v156
	v_mul_f32_e32 v156, v79, v181
	v_mul_f32_e32 v79, v79, v180
	v_fma_f32 v79, -v75, v181, v79
	v_fma_f32 v75, v75, v180, v156
	s_waitcnt vmcnt(0)
	v_mul_f32_e32 v156, v60, v205
	v_mul_f32_e32 v60, v60, v204
	v_fma_f32 v60, -v56, v205, v60
	v_fma_f32 v56, v56, v204, v156
	v_mul_f32_e32 v156, v61, v207
	v_mul_f32_e32 v61, v61, v206
	v_fma_f32 v61, -v57, v207, v61
	v_fma_f32 v57, v57, v206, v156
	v_mul_f32_e32 v156, v62, v209
	v_mul_f32_e32 v62, v62, v208
	v_fma_f32 v62, -v58, v209, v62
	v_fma_f32 v58, v58, v208, v156
	v_mul_f32_e32 v156, v63, v211
	v_mul_f32_e32 v63, v63, v210
	v_fma_f32 v63, -v59, v211, v63
	v_fma_f32 v59, v59, v210, v156
	v_mul_f32_e32 v156, v44, v213
	v_mul_f32_e32 v44, v44, v212
	v_fma_f32 v44, -v40, v213, v44
	v_fma_f32 v40, v40, v212, v156
	v_mul_f32_e32 v156, v45, v215
	v_mul_f32_e32 v45, v45, v214
	v_fma_f32 v45, -v41, v215, v45
	v_fma_f32 v41, v41, v214, v156
	v_mul_f32_e32 v156, v46, v217
	v_mul_f32_e32 v46, v46, v216
	v_fma_f32 v46, -v42, v217, v46
	v_fma_f32 v42, v42, v216, v156
	v_mul_f32_e32 v156, v47, v219
	v_mul_f32_e32 v47, v47, v218
	v_fma_f32 v47, -v43, v219, v47
	v_fma_f32 v43, v43, v218, v156
	v_mul_f32_e32 v156, v28, v221
	v_mul_f32_e32 v28, v28, v220
	v_fma_f32 v28, -v24, v221, v28
	v_fma_f32 v24, v24, v220, v156
	v_mul_f32_e32 v156, v29, v223
	v_mul_f32_e32 v29, v29, v222
	v_fma_f32 v29, -v25, v223, v29
	v_fma_f32 v25, v25, v222, v156
	v_mul_f32_e32 v156, v30, v225
	v_mul_f32_e32 v30, v30, v224
	v_fma_f32 v30, -v26, v225, v30
	v_fma_f32 v26, v26, v224, v156
	v_mul_f32_e32 v156, v31, v227
	v_mul_f32_e32 v31, v31, v226
	v_fma_f32 v31, -v27, v227, v31
	v_fma_f32 v27, v27, v226, v156
	v_mul_f32_e32 v156, v12, v229
	v_mul_f32_e32 v12, v12, v228
	v_fma_f32 v12, -v8, v229, v12
	v_fma_f32 v8, v8, v228, v156
	v_mul_f32_e32 v156, v13, v231
	v_mul_f32_e32 v13, v13, v230
	v_fma_f32 v13, -v9, v231, v13
	v_fma_f32 v9, v9, v230, v156
	v_mul_f32_e32 v156, v14, v233
	v_mul_f32_e32 v14, v14, v232
	v_fma_f32 v14, -v10, v233, v14
	v_fma_f32 v10, v10, v232, v156
	v_mul_f32_e32 v156, v15, v235
	v_mul_f32_e32 v15, v15, v234
	v_fma_f32 v15, -v11, v235, v15
	v_fma_f32 v11, v11, v234, v156
; DI void rope4(f32x4& v0, f32x4& v1, const float* tab  ) {
;     const f32x4 t0 = *(const f32x4*)tab, t1 = *(const f32x4*)(tab + 4);
;     const float c[4] = {t0[0], t0[2], t1[0], t1[2]}, s[4] = {t0[1], t0[3], t1[1], t1[3]};
; #pragma unroll
;     for (int j = 0; j < 4; ++j) { const float a = v0[j], b = v1[j]; v0[j] = a * c[j] - b * s[j]; v1[j] = b * c[j] + a * s[j]; }
; }
;     DI void operator()(const f32x4 (&acc)[2][2][4][2], const Unit& u, int wr, int wc, int fr, int fq) const {
;     ...
;                     if (hc >= 128 && lat) rope4(v0, v1, (const float*)(ws + WS_TABM) + ((size_t)t * 32 + ((hc - 128) >> 5) * 16 + 4 * fq) * 2);
.Lqu0_nrp0:
	s_cmp_eq_u32 s82, 1
	s_cbranch_scc0 .Lqu0_nrp1
	global_load_dwordx4 v[204:207], v194, s[10:11]
	global_load_dwordx4 v[208:211], v194, s[10:11] offset:16
	global_load_dwordx4 v[212:215], v195, s[10:11]
	global_load_dwordx4 v[216:219], v195, s[10:11] offset:16
	global_load_dwordx4 v[220:223], v196, s[10:11]
	global_load_dwordx4 v[224:227], v196, s[10:11] offset:16
	global_load_dwordx4 v[228:231], v197, s[10:11]
	global_load_dwordx4 v[232:235], v197, s[10:11] offset:16
	s_waitcnt vmcnt(8)
	v_mul_f32_e32 v156, v116, v237
	v_mul_f32_e32 v116, v116, v236
	v_fma_f32 v116, -v112, v237, v116
	v_fma_f32 v112, v112, v236, v156
	v_mul_f32_e32 v156, v117, v239
	v_mul_f32_e32 v117, v117, v238
	v_fma_f32 v117, -v113, v239, v117
	v_fma_f32 v113, v113, v238, v156
	v_mul_f32_e32 v156, v118, v241
	v_mul_f32_e32 v118, v118, v240
	v_fma_f32 v118, -v114, v241, v118
	v_fma_f32 v114, v114, v240, v156
	v_mul_f32_e32 v156, v119, v243
	v_mul_f32_e32 v119, v119, v242
	v_fma_f32 v119, -v115, v243, v119
	v_fma_f32 v115, v115, v242, v156
	v_mul_f32_e32 v156, v100, v245
	v_mul_f32_e32 v100, v100, v244
	v_fma_f32 v100, -v96, v245, v100
	v_fma_f32 v96, v96, v244, v156
	v_mul_f32_e32 v156, v101, v247
	v_mul_f32_e32 v101, v101, v246
	v_fma_f32 v101, -v97, v247, v101
	v_fma_f32 v97, v97, v246, v156
	v_mul_f32_e32 v156, v102, v249
	v_mul_f32_e32 v102, v102, v248
	v_fma_f32 v102, -v98, v249, v102
	v_fma_f32 v98, v98, v248, v156
	v_mul_f32_e32 v156, v103, v251
	v_mul_f32_e32 v103, v103, v250
	v_fma_f32 v103, -v99, v251, v103
	v_fma_f32 v99, v99, v250, v156
	v_mul_f32_e32 v156, v84, v167
	v_mul_f32_e32 v84, v84, v166
	v_fma_f32 v84, -v80, v167, v84
	v_fma_f32 v80, v80, v166, v156
	v_mul_f32_e32 v156, v85, v169
	v_mul_f32_e32 v85, v85, v168
	v_fma_f32 v85, -v81, v169, v85
	v_fma_f32 v81, v81, v168, v156
	v_mul_f32_e32 v156, v86, v171
	v_mul_f32_e32 v86, v86, v170
	v_fma_f32 v86, -v82, v171, v86
	v_fma_f32 v82, v82, v170, v156
	v_mul_f32_e32 v156, v87, v173
	v_mul_f32_e32 v87, v87, v172
	v_fma_f32 v87, -v83, v173, v87
	v_fma_f32 v83, v83, v172, v156
	v_mul_f32_e32 v156, v68, v175
	v_mul_f32_e32 v68, v68, v174
	v_fma_f32 v68, -v64, v175, v68
	v_fma_f32 v64, v64, v174, v156
	v_mul_f32_e32 v156, v69, v177
	v_mul_f32_e32 v69, v69, v176
	v_fma_f32 v69, -v65, v177, v69
	v_fma_f32 v65, v65, v176, v156
	v_mul_f32_e32 v156, v70, v179
	v_mul_f32_e32 v70, v70, v178
	v_fma_f32 v70, -v66, v179, v70
	v_fma_f32 v66, v66, v178, v156
	v_mul_f32_e32 v156, v71, v181
	v_mul_f32_e32 v71, v71, v180
	v_fma_f32 v71, -v67, v181, v71
	v_fma_f32 v67, v67, v180, v156
	s_waitcnt vmcnt(0)
	v_mul_f32_e32 v156, v52, v205
	v_mul_f32_e32 v52, v52, v204
	v_fma_f32 v52, -v48, v205, v52
	v_fma_f32 v48, v48, v204, v156
	v_mul_f32_e32 v156, v53, v207
	v_mul_f32_e32 v53, v53, v206
	v_fma_f32 v53, -v49, v207, v53
	v_fma_f32 v49, v49, v206, v156
	v_mul_f32_e32 v156, v54, v209
	v_mul_f32_e32 v54, v54, v208
	v_fma_f32 v54, -v50, v209, v54
	v_fma_f32 v50, v50, v208, v156
	v_mul_f32_e32 v156, v55, v211
	v_mul_f32_e32 v55, v55, v210
	v_fma_f32 v55, -v51, v211, v55
	v_fma_f32 v51, v51, v210, v156
	v_mul_f32_e32 v156, v36, v213
	v_mul_f32_e32 v36, v36, v212
	v_fma_f32 v36, -v32, v213, v36
	v_fma_f32 v32, v32, v212, v156
	v_mul_f32_e32 v156, v37, v215
	v_mul_f32_e32 v37, v37, v214
	v_fma_f32 v37, -v33, v215, v37
	v_fma_f32 v33, v33, v214, v156
	v_mul_f32_e32 v156, v38, v217
	v_mul_f32_e32 v38, v38, v216
	v_fma_f32 v38, -v34, v217, v38
	v_fma_f32 v34, v34, v216, v156
	v_mul_f32_e32 v156, v39, v219
	v_mul_f32_e32 v39, v39, v218
	v_fma_f32 v39, -v35, v219, v39
	v_fma_f32 v35, v35, v218, v156
	v_mul_f32_e32 v156, v20, v221
	v_mul_f32_e32 v20, v20, v220
	v_fma_f32 v20, -v16, v221, v20
	v_fma_f32 v16, v16, v220, v156
	v_mul_f32_e32 v156, v21, v223
	v_mul_f32_e32 v21, v21, v222
	v_fma_f32 v21, -v17, v223, v21
	v_fma_f32 v17, v17, v222, v156
	v_mul_f32_e32 v156, v22, v225
	v_mul_f32_e32 v22, v22, v224
	v_fma_f32 v22, -v18, v225, v22
	v_fma_f32 v18, v18, v224, v156
	v_mul_f32_e32 v156, v23, v227
	v_mul_f32_e32 v23, v23, v226
	v_fma_f32 v23, -v19, v227, v23
	v_fma_f32 v19, v19, v226, v156
	v_mul_f32_e32 v156, v4, v229
	v_mul_f32_e32 v4, v4, v228
	v_fma_f32 v4, -v0, v229, v4
	v_fma_f32 v0, v0, v228, v156
	v_mul_f32_e32 v156, v5, v231
	v_mul_f32_e32 v5, v5, v230
	v_fma_f32 v5, -v1, v231, v5
	v_fma_f32 v1, v1, v230, v156
	v_mul_f32_e32 v156, v6, v233
	v_mul_f32_e32 v6, v6, v232
	v_fma_f32 v6, -v2, v233, v6
	v_fma_f32 v2, v2, v232, v156
	v_mul_f32_e32 v156, v7, v235
	v_mul_f32_e32 v7, v7, v234
	v_fma_f32 v7, -v3, v235, v7
	v_fma_f32 v3, v3, v234, v156
; DI void st_bf16x4(bf16_t* p, f32x4 v) { u32x2 w; w.x = cvt_pk_bf16(v[0], v[1]); w.y = cvt_pk_bf16(v[2], v[3]); *(u32x2*)p = w; }
;     DI void operator()(const f32x4 (&acc)[2][2][4][2], const Unit& u, int wr, int wc, int fr, int fq) const {
;     ...
;                     if (colg >= 960) continue;
;                     f32x4 v0 = acc[ai][bj][m][0] * rs, v1 = acc[ai][bj][m][1] * rs;
;                     const int hc = colg % 192;
;                     if (hc >= 128 && lat) rope4(v0, v1, (const float*)(ws + WS_TABM) + ((size_t)t * 32 + ((hc - 128) >> 5) * 16 + 4 * fq) * 2);
;                     st_bf16x4(Q + (size_t)row * 960 + colg + 4 * fq, v0); st_bf16x4(Q + (size_t)row * 960 + colg + 4 * fq + 16, v1);
.Lqu0_nrp1:
	s_cmpk_ge_u32 s1, 0x3c0
	s_cbranch_scc1 .Lqu0_nst0
	v_cvt_pk_bf16_f32 v124, v124, v125
	v_cvt_pk_bf16_f32 v125, v126, v127
	global_store_dwordx2 v198, v[124:125], s[8:9] offset:0
	v_cvt_pk_bf16_f32 v120, v120, v121
	v_cvt_pk_bf16_f32 v121, v122, v123
	global_store_dwordx2 v198, v[120:121], s[8:9] offset:32
	v_cvt_pk_bf16_f32 v108, v108, v109
	v_cvt_pk_bf16_f32 v109, v110, v111
	global_store_dwordx2 v199, v[108:109], s[8:9] offset:0
	v_cvt_pk_bf16_f32 v104, v104, v105
	v_cvt_pk_bf16_f32 v105, v106, v107
	global_store_dwordx2 v199, v[104:105], s[8:9] offset:32
	v_cvt_pk_bf16_f32 v92, v92, v93
	v_cvt_pk_bf16_f32 v93, v94, v95
	global_store_dwordx2 v200, v[92:93], s[8:9] offset:0
	v_cvt_pk_bf16_f32 v88, v88, v89
	v_cvt_pk_bf16_f32 v89, v90, v91
	global_store_dwordx2 v200, v[88:89], s[8:9] offset:32
	v_cvt_pk_bf16_f32 v76, v76, v77
	v_cvt_pk_bf16_f32 v77, v78, v79
	global_store_dwordx2 v201, v[76:77], s[8:9] offset:0
	v_cvt_pk_bf16_f32 v72, v72, v73
	v_cvt_pk_bf16_f32 v73, v74, v75
	global_store_dwordx2 v201, v[72:73], s[8:9] offset:32
	v_cvt_pk_bf16_f32 v60, v60, v61
	v_cvt_pk_bf16_f32 v61, v62, v63
	global_store_dwordx2 v152, v[60:61], s[8:9] offset:0
	v_cvt_pk_bf16_f32 v56, v56, v57
	v_cvt_pk_bf16_f32 v57, v58, v59
	global_store_dwordx2 v152, v[56:57], s[8:9] offset:32
	v_cvt_pk_bf16_f32 v44, v44, v45
	v_cvt_pk_bf16_f32 v45, v46, v47
	global_store_dwordx2 v153, v[44:45], s[8:9] offset:0
	v_cvt_pk_bf16_f32 v40, v40, v41
	v_cvt_pk_bf16_f32 v41, v42, v43
	global_store_dwordx2 v153, v[40:41], s[8:9] offset:32
	v_cvt_pk_bf16_f32 v28, v28, v29
	v_cvt_pk_bf16_f32 v29, v30, v31
	global_store_dwordx2 v154, v[28:29], s[8:9] offset:0
	v_cvt_pk_bf16_f32 v24, v24, v25
	v_cvt_pk_bf16_f32 v25, v26, v27
	global_store_dwordx2 v154, v[24:25], s[8:9] offset:32
	v_cvt_pk_bf16_f32 v12, v12, v13
	v_cvt_pk_bf16_f32 v13, v14, v15
	global_store_dwordx2 v155, v[12:13], s[8:9] offset:0
	v_cvt_pk_bf16_f32 v8, v8, v9
	v_cvt_pk_bf16_f32 v9, v10, v11
	global_store_dwordx2 v155, v[8:9], s[8:9] offset:32
.Lqu0_nst0:
	s_cmpk_ge_u32 s1, 0x340
	s_cbranch_scc1 .Lqu0_nst1
	v_cvt_pk_bf16_f32 v116, v116, v117
	v_cvt_pk_bf16_f32 v117, v118, v119
	global_store_dwordx2 v198, v[116:117], s[8:9] offset:256
	v_cvt_pk_bf16_f32 v112, v112, v113
	v_cvt_pk_bf16_f32 v113, v114, v115
	global_store_dwordx2 v198, v[112:113], s[8:9] offset:288
	v_cvt_pk_bf16_f32 v100, v100, v101
	v_cvt_pk_bf16_f32 v101, v102, v103
	global_store_dwordx2 v199, v[100:101], s[8:9] offset:256
	v_cvt_pk_bf16_f32 v96, v96, v97
	v_cvt_pk_bf16_f32 v97, v98, v99
	global_store_dwordx2 v199, v[96:97], s[8:9] offset:288
	v_cvt_pk_bf16_f32 v84, v84, v85
	v_cvt_pk_bf16_f32 v85, v86, v87
	global_store_dwordx2 v200, v[84:85], s[8:9] offset:256
	v_cvt_pk_bf16_f32 v80, v80, v81
	v_cvt_pk_bf16_f32 v81, v82, v83
	global_store_dwordx2 v200, v[80:81], s[8:9] offset:288
	v_cvt_pk_bf16_f32 v68, v68, v69
	v_cvt_pk_bf16_f32 v69, v70, v71
	global_store_dwordx2 v201, v[68:69], s[8:9] offset:256
	v_cvt_pk_bf16_f32 v64, v64, v65
	v_cvt_pk_bf16_f32 v65, v66, v67
	global_store_dwordx2 v201, v[64:65], s[8:9] offset:288
	v_cvt_pk_bf16_f32 v52, v52, v53
	v_cvt_pk_bf16_f32 v53, v54, v55
	global_store_dwordx2 v152, v[52:53], s[8:9] offset:256
	v_cvt_pk_bf16_f32 v48, v48, v49
	v_cvt_pk_bf16_f32 v49, v50, v51
	global_store_dwordx2 v152, v[48:49], s[8:9] offset:288
	v_cvt_pk_bf16_f32 v36, v36, v37
	v_cvt_pk_bf16_f32 v37, v38, v39
	global_store_dwordx2 v153, v[36:37], s[8:9] offset:256
	v_cvt_pk_bf16_f32 v32, v32, v33
	v_cvt_pk_bf16_f32 v33, v34, v35
	global_store_dwordx2 v153, v[32:33], s[8:9] offset:288
	v_cvt_pk_bf16_f32 v20, v20, v21
	v_cvt_pk_bf16_f32 v21, v22, v23
	global_store_dwordx2 v154, v[20:21], s[8:9] offset:256
	v_cvt_pk_bf16_f32 v16, v16, v17
	v_cvt_pk_bf16_f32 v17, v18, v19
	global_store_dwordx2 v154, v[16:17], s[8:9] offset:288
	v_cvt_pk_bf16_f32 v4, v4, v5
	v_cvt_pk_bf16_f32 v5, v6, v7
	global_store_dwordx2 v155, v[4:5], s[8:9] offset:256
	v_cvt_pk_bf16_f32 v0, v0, v1
	v_cvt_pk_bf16_f32 v1, v2, v3
	global_store_dwordx2 v155, v[0:1], s[8:9] offset:288
.Lqu0_nst1:
	s_branch .LBB0_981
.LBB0_1051:
	s_waitcnt vmcnt(0)
	s_cmpk_gt_u32 s2, 0xff
	s_cbranch_scc1 .LBB0_1053
	s_barrier

;     DI bool next(int i, Unit& u) const {
;         const long L = (long)i * G + c;
;         u.kq = -1;
;         if (split && L >= nwg) {
;             const int q = (int)(L - nwg); if (q >= 128) return false;
;             const int cu = q >> 2; u.kq = q & 3; u.pm = (cu >> 3) * 9; u.pn = cu & 7; return true;
;         }
;         if (L >= nwg) return false;
;         int wgid = (int)L; { const int q = nwg / NXCD, r = nwg % NXCD, xcd = wgid % NXCD, off = wgid / NXCD; wgid = (xcd < r ? xcd * (q + 1) : r * (q + 1) + (xcd - r) * q) + off; }
.LBB0_1054:
	s_add_u32 s89, s26, 180
	s_and_b32 s89, s89, 0xff
	s_cmpk_eq_u32 s33, 0x100
	s_cselect_b32 s89, s89, s26
	s_cmpk_lt_i32 s89, 0xb4
	v_mov_b32_e32 v8, v202
	s_cselect_b64 s[0:1], -1, 0
	v_writelane_b32 v253, s0, 19
	s_cmpk_gt_i32 s89, 0xb3
	v_readfirstlane_b32 s2, v8
	v_writelane_b32 v253, s1, 20
	s_cbranch_scc1 .LBB0_1076
	s_ashr_i32 s3, s26, 31
	s_lshr_b32 s0, s3, 29
	s_add_i32 s4, s89, s0
	s_and_b32 s0, s4, -8
	s_sub_i32 s5, s89, s0
	s_cmp_gt_i32 s5, 3
	s_cbranch_scc0 .LBB0_1057
	s_mul_i32 s0, s5, 22
	s_add_i32 s8, s0, 4
	s_cbranch_execz .LBB0_1058
	s_branch .LBB0_1059

;     DI bool next(int i, Unit& u) const {
;         const long L = (long)i * G + c;
;         u.kq = -1;
;         if (split && L >= nwg) {
;             const int q = (int)(L - nwg); if (q >= 128) return false;
;             const int cu = q >> 2; u.kq = q & 3; u.pm = (cu >> 3) * 9; u.pn = cu & 7; return true;
;         }
;         if (L >= nwg) return false;
;         int wgid = (int)L; { const int q = nwg / NXCD, r = nwg % NXCD, xcd = wgid % NXCD, off = wgid / NXCD; wgid = (xcd < r ? xcd * (q + 1) : r * (q + 1) + (xcd - r) * q) + off; }
; template <class Epi, bool PERMROWS = false>
; DI void gemm_phase(LAS unsigned char* lds, const bf16_t* A, int lda, const bf16_t* Bt, int K, const Sched& S, const Epi& E) {
;     ...
;         const bool has_next = S.next(ui + 1, nxt);
.LBB0_1062:
	s_add_i32 s43, s43, 1
	s_mul_i32 s0, s43, s62
	s_mul_hi_u32 s1, s43, s33
	s_add_i32 s1, s1, s0
	s_mul_i32 s0, s43, s33
	s_add_u32 s89, s26, 180
	s_and_b32 s89, s89, 0xff
	s_cmpk_eq_u32 s33, 0x100
	s_cselect_b32 s89, s89, s26
	s_add_u32 s0, s0, s89
	s_addc_u32 s1, s1, s3
	v_cmp_gt_i64_e64 s[6:7], s[0:1], v[148:149]
	v_cmp_lt_i64_e64 s[8:9], s[0:1], v[146:147]
	s_and_b64 vcc, exec, s[6:7]
	s_cbranch_vccnz .LBB0_1068
	s_ashr_i32 s1, s0, 31
	s_lshr_b32 s1, s1, 29
	s_add_i32 s14, s0, s1
	s_and_b32 s1, s14, -8
	s_sub_i32 s15, s0, s1
	s_cmp_gt_i32 s15, 3
	s_mov_b64 s[0:1], -1
	s_cbranch_scc0 .LBB0_1065
	s_mul_i32 s0, s15, 22
	s_add_i32 s16, s0, 4
	s_mov_b64 s[0:1], 0

; #define LAS __attribute__((address_space(3)))
; DI float ret_lg2(const Params& p, int l, int dir, int h) { return log1pf(-exp2f(p.in[12][(l * 2 + dir) * 5 + h])) * 1.4426950408889634f; }
; DI void phase_ret_scan(const Params& p, int l, LAS unsigned char* lds) {
;     ...
;         const int it = next_item(ctr, slot);
;         if (it >= 320) break;
;         const int dvb = it & 7, dir = (it >> 3) & 1, h = (it >> 4) % 5, b = it / 80, dkb = wid;
;         {
;             const bf16_t* vsrc = (const bf16_t*)(ws + WS_VTR) + ((size_t)b * 640 + h * 128 + dvb * 16) * RB;
;             u32x4 t[9];
; #pragma unroll
;             for (int i = 0; i < 9; ++i) { const int cid = tid + i * 512, rr = cid / 288, cc = cid % 288; t[i] = *(const u32x4*)(vsrc + (size_t)rr * RB + cc * 8); }
; #pragma unroll
;             for (int i = 0; i < 9; ++i) { const int cid = tid + i * 512, rr = cid / 288, cc = cid % 288; *(LAS u32x4*)(lds + rr * VRS + cc * 16) = t[i]; }
;         }
;         const float lg = ret_lg2(p, l, dir, h), gL = exp2f(lg * 128.f);
.LBB0_1082:
	s_or_b64 exec, exec, s[0:1]
	s_waitcnt vmcnt(0)
	v_mov_b32_e32 v0, s3
	s_waitcnt lgkmcnt(0)
	s_barrier
	ds_read_b32 v0, v0
	s_mov_b64 s[0:1], -1
	s_waitcnt lgkmcnt(0)
	v_cmp_lt_i32_e32 vcc, s4, v0
	v_readfirstlane_b32 s10, v0
	s_cbranch_vccnz .LBB0_1077
	s_ashr_i32 s0, s10, 4
	s_mul_hi_i32 s1, s0, 0x66666667
	s_lshr_b32 s6, s1, 31
	s_ashr_i32 s1, s1, 1
	s_add_i32 s1, s1, s6
	s_mul_i32 s1, s1, 5
	s_sub_i32 s6, s0, s1
	s_mul_hi_i32 s0, s10, 0x66666667
	s_lshr_b32 s1, s0, 31
	s_ashr_i32 s7, s0, 5
	s_add_i32 s7, s7, s1
	s_lshl_b32 s12, s6, 7
	s_mul_i32 s0, s7, 0x280
	s_ashr_i32 s13, s12, 31
	s_mul_hi_i32 s1, s7, 0x280
	s_add_u32 s0, s0, s12
	s_addc_u32 s1, s1, s13
	s_lshl_b32 s12, s10, 4
	s_and_b32 s17, s12, 0x70
	s_or_b32 s12, s0, s17
	s_mul_i32 s13, s1, 0x1200
	s_mul_hi_u32 s18, s12, 0x1200
	s_add_i32 s18, s18, s13
	s_mulk_i32 s12, 0x1200
	s_add_u32 s12, s87, s12
	s_addc_u32 s13, s91, s18
	s_bfe_u32 s10, s10, 0x10003
	v_lshl_add_u64 v[0:1], s[12:13], 0, v[44:45]
	v_lshl_add_u64 v[2:3], s[12:13], 0, v[48:49]
	v_lshl_add_u64 v[8:9], s[12:13], 0, v[52:53]
	s_mul_i32 s18, s10, 5
	v_lshl_add_u64 v[0:1], v[46:47], 1, v[0:1]
	v_lshl_add_u64 v[4:5], v[50:51], 1, v[2:3]
	v_lshl_add_u64 v[8:9], v[54:55], 1, v[8:9]
	v_lshl_add_u64 v[10:11], s[12:13], 0, v[56:57]
	s_add_i32 s18, s18, s6
	global_load_dwordx4 v[0:3], v[0:1], off
	s_nop 0
	global_load_dwordx4 v[4:7], v[4:5], off
	v_lshl_add_u64 v[10:11], v[58:59], 1, v[10:11]
	global_load_dwordx4 v[12:15], v[8:9], off
	global_load_dwordx4 v[16:19], v[10:11], off
	v_lshl_add_u64 v[8:9], s[12:13], 0, v[60:61]
	s_ashr_i32 s19, s18, 31
	v_lshl_add_u64 v[8:9], v[62:63], 1, v[8:9]
	v_lshl_add_u64 v[10:11], s[12:13], 0, v[64:65]
	s_lshl_b64 s[18:19], s[18:19], 2
	v_lshl_add_u64 v[10:11], v[66:67], 1, v[10:11]
	global_load_dwordx4 v[20:23], v[8:9], off
	global_load_dwordx4 v[24:27], v[10:11], off
	v_lshl_add_u64 v[8:9], s[12:13], 0, v[68:69]
	s_add_u32 s18, s60, s18
	v_lshl_add_u64 v[8:9], v[70:71], 1, v[8:9]
	v_lshl_add_u64 v[10:11], s[12:13], 0, v[72:73]
	s_addc_u32 s19, s61, s19
	v_lshl_add_u64 v[10:11], v[74:75], 1, v[10:11]
	global_load_dwordx4 v[28:31], v[8:9], off
	global_load_dwordx4 v[32:35], v[10:11], off
	global_load_dword v81, v41, s[18:19]
	v_lshl_add_u64 v[8:9], s[12:13], 0, v[76:77]
	v_lshl_add_u64 v[8:9], v[78:79], 1, v[8:9]
	global_load_dwordx4 v[8:11], v[8:9], off
	v_lshl_add_u64 v[166:167], v[38:39], 0, s[0:1]
	v_mad_u64_u32 v[84:85], s[0:1], v166, s2, v[42:43]
	v_mov_b32_e32 v40, v85
	v_mad_u64_u32 v[166:167], s[0:1], v167, s2, v[40:41]
	s_mul_i32 s7, s7, 5
	v_mov_b32_e32 v85, v166
	s_waitcnt vmcnt(0)
	ds_write_b128 v152, v[0:3]
	ds_write_b128 v153, v[4:7]
	ds_write_b128 v154, v[12:15]
	ds_write_b128 v155, v[16:19]
	ds_write_b128 v156, v[20:23]
	ds_write_b128 v157, v[24:27]
	ds_write_b128 v158, v[28:31]
	ds_write_b128 v159, v[32:35]
	v_cmp_gt_f32_e32 vcc, s5, v81
	s_and_b64 s[0:1], vcc, exec
	s_cselect_b32 s0, 0xffffffc0, 0
	v_cndmask_b32_e32 v0, 0, v162, vcc
	v_add_f32_e32 v0, v81, v0
	v_exp_f32_e32 v0, v0
	s_cmp_eq_u32 s10, 0
	s_cselect_b64 vcc, -1, 0
	s_add_i32 s7, s7, s6
	s_lshl_b32 s1, s7, 1
	s_or_b32 s1, s1, s10
	v_ldexp_f32 v22, v0, s0
	s_mul_hi_i32 s0, s1, 0x90000
	s_mul_i32 s1, s1, 0x90000
	v_sub_f32_e32 v6, 1.0, v22
	s_add_u32 s12, s92, s1
	v_add_f32_e32 v2, -1.0, v6
	v_frexp_mant_f32_e32 v7, v6
	v_cvt_f64_f32_e32 v[0:1], v6
	s_addc_u32 s13, s93, s0
	v_sub_f32_e32 v12, v2, v6
	v_frexp_exp_i32_f64_e32 v14, v[0:1]
	v_cmp_gt_f32_e64 s[0:1], s14, v7
	v_sub_f32_e64 v13, -v22, v2
	ds_write_b128 v160, v[8:11]
	v_add_f32_e32 v8, 1.0, v12
	v_subbrev_co_u32_e64 v14, s[0:1], 0, v14, s[0:1]
	v_add_f32_e32 v7, v13, v8
	v_sub_u32_e32 v8, 0, v14
	v_ldexp_f32 v6, v6, v8
	v_ldexp_f32 v7, v7, v8
	v_add_f32_e32 v8, -1.0, v6
	v_add_f32_e32 v9, 1.0, v6
	v_add_f32_e32 v10, 1.0, v8
	v_add_f32_e32 v11, -1.0, v9
	v_sub_f32_e32 v10, v6, v10
	v_sub_f32_e32 v6, v6, v11
	v_add_f32_e32 v6, v7, v6
	v_add_f32_e32 v15, v9, v6
	v_rcp_f32_e32 v17, v15
	v_add_f32_e32 v10, v7, v10
	v_sub_f32_e32 v7, v15, v9
	v_sub_f32_e32 v16, v6, v7
	v_add_f32_e32 v7, v8, v10
	v_mul_f32_e32 v19, v7, v17
	v_sub_f32_e32 v6, v7, v8
	v_mul_f32_e32 v8, v15, v19
	v_sub_f32_e32 v18, v10, v6
	v_fma_f32 v10, v19, v15, -v8
	v_fmac_f32_e32 v10, v19, v16
	v_add_f32_e32 v6, v8, v10
	v_sub_f32_e32 v9, v7, v6
	v_pk_add_f32 v[12:13], v[6:7], v[8:9] neg_lo:[0,1] neg_hi:[0,1]
	v_mov_b32_e32 v11, v6
	v_pk_add_f32 v[6:7], v[12:13], v[10:11] neg_lo:[0,1] neg_hi:[0,1]
	v_cmp_nlt_f32_e64 s[0:1], 1.0, v22
	v_add_f32_e32 v7, v18, v7
	v_add_f32_e32 v6, v6, v7
	v_add_f32_e32 v7, v9, v6
	v_mul_f32_e32 v18, v17, v7
	v_mul_f32_e32 v8, v15, v18
	v_fma_f32 v10, v18, v15, -v8
	v_fmac_f32_e32 v10, v18, v16
	v_sub_f32_e32 v9, v9, v7
	v_add_f32_e32 v15, v6, v9
	v_add_f32_e32 v6, v8, v10
	v_sub_f32_e32 v9, v7, v6
	v_pk_add_f32 v[12:13], v[6:7], v[8:9] neg_lo:[0,1] neg_hi:[0,1]
	v_mov_b32_e32 v11, v6
	v_pk_add_f32 v[6:7], v[12:13], v[10:11] neg_lo:[0,1] neg_hi:[0,1]
	s_lshl_b32 s10, s10, 8
	v_add_f32_e32 v7, v15, v7
	v_add_f32_e32 v6, v6, v7
	v_add_f32_e32 v7, v19, v18
	v_add_f32_e32 v6, v9, v6
	v_sub_f32_e32 v8, v7, v19
	v_mul_f32_e32 v6, v17, v6
	v_sub_f32_e32 v8, v18, v8
	v_add_f32_e32 v8, v8, v6
	v_add_f32_e32 v10, v7, v8
	v_mul_f32_e32 v11, v10, v10
	v_fmamk_f32 v6, v11, 0x3e9b6dac, v161
	v_fmaak_f32 v83, v11, v6, 0x3f2aaada
	v_cvt_f32_i32_e32 v6, v14
	v_sub_f32_e32 v7, v10, v7
	v_sub_f32_e32 v7, v8, v7
	v_ldexp_f32 v12, v7, 1
	v_mul_f32_e32 v7, v10, v11
	v_ldexp_f32 v9, v10, 1
	v_pk_mul_f32 v[10:11], v[6:7], v[82:83]
	v_lshl_add_u64 v[4:5], v[84:85], 0, s[10:11]
	v_fma_f32 v8, v6, s15, -v10
	v_fmac_f32_e32 v8, 0xb102e308, v6
	v_pk_add_f32 v[6:7], v[10:11], v[8:9]
; #define LAS __attribute__((address_space(3)))
; DI float ret_lg2(const Params& p, int l, int dir, int h) { return log1pf(-exp2f(p.in[12][(l * 2 + dir) * 5 + h])) * 1.4426950408889634f; }
; DI void phase_ret_scan(const Params& p, int l, LAS unsigned char* lds) {
;     ...
;         const float lg = ret_lg2(p, l, dir, h), gL = exp2f(lg * 128.f);
;         float wt[4][8];
; #pragma unroll
;         for (int ks = 0; ks < 4; ++ks)
; #pragma unroll
;             for (int e = 0; e < 8; ++e) { const int pp = ks * 32 + q4 * 8 + e; wt[ks][e] = exp2f(lg * (float)(dir == 0 ? 127 - pp : pp)); }
;         const bf16_t* kt = (const bf16_t*)(ws + WS_KTR) + ((size_t)b * 640 + h * 128 + dkb * 16 + r16) * RB + q4 * 8;
;         const LAS unsigned char* vl = lds + r16 * VRS + q4 * 16;
;         bf16_t* sb = (bf16_t*)(ws + WS_S) + ((size_t)((b * 5 + h) * 2 + dir) * 18) * 16384 + (dvb * 16 + r16) * 128 + dkb * 16 + q4 * 4;
;         f32x4 st = (f32x4){0.f, 0.f, 0.f, 0.f};
;         bf16x8 ca[4];
;         { const int c0 = dir == 0 ? 0 : 1;
; #pragma unroll
;           for (int ks = 0; ks < 4; ++ks) ca[ks] = *(const bf16x8*)(kt + c0 * 128 + ks * 32); }
	global_load_dwordx4 v[0:3], v[4:5], off
	v_sub_f32_e32 v9, v7, v9
	v_sub_f32_e32 v9, v11, v9
	v_add_f32_e32 v13, v12, v9
	v_mov_b32_e32 v12, v10
	v_pk_add_f32 v[10:11], v[6:7], v[10:11] neg_lo:[0,1] neg_hi:[0,1]
	v_pk_add_f32 v[14:15], v[6:7], v[12:13]
	v_mov_b32_e32 v9, v6
	v_mov_b32_e32 v11, v15
	v_pk_add_f32 v[16:17], v[8:9], v[10:11] neg_lo:[0,1] neg_hi:[0,1]
	v_pk_add_f32 v[8:9], v[8:9], v[10:11]
	v_mov_b32_e32 v20, v7
	v_pk_add_f32 v[10:11], v[8:9], v[6:7] op_sel:[1,0] op_sel_hi:[0,1] neg_lo:[0,1] neg_hi:[0,1]
	v_pk_add_f32 v[18:19], v[14:15], v[10:11] op_sel_hi:[1,0] neg_lo:[0,1] neg_hi:[0,1]
	v_mov_b32_e32 v14, v15
	v_mov_b32_e32 v15, v9
	v_mov_b32_e32 v21, v10
	v_pk_add_f32 v[10:11], v[14:15], v[20:21] neg_lo:[0,1] neg_hi:[0,1]
	v_mov_b32_e32 v12, v13
	v_mov_b32_e32 v13, v6
	v_pk_add_f32 v[6:7], v[12:13], v[10:11] neg_lo:[0,1] neg_hi:[0,1]
	v_mov_b32_e32 v18, v16
	v_pk_add_f32 v[10:11], v[18:19], v[6:7]
	v_mov_b32_e32 v17, v9
	v_pk_add_f32 v[12:13], v[10:11], v[10:11] op_sel:[0,1] op_sel_hi:[1,0]
	v_mov_b32_e32 v81, v41
	v_pk_add_f32 v[8:9], v[8:9], v[12:13] op_sel:[1,0] op_sel_hi:[0,1]
	v_mov_b32_e32 v11, v8
	v_pk_add_f32 v[14:15], v[10:11], v[16:17] neg_lo:[0,1] neg_hi:[0,1]
	v_mov_b32_e32 v7, v12
	v_sub_f32_e32 v9, v10, v14
	v_pk_add_f32 v[6:7], v[6:7], v[14:15] neg_lo:[0,1] neg_hi:[0,1]
	v_sub_f32_e32 v9, v16, v9
	v_add_f32_e32 v6, v6, v9
	v_add_f32_e32 v6, v6, v7
	v_add_f32_e32 v6, v8, v6
	v_cndmask_b32_e64 v6, v163, v6, s[0:1]
	v_cmp_neq_f32_e64 s[0:1], 1.0, v22
	s_mov_b32 s10, 0
	s_nop 0
	v_cndmask_b32_e64 v6, v164, v6, s[0:1]
	v_cmp_lt_f32_e64 s[0:1], |v22|, s16
	s_nop 1
	v_cndmask_b32_e64 v6, v6, -v22, s[0:1]
	v_mul_f32_e32 v18, 0x3fb8aa3b, v6
	v_cndmask_b32_e32 v6, v87, v89, vcc
	v_cvt_f32_ubyte0_e32 v6, v6
	v_mul_f32_e32 v7, v18, v6
	v_cmp_gt_f32_e64 s[0:1], s5, v7
	v_mul_f32_e32 v19, 0x43000000, v18
	v_mov_b32_e32 v22, 0
	v_cndmask_b32_e64 v7, 0, v162, s[0:1]
	v_fmac_f32_e32 v7, v18, v6
	v_exp_f32_e32 v6, v7
	v_cndmask_b32_e64 v7, 0, v165, s[0:1]
	v_mov_b32_e32 v23, v22
	v_mov_b32_e32 v24, v22
	v_ldexp_f32 v26, v6, v7
	v_cndmask_b32_e32 v6, v90, v91, vcc
	v_cvt_f32_ubyte0_e32 v6, v6
	v_mul_f32_e32 v7, v18, v6
	v_cmp_gt_f32_e64 s[0:1], s5, v7
	v_mov_b32_e32 v25, v22
	s_nop 0
	v_cndmask_b32_e64 v7, 0, v162, s[0:1]
	v_fmac_f32_e32 v7, v18, v6
	v_exp_f32_e32 v6, v7
	v_cndmask_b32_e32 v7, v92, v93, vcc
	v_cvt_f32_ubyte0_e32 v7, v7
	v_mul_f32_e32 v8, v18, v7
	v_cmp_gt_f32_e64 s[6:7], s5, v8
	s_nop 1
	v_cndmask_b32_e64 v8, 0, v162, s[6:7]
	v_fmac_f32_e32 v8, v18, v7
	v_exp_f32_e32 v7, v8
	v_cndmask_b32_e64 v8, 0, v165, s[0:1]
	v_ldexp_f32 v27, v6, v8
	v_cndmask_b32_e64 v6, 0, v165, s[6:7]
	v_ldexp_f32 v28, v7, v6
	v_cndmask_b32_e32 v6, v94, v95, vcc
	v_cvt_f32_ubyte0_e32 v6, v6
	v_mul_f32_e32 v7, v18, v6
	v_cmp_gt_f32_e64 s[0:1], s5, v7
	s_nop 1
	v_cndmask_b32_e64 v7, 0, v162, s[0:1]
	v_fmac_f32_e32 v7, v18, v6
	v_exp_f32_e32 v6, v7
	v_cndmask_b32_e32 v7, v96, v97, vcc
	v_cvt_f32_ubyte0_e32 v7, v7
	v_mul_f32_e32 v8, v18, v7
	v_cmp_gt_f32_e64 s[6:7], s5, v8
	s_nop 1
	v_cndmask_b32_e64 v8, 0, v162, s[6:7]
	v_fmac_f32_e32 v8, v18, v7
	v_exp_f32_e32 v7, v8
	v_cndmask_b32_e64 v8, 0, v165, s[0:1]
	v_ldexp_f32 v29, v6, v8
	v_cndmask_b32_e64 v6, 0, v165, s[6:7]
	v_ldexp_f32 v30, v7, v6
	v_cndmask_b32_e32 v6, v98, v99, vcc
	v_cvt_f32_ubyte0_e32 v6, v6
	v_mul_f32_e32 v7, v18, v6
	v_cmp_gt_f32_e64 s[0:1], s5, v7
	s_nop 1
	v_cndmask_b32_e64 v7, 0, v162, s[0:1]
	v_fmac_f32_e32 v7, v18, v6
	v_exp_f32_e32 v6, v7
	v_cndmask_b32_e32 v7, v100, v101, vcc
	v_cvt_f32_ubyte0_e32 v7, v7
	v_mul_f32_e32 v8, v18, v7
	v_cmp_gt_f32_e64 s[6:7], s5, v8
	s_nop 1
	v_cndmask_b32_e64 v8, 0, v162, s[6:7]
	v_fmac_f32_e32 v8, v18, v7
	v_exp_f32_e32 v7, v8
	v_cndmask_b32_e64 v8, 0, v165, s[0:1]
	v_ldexp_f32 v31, v6, v8
	v_cndmask_b32_e64 v6, 0, v165, s[6:7]
	v_ldexp_f32 v32, v7, v6
	v_cndmask_b32_e32 v6, v102, v103, vcc
	v_cvt_f32_ubyte0_e32 v6, v6
	v_mul_f32_e32 v7, v18, v6
	v_cmp_gt_f32_e64 s[0:1], s5, v7
	s_nop 1
	v_cndmask_b32_e64 v7, 0, v162, s[0:1]
	v_fmac_f32_e32 v7, v18, v6
	v_exp_f32_e32 v6, v7
	v_cndmask_b32_e32 v7, v104, v105, vcc
	v_cvt_f32_ubyte0_e32 v7, v7
	v_mul_f32_e32 v8, v18, v7
	v_cmp_gt_f32_e64 s[6:7], s5, v8
	s_nop 1
	v_cndmask_b32_e64 v8, 0, v162, s[6:7]
	v_fmac_f32_e32 v8, v18, v7
	v_exp_f32_e32 v7, v8
	v_cndmask_b32_e64 v8, 0, v165, s[0:1]
	v_ldexp_f32 v33, v6, v8
	v_cndmask_b32_e64 v6, 0, v165, s[6:7]
	v_ldexp_f32 v34, v7, v6
	v_cndmask_b32_e32 v6, v106, v107, vcc
	v_cvt_f32_ubyte0_e32 v6, v6
	v_mul_f32_e32 v7, v18, v6
	v_cmp_gt_f32_e64 s[0:1], s5, v7
	s_nop 1
	v_cndmask_b32_e64 v7, 0, v162, s[0:1]
	v_fmac_f32_e32 v7, v18, v6
	v_exp_f32_e32 v6, v7
	v_cndmask_b32_e32 v7, v108, v109, vcc
	v_cvt_f32_ubyte0_e32 v7, v7
	v_mul_f32_e32 v8, v18, v7
	v_cmp_gt_f32_e64 s[6:7], s5, v8
	s_nop 1
	v_cndmask_b32_e64 v8, 0, v162, s[6:7]
	v_fmac_f32_e32 v8, v18, v7
	v_exp_f32_e32 v7, v8
	v_cndmask_b32_e64 v8, 0, v165, s[0:1]
	v_ldexp_f32 v35, v6, v8
	v_cndmask_b32_e64 v6, 0, v165, s[6:7]
	v_ldexp_f32 v83, v7, v6
	v_cndmask_b32_e32 v6, v110, v111, vcc
	v_cvt_f32_ubyte0_e32 v6, v6
	v_mul_f32_e32 v7, v18, v6
	v_cmp_gt_f32_e64 s[0:1], s5, v7
	s_nop 1
	v_cndmask_b32_e64 v7, 0, v162, s[0:1]
	v_fmac_f32_e32 v7, v18, v6
	v_exp_f32_e32 v6, v7
	v_cndmask_b32_e32 v7, v112, v113, vcc
	v_cvt_f32_ubyte0_e32 v7, v7
	v_mul_f32_e32 v8, v18, v7
	v_cmp_gt_f32_e64 s[6:7], s5, v8
	s_nop 1
	v_cndmask_b32_e64 v8, 0, v162, s[6:7]
	v_fmac_f32_e32 v8, v18, v7
	v_exp_f32_e32 v7, v8
	v_cndmask_b32_e64 v8, 0, v165, s[0:1]
	v_ldexp_f32 v166, v6, v8
	v_cndmask_b32_e64 v6, 0, v165, s[6:7]
	v_ldexp_f32 v167, v7, v6
	v_cndmask_b32_e32 v6, v114, v115, vcc
	v_cvt_f32_ubyte0_e32 v6, v6
; #define LAS __attribute__((address_space(3)))
; DI float ret_lg2(const Params& p, int l, int dir, int h) { return log1pf(-exp2f(p.in[12][(l * 2 + dir) * 5 + h])) * 1.4426950408889634f; }
; DI void phase_ret_scan(const Params& p, int l, LAS unsigned char* lds) {
;     ...
;         const float lg = ret_lg2(p, l, dir, h), gL = exp2f(lg * 128.f);
;         float wt[4][8];
; #pragma unroll
;         for (int ks = 0; ks < 4; ++ks)
; #pragma unroll
;             for (int e = 0; e < 8; ++e) { const int pp = ks * 32 + q4 * 8 + e; wt[ks][e] = exp2f(lg * (float)(dir == 0 ? 127 - pp : pp)); }
;         const bf16_t* kt = (const bf16_t*)(ws + WS_KTR) + ((size_t)b * 640 + h * 128 + dkb * 16 + r16) * RB + q4 * 8;
;         const LAS unsigned char* vl = lds + r16 * VRS + q4 * 16;
;         bf16_t* sb = (bf16_t*)(ws + WS_S) + ((size_t)((b * 5 + h) * 2 + dir) * 18) * 16384 + (dvb * 16 + r16) * 128 + dkb * 16 + q4 * 4;
;         f32x4 st = (f32x4){0.f, 0.f, 0.f, 0.f};
;         bf16x8 ca[4];
;         { const int c0 = dir == 0 ? 0 : 1;
; #pragma unroll
;           for (int ks = 0; ks < 4; ++ks) ca[ks] = *(const bf16x8*)(kt + c0 * 128 + ks * 32); }
;         __syncthreads();
	v_mul_f32_e32 v7, v18, v6
	v_cmp_gt_f32_e64 s[0:1], s5, v7
	s_nop 1
	v_cndmask_b32_e64 v7, 0, v162, s[0:1]
	v_fmac_f32_e32 v7, v18, v6
	v_exp_f32_e32 v6, v7
	v_cndmask_b32_e32 v7, v116, v117, vcc
	v_cvt_f32_ubyte0_e32 v7, v7
	v_mul_f32_e32 v8, v18, v7
	v_cmp_gt_f32_e64 s[6:7], s5, v8
	s_nop 1
	v_cndmask_b32_e64 v8, 0, v162, s[6:7]
	v_fmac_f32_e32 v8, v18, v7
	v_exp_f32_e32 v7, v8
	v_cndmask_b32_e64 v8, 0, v165, s[0:1]
	v_ldexp_f32 v168, v6, v8
	v_cndmask_b32_e64 v6, 0, v165, s[6:7]
	v_ldexp_f32 v169, v7, v6
	v_cndmask_b32_e32 v6, v118, v119, vcc
	v_cvt_f32_ubyte0_e32 v6, v6
	v_mul_f32_e32 v7, v18, v6
	v_cmp_gt_f32_e64 s[0:1], s5, v7
	s_nop 1
	v_cndmask_b32_e64 v7, 0, v162, s[0:1]
	v_fmac_f32_e32 v7, v18, v6
	v_exp_f32_e32 v6, v7
	v_cndmask_b32_e32 v7, v120, v121, vcc
	v_cvt_f32_ubyte0_e32 v7, v7
	v_mul_f32_e32 v8, v18, v7
	v_cmp_gt_f32_e64 s[6:7], s5, v8
	s_nop 1
	v_cndmask_b32_e64 v8, 0, v162, s[6:7]
	v_fmac_f32_e32 v8, v18, v7
	v_exp_f32_e32 v7, v8
	v_cndmask_b32_e64 v8, 0, v165, s[0:1]
	v_ldexp_f32 v170, v6, v8
	v_cndmask_b32_e64 v6, 0, v165, s[6:7]
	v_ldexp_f32 v171, v7, v6
	v_cndmask_b32_e32 v6, v122, v123, vcc
	v_cvt_f32_ubyte0_e32 v6, v6
	v_mul_f32_e32 v7, v18, v6
	v_cmp_gt_f32_e64 s[0:1], s5, v7
	s_nop 1
	v_cndmask_b32_e64 v7, 0, v162, s[0:1]
	v_fmac_f32_e32 v7, v18, v6
	v_exp_f32_e32 v6, v7
	v_cndmask_b32_e32 v7, v124, v125, vcc
	v_cvt_f32_ubyte0_e32 v7, v7
	v_mul_f32_e32 v8, v18, v7
	v_cmp_gt_f32_e64 s[6:7], s5, v8
	s_nop 1
	v_cndmask_b32_e64 v8, 0, v162, s[6:7]
	v_fmac_f32_e32 v8, v18, v7
	v_exp_f32_e32 v7, v8
	v_cndmask_b32_e64 v8, 0, v165, s[0:1]
	v_ldexp_f32 v172, v6, v8
	v_cndmask_b32_e64 v6, 0, v165, s[6:7]
	v_ldexp_f32 v173, v7, v6
	v_cndmask_b32_e32 v6, v126, v127, vcc
	v_cvt_f32_ubyte0_e32 v6, v6
	v_mul_f32_e32 v7, v18, v6
	v_cmp_gt_f32_e64 s[0:1], s5, v7
	s_nop 1
	v_cndmask_b32_e64 v7, 0, v162, s[0:1]
	v_fmac_f32_e32 v7, v18, v6
	v_exp_f32_e32 v6, v7
	v_cndmask_b32_e32 v7, v128, v129, vcc
	v_cvt_f32_ubyte0_e32 v7, v7
	v_mul_f32_e32 v8, v18, v7
	v_cmp_gt_f32_e64 s[6:7], s5, v8
	s_nop 1
	v_cndmask_b32_e64 v8, 0, v162, s[6:7]
	v_fmac_f32_e32 v8, v18, v7
	v_exp_f32_e32 v7, v8
	v_cndmask_b32_e64 v8, 0, v165, s[0:1]
	v_ldexp_f32 v174, v6, v8
	v_cndmask_b32_e64 v6, 0, v165, s[6:7]
	v_ldexp_f32 v175, v7, v6
	v_cndmask_b32_e32 v6, v130, v131, vcc
	v_cvt_f32_ubyte0_e32 v6, v6
	v_mul_f32_e32 v7, v18, v6
	v_cmp_gt_f32_e64 s[0:1], s5, v7
	s_nop 1
	v_cndmask_b32_e64 v7, 0, v162, s[0:1]
	v_fmac_f32_e32 v7, v18, v6
	v_exp_f32_e32 v6, v7
	v_cndmask_b32_e32 v7, v132, v133, vcc
	v_cvt_f32_ubyte0_e32 v7, v7
	v_mul_f32_e32 v8, v18, v7
	v_cmp_gt_f32_e64 s[6:7], s5, v8
	s_nop 1
	v_cndmask_b32_e64 v8, 0, v162, s[6:7]
	v_fmac_f32_e32 v8, v18, v7
	v_exp_f32_e32 v7, v8
	v_cndmask_b32_e64 v8, 0, v165, s[0:1]
	v_ldexp_f32 v176, v6, v8
	v_cndmask_b32_e64 v6, 0, v165, s[6:7]
	v_ldexp_f32 v177, v7, v6
	v_cndmask_b32_e32 v6, v134, v135, vcc
	v_cvt_f32_ubyte0_e32 v6, v6
	v_mul_f32_e32 v7, v18, v6
	v_cmp_gt_f32_e64 s[0:1], s5, v7
	s_nop 1
	v_cndmask_b32_e64 v7, 0, v162, s[0:1]
	v_fmac_f32_e32 v7, v18, v6
	v_exp_f32_e32 v6, v7
	v_cndmask_b32_e32 v7, v136, v137, vcc
	v_cvt_f32_ubyte0_e32 v7, v7
	v_mul_f32_e32 v8, v18, v7
	v_cmp_gt_f32_e64 s[6:7], s5, v8
	s_nop 1
	v_cndmask_b32_e64 v8, 0, v162, s[6:7]
	v_fmac_f32_e32 v8, v18, v7
	v_exp_f32_e32 v7, v8
	v_cndmask_b32_e64 v8, 0, v165, s[0:1]
	v_ldexp_f32 v178, v6, v8
	v_cndmask_b32_e64 v6, 0, v165, s[6:7]
	v_ldexp_f32 v179, v7, v6
	v_cndmask_b32_e32 v6, v138, v139, vcc
	v_cvt_f32_ubyte0_e32 v6, v6
	v_mul_f32_e32 v7, v18, v6
	v_cmp_gt_f32_e64 s[0:1], s5, v7
	s_nop 1
	v_cndmask_b32_e64 v7, 0, v162, s[0:1]
	v_fmac_f32_e32 v7, v18, v6
	v_exp_f32_e32 v16, v7
	global_load_dwordx4 v[12:15], v[4:5], off offset:64
	global_load_dwordx4 v[8:11], v[4:5], off offset:128
	s_nop 0
	global_load_dwordx4 v[4:7], v[4:5], off offset:192
	v_cndmask_b32_e64 v17, 0, v165, s[0:1]
	s_waitcnt lgkmcnt(0)
	v_ldexp_f32 v180, v16, v17
	v_cndmask_b32_e32 v16, v140, v141, vcc
	v_cvt_f32_ubyte0_e32 v16, v16
	v_mul_f32_e32 v17, v18, v16
	v_cmp_gt_f32_e64 s[0:1], s5, v17
	s_barrier
	s_nop 0
	v_cndmask_b32_e64 v17, 0, v162, s[0:1]
	v_fmac_f32_e32 v17, v18, v16
	v_exp_f32_e32 v16, v17
	v_cndmask_b32_e32 v17, v142, v143, vcc
	v_cvt_f32_ubyte0_e32 v17, v17
	v_mul_f32_e32 v20, v18, v17
	v_cmp_gt_f32_e64 s[6:7], s5, v20
	s_nop 1
	v_cndmask_b32_e64 v20, 0, v162, s[6:7]
	v_fmac_f32_e32 v20, v18, v17
	v_exp_f32_e32 v17, v20
	v_cndmask_b32_e64 v20, 0, v165, s[0:1]
	v_ldexp_f32 v181, v16, v20
	v_cndmask_b32_e64 v16, 0, v165, s[6:7]
	v_ldexp_f32 v182, v17, v16
	v_cndmask_b32_e32 v16, v144, v145, vcc
	v_cvt_f32_ubyte0_e32 v16, v16
	v_mul_f32_e32 v17, v18, v16
	v_cmp_gt_f32_e64 s[0:1], s5, v17
	s_nop 1
	v_cndmask_b32_e64 v17, 0, v162, s[0:1]
	v_fmac_f32_e32 v17, v18, v16
	v_exp_f32_e32 v16, v17
	v_cndmask_b32_e32 v17, v146, v147, vcc
	v_cvt_f32_ubyte0_e32 v17, v17
	v_mul_f32_e32 v20, v18, v17
	v_cmp_gt_f32_e64 s[6:7], s5, v20
	s_nop 1
	v_cndmask_b32_e64 v20, 0, v162, s[6:7]
	v_fmac_f32_e32 v20, v18, v17
	v_exp_f32_e32 v17, v20
	v_cndmask_b32_e64 v20, 0, v165, s[0:1]
	v_ldexp_f32 v183, v16, v20
	v_cndmask_b32_e64 v16, 0, v165, s[6:7]
	v_ldexp_f32 v184, v17, v16
	v_cndmask_b32_e32 v16, v148, v149, vcc
	v_cvt_f32_ubyte0_e32 v16, v16
	v_mul_f32_e32 v17, v18, v16
	v_cmp_gt_f32_e64 s[0:1], s5, v17
	s_nop 1
	v_cndmask_b32_e64 v17, 0, v162, s[0:1]
	v_fmac_f32_e32 v17, v18, v16
	v_exp_f32_e32 v16, v17
	v_cndmask_b32_e32 v17, v150, v151, vcc
	v_cvt_f32_ubyte0_e32 v17, v17
	v_mul_f32_e32 v20, v18, v17
	v_cmp_gt_f32_e64 s[6:7], s5, v20
	s_nop 1
	v_cndmask_b32_e64 v20, 0, v162, s[6:7]
	v_fmac_f32_e32 v20, v18, v17
	v_exp_f32_e32 v17, v20
	v_cndmask_b32_e64 v20, 0, v165, s[0:1]
	v_cmp_gt_f32_e64 s[0:1], s5, v19
	v_ldexp_f32 v185, v16, v20
	v_cndmask_b32_e64 v16, 0, v165, s[6:7]
	v_cndmask_b32_e64 v19, 0, v162, s[0:1]
	v_fmac_f32_e32 v19, 0x43000000, v18
	v_exp_f32_e32 v18, v19
	v_ldexp_f32 v186, v17, v16
	v_or_b32_e32 v16, s17, v86
	v_lshlrev_b32_e32 v40, 8, v16
	s_and_b64 s[0:1], s[0:1], exec
	v_lshl_add_u64 v[16:17], s[12:13], 0, v[40:41]
	s_cselect_b32 s0, 0xffffffc0, 0
	v_lshl_add_u64 v[16:17], v[36:37], 1, v[16:17]
	v_ldexp_f32 v18, v18, s0
	v_lshl_add_u64 v[16:17], v[16:17], 0, v[80:81]
	v_mov_b32_e32 v20, v18
	v_mov_b32_e32 v21, v18
	s_mov_b32 s0, 0
	s_waitcnt vmcnt(0)
; #define LAS __attribute__((address_space(3)))
; DI void st_bf16x4(bf16_t* p, f32x4 v) { u32x2 w; w.x = cvt_pk_bf16(v[0], v[1]); w.y = cvt_pk_bf16(v[2], v[3]); *(u32x2*)p = w; }
; #define MFMA16(a, b, c) __builtin_amdgcn_mfma_f32_16x16x32_bf16((a), (b), (c), 0, 0, 0)
; DI void phase_ret_scan(const Params& p, int l, LAS unsigned char* lds) {
;     ...
;         for (int step = 0; step < 18; ++step) {
;             const int c = dir == 0 ? step : (step < 2 ? 1 - step : 19 - step);
;             const int sn = step < 17 ? step + 1 : 17;
;             const int cn = dir == 0 ? sn : (sn < 2 ? 1 - sn : 19 - sn);
;             bf16x8 na_[4];
; #pragma unroll
;             for (int ks = 0; ks < 4; ++ks) na_[ks] = *(const bf16x8*)(kt + cn * 128 + ks * 32);
;             st_bf16x4(sb + (size_t)c * 16384, st);
;             f32x4 u = (f32x4){0.f, 0.f, 0.f, 0.f};
; #pragma unroll
;             for (int ks = 0; ks < 4; ++ks) u = MFMA16(scale_bf16x8(ca[ks], wt[ks]), *(const LAS bf16x8*)(vl + (c * 128 + ks * 32) * 2), u);
;             st = st * gL + u;
.LBB0_1084:
	s_cmp_eq_u32 s10, 0
	s_cselect_b32 s1, 1, 19
	s_add_i32 s1, s1, s10
	s_or_b32 s12, s0, 1
	s_add_i32 s13, s1, -1
	s_and_b64 s[6:7], vcc, exec
	s_cselect_b32 s6, s12, s13
	s_lshl_b32 s12, s6, 7
	s_waitcnt vmcnt(4)
	v_lshlrev_b32_e32 v40, 16, v0
	v_and_b32_e32 v0, 0xffff0000, v0
	v_lshlrev_b32_e32 v81, 16, v1
	v_and_b32_e32 v1, 0xffff0000, v1
	s_ashr_i32 s13, s12, 31
	v_lshlrev_b32_e32 v188, 16, v3
	s_waitcnt vmcnt(3)
	v_lshlrev_b32_e32 v189, 16, v12
	v_lshlrev_b32_e32 v190, 16, v13
	v_lshlrev_b32_e32 v191, 16, v14
	v_lshlrev_b32_e32 v192, 16, v15
	s_waitcnt vmcnt(2)
	v_lshlrev_b32_e32 v193, 16, v8
	v_lshlrev_b32_e32 v194, 16, v9
	v_lshlrev_b32_e32 v195, 16, v10
	v_lshlrev_b32_e32 v196, 16, v11
	s_waitcnt vmcnt(1)
	v_lshlrev_b32_e32 v197, 16, v4
	v_lshlrev_b32_e32 v198, 16, v5
	v_lshlrev_b32_e32 v199, 16, v6
	v_mul_f32_e32 v201, v27, v0
	v_mul_f32_e32 v203, v29, v1
	v_lshl_add_u64 v[0:1], s[12:13], 1, v[84:85]
	v_mul_f32_e32 v209, v32, v188
	v_mul_f32_e32 v211, v34, v189
	v_mul_f32_e32 v212, v83, v190
	v_mul_f32_e32 v213, v167, v191
	v_mul_f32_e32 v214, v169, v192
	v_mul_f32_e32 v215, v171, v193
	v_mul_f32_e32 v217, v173, v194
	v_mul_f32_e32 v219, v175, v195
	v_mul_f32_e32 v221, v177, v196
	v_mul_f32_e32 v223, v179, v197
	v_mul_f32_e32 v225, v181, v198
	v_mul_f32_e32 v227, v183, v199
	global_load_dwordx4 v[188:191], v[0:1], off
	global_load_dwordx4 v[192:195], v[0:1], off offset:64
	global_load_dwordx4 v[196:199], v[0:1], off offset:128
	s_and_b64 s[12:13], vcc, exec
	s_cselect_b32 s12, s0, s1
	s_ashr_i32 s13, s12, 31
	v_lshlrev_b32_e32 v187, 16, v2
	v_and_b32_e32 v2, 0xffff0000, v2
	v_and_b32_e32 v3, 0xffff0000, v3
	global_load_dwordx4 v[204:207], v[0:1], off offset:192
	v_lshl_add_u32 v231, s12, 8, v88
	s_lshl_b64 s[12:13], s[12:13], 15
	v_and_b32_e32 v4, 0xffff0000, v4
	v_and_b32_e32 v5, 0xffff0000, v5
	v_and_b32_e32 v6, 0xffff0000, v6
	v_lshlrev_b32_e32 v200, 16, v7
	v_and_b32_e32 v7, 0xffff0000, v7
	v_mul_f32_e32 v208, v31, v2
	v_mul_f32_e32 v210, v33, v3
	v_cvt_pk_bf16_f32 v0, v22, v23
	v_cvt_pk_bf16_f32 v1, v24, v25
	v_lshl_add_u64 v[2:3], v[16:17], 0, s[12:13]
	v_mul_f32_e32 v40, v26, v40
	v_mul_f32_e32 v81, v28, v81
	v_mul_f32_e32 v187, v30, v187
	v_mul_f32_e32 v224, v180, v4
	v_mul_f32_e32 v226, v182, v5
	v_mul_f32_e32 v228, v184, v6
	v_mul_f32_e32 v229, v186, v7
	global_store_dwordx2 v[2:3], v[0:1], off
	v_cvt_pk_bf16_f32 v0, v40, v201
	v_cvt_pk_bf16_f32 v1, v81, v203
	v_cvt_pk_bf16_f32 v2, v187, v208
	v_cvt_pk_bf16_f32 v3, v209, v210
	ds_read_b128 v[4:7], v231
	v_and_b32_e32 v12, 0xffff0000, v12
	v_and_b32_e32 v13, 0xffff0000, v13
	v_and_b32_e32 v14, 0xffff0000, v14
	v_and_b32_e32 v15, 0xffff0000, v15
	s_add_i32 s1, s0, 2
	v_and_b32_e32 v8, 0xffff0000, v8
	v_and_b32_e32 v9, 0xffff0000, v9
	v_and_b32_e32 v10, 0xffff0000, v10
	v_and_b32_e32 v11, 0xffff0000, v11
	v_mul_f32_e32 v12, v35, v12
	v_mul_f32_e32 v13, v166, v13
	v_mul_f32_e32 v14, v168, v14
	v_mul_f32_e32 v15, v170, v15
	s_cmp_lg_u32 s0, 16
	v_mul_f32_e32 v216, v172, v8
	v_mul_f32_e32 v218, v174, v9
	v_mul_f32_e32 v220, v176, v10
	v_mul_f32_e32 v222, v178, v11
	v_cvt_pk_bf16_f32 v8, v211, v12
	v_cvt_pk_bf16_f32 v9, v212, v13
	v_cvt_pk_bf16_f32 v10, v213, v14
	v_cvt_pk_bf16_f32 v11, v214, v15
	ds_read_b128 v[12:15], v231 offset:64
	s_cselect_b32 s0, s1, 17
	s_cmp_gt_u32 s0, 1
	s_waitcnt lgkmcnt(1)
	v_mfma_f32_16x16x32_bf16 v[0:3], v[0:3], v[4:7], 0
	s_cselect_b32 s7, 19, 1
	s_sub_i32 s7, s7, s0
	v_cvt_pk_bf16_f32 v208, v215, v216
	v_cvt_pk_bf16_f32 v209, v217, v218
	v_cvt_pk_bf16_f32 v210, v219, v220
	v_cvt_pk_bf16_f32 v211, v221, v222
	ds_read_b128 v[212:215], v231 offset:128
	s_and_b64 s[12:13], vcc, exec
	s_cselect_b32 s0, s0, s7
	s_waitcnt lgkmcnt(1)
	v_mfma_f32_16x16x32_bf16 v[4:7], v[8:11], v[12:15], v[0:3]
	s_lshl_b32 s12, s0, 7
	s_ashr_i32 s13, s12, 31
	v_cvt_pk_bf16_f32 v216, v223, v224
	v_cvt_pk_bf16_f32 v217, v225, v226
	v_lshl_add_u64 v[224:225], s[12:13], 1, v[84:85]
	v_mul_f32_e32 v200, v185, v200
	v_cvt_pk_bf16_f32 v218, v227, v228
	v_cvt_pk_bf16_f32 v219, v200, v229
	ds_read_b128 v[220:223], v231 offset:192
	global_load_dwordx4 v[0:3], v[224:225], off
	s_waitcnt lgkmcnt(1)
; #define LAS __attribute__((address_space(3)))
; DI void st_bf16x4(bf16_t* p, f32x4 v) { u32x2 w; w.x = cvt_pk_bf16(v[0], v[1]); w.y = cvt_pk_bf16(v[2], v[3]); *(u32x2*)p = w; }
; #define MFMA16(a, b, c) __builtin_amdgcn_mfma_f32_16x16x32_bf16((a), (b), (c), 0, 0, 0)
; DI void phase_ret_scan(const Params& p, int l, LAS unsigned char* lds) {
;     ...
;             bf16x8 na_[4];
; #pragma unroll
;             for (int ks = 0; ks < 4; ++ks) na_[ks] = *(const bf16x8*)(kt + cn * 128 + ks * 32);
;             st_bf16x4(sb + (size_t)c * 16384, st);
;             f32x4 u = (f32x4){0.f, 0.f, 0.f, 0.f};
; #pragma unroll
;             for (int ks = 0; ks < 4; ++ks) u = MFMA16(scale_bf16x8(ca[ks], wt[ks]), *(const LAS bf16x8*)(vl + (c * 128 + ks * 32) * 2), u);
;             st = st * gL + u;
; #pragma unroll
;             for (int ks = 0; ks < 4; ++ks) ca[ks] = na_[ks];
	v_mfma_f32_16x16x32_bf16 v[208:211], v[208:211], v[212:215], v[4:7]
	global_load_dwordx4 v[12:15], v[224:225], off offset:64
	global_load_dwordx4 v[8:11], v[224:225], off offset:128
	s_nop 0
	global_load_dwordx4 v[4:7], v[224:225], off offset:192
	s_ashr_i32 s7, s6, 31
	v_mov_b32_e32 v19, v18
	s_waitcnt lgkmcnt(0)
	v_mfma_f32_16x16x32_bf16 v[208:211], v[216:219], v[220:223], v[208:211]
	v_lshl_add_u32 v230, s6, 8, v88
	s_lshl_b64 s[6:7], s[6:7], 15
	v_lshl_add_u64 v[200:201], v[16:17], 0, s[6:7]
	s_waitcnt vmcnt(8)
	v_lshlrev_b32_e32 v40, 16, v190
	v_and_b32_e32 v81, 0xffff0000, v190
	s_nop 1
	v_pk_fma_f32 v[212:213], v[18:19], v[24:25], v[210:211]
	v_pk_fma_f32 v[214:215], v[20:21], v[22:23], v[208:209]
	v_lshlrev_b32_e32 v24, 16, v189
	v_cvt_pk_bf16_f32 v22, v214, v215
	v_cvt_pk_bf16_f32 v23, v212, v213
	global_store_dwordx2 v[200:201], v[22:23], off
	v_lshlrev_b32_e32 v22, 16, v188
	v_and_b32_e32 v23, 0xffff0000, v188
	v_and_b32_e32 v25, 0xffff0000, v189
	v_and_b32_e32 v188, 0xffff0000, v191
	v_lshlrev_b32_e32 v187, 16, v191
	s_waitcnt vmcnt(8)
	v_lshlrev_b32_e32 v189, 16, v192
	v_and_b32_e32 v190, 0xffff0000, v192
	v_lshlrev_b32_e32 v191, 16, v193
	v_mul_f32_e32 v22, v26, v22
	v_mul_f32_e32 v23, v27, v23
	v_mul_f32_e32 v24, v28, v24
	v_mul_f32_e32 v25, v29, v25
	v_mul_f32_e32 v188, v33, v188
	v_mul_f32_e32 v40, v30, v40
	v_mul_f32_e32 v81, v31, v81
	v_mul_f32_e32 v187, v32, v187
	v_mul_f32_e32 v218, v34, v189
	v_mul_f32_e32 v219, v35, v190
	v_mul_f32_e32 v220, v83, v191
	v_cvt_pk_bf16_f32 v22, v22, v23
	v_cvt_pk_bf16_f32 v23, v24, v25
	v_cvt_pk_bf16_f32 v24, v40, v81
	v_cvt_pk_bf16_f32 v25, v187, v188
	ds_read_b128 v[188:191], v230
	v_and_b32_e32 v192, 0xffff0000, v193
	v_lshlrev_b32_e32 v193, 16, v194
	v_and_b32_e32 v194, 0xffff0000, v194
	v_lshlrev_b32_e32 v200, 16, v195
	v_and_b32_e32 v195, 0xffff0000, v195
	s_waitcnt vmcnt(7)
	v_lshlrev_b32_e32 v201, 16, v196
	v_and_b32_e32 v196, 0xffff0000, v196
	v_lshlrev_b32_e32 v203, 16, v197
	v_and_b32_e32 v197, 0xffff0000, v197
	v_lshlrev_b32_e32 v208, 16, v198
	v_and_b32_e32 v198, 0xffff0000, v198
	v_lshlrev_b32_e32 v209, 16, v199
	v_and_b32_e32 v199, 0xffff0000, v199
	v_mul_f32_e32 v194, v168, v194
	v_mul_f32_e32 v195, v170, v195
	v_mul_f32_e32 v221, v166, v192
	v_mul_f32_e32 v222, v167, v193
	v_mul_f32_e32 v200, v169, v200
	v_mul_f32_e32 v223, v172, v196
	v_mul_f32_e32 v224, v174, v197
	v_mul_f32_e32 v225, v176, v198
	v_mul_f32_e32 v226, v178, v199
	v_cvt_pk_bf16_f32 v192, v218, v219
	v_cvt_pk_bf16_f32 v193, v220, v221
	v_cvt_pk_bf16_f32 v194, v222, v194
	v_cvt_pk_bf16_f32 v195, v200, v195
	ds_read_b128 v[196:199], v230 offset:64
	s_waitcnt lgkmcnt(1)
	v_mfma_f32_16x16x32_bf16 v[22:25], v[22:25], v[188:191], 0
	s_waitcnt vmcnt(6)
	v_lshlrev_b32_e32 v210, 16, v204
	v_and_b32_e32 v204, 0xffff0000, v204
	v_lshlrev_b32_e32 v211, 16, v205
	v_and_b32_e32 v205, 0xffff0000, v205
	v_lshlrev_b32_e32 v216, 16, v206
	v_and_b32_e32 v206, 0xffff0000, v206
	v_lshlrev_b32_e32 v217, 16, v207
	v_and_b32_e32 v207, 0xffff0000, v207
	v_mul_f32_e32 v201, v171, v201
	v_mul_f32_e32 v203, v173, v203
	v_mul_f32_e32 v208, v175, v208
	v_mul_f32_e32 v209, v177, v209
	v_mul_f32_e32 v227, v180, v204
	v_mul_f32_e32 v228, v182, v205
	v_mul_f32_e32 v229, v184, v206
	v_mul_f32_e32 v231, v186, v207
	v_cvt_pk_bf16_f32 v204, v201, v223
	v_cvt_pk_bf16_f32 v205, v203, v224
	v_cvt_pk_bf16_f32 v206, v208, v225
	v_cvt_pk_bf16_f32 v207, v209, v226
	ds_read_b128 v[188:191], v230 offset:128
	s_waitcnt lgkmcnt(1)
	v_mfma_f32_16x16x32_bf16 v[22:25], v[192:195], v[196:199], v[22:25]
	v_mul_f32_e32 v210, v179, v210
	v_mul_f32_e32 v211, v181, v211
	v_mul_f32_e32 v216, v183, v216
	v_mul_f32_e32 v217, v185, v217
	v_cvt_pk_bf16_f32 v208, v210, v227
	v_cvt_pk_bf16_f32 v209, v211, v228
	v_cvt_pk_bf16_f32 v210, v216, v229
	v_cvt_pk_bf16_f32 v211, v217, v231
	s_waitcnt lgkmcnt(0)
	v_mfma_f32_16x16x32_bf16 v[22:25], v[204:207], v[188:191], v[22:25]
	ds_read_b128 v[188:191], v230 offset:192
	s_add_i32 s10, s10, -2
	s_mov_b32 s0, s1
	s_waitcnt lgkmcnt(0)
	v_mfma_f32_16x16x32_bf16 v[22:25], v[208:211], v[188:191], v[22:25]
	s_cmp_eq_u32 s1, 18
	s_nop 6
	v_pk_fma_f32 v[24:25], v[18:19], v[212:213], v[24:25]
	v_pk_fma_f32 v[22:23], v[20:21], v[214:215], v[22:23]
	s_cbranch_scc0 .LBB0_1084
	s_mov_b64 s[0:1], 0
	s_branch .LBB0_1077

; #define LAS __attribute__((address_space(3)))
; DI int otid() { int t = threadIdx.x; asm volatile("" : "+v"(t)); return t; }
; DI void prep_items(const Params& p, LAS unsigned char* lds, int l, unsigned* ctr, int max_items) {
;     const int tid = otid(), lane = tid & 63, wid = tid >> 6;
;     LAS float* s_c = (LAS float*)lds;
;     LAS float* s_red = (LAS float*)(lds + 40960);
;     volatile LAS int* slot = (volatile LAS int*)(lds + LDS_CTRL + 64);
;     constexpr int N_ADA = 48, PER_L = 12832, N_CONV = PER_L / 8;
;     const int n_tab = (l == 0) ? 48 : 0;
;     float* mod = (float*)(p.ws + WS_MOD);
;     bool have_c = false;
;     for (int done = 0; done < max_items; ++done) {
; DI void deferred_prep(const Params& p, LAS unsigned char* lds, int max_items) { prep_items(p, lds, 1, (unsigned*)(p.ws + WS_QCTR + 256 * 5), max_items); }
.LBB0_1788:
	s_cmpk_lg_u32 s33, 0x100
	s_cbranch_scc1 .Ldef_go_3
	s_cmpk_lt_u32 s26, 128
	s_cbranch_scc1 .Ldef_skip_3
.Ldef_go_3:
	v_writelane_b32 v254, s0, 0
	v_writelane_b32 v254, s1, 1
	v_writelane_b32 v254, s2, 2
	v_writelane_b32 v254, s3, 3
	v_writelane_b32 v254, s4, 4
	v_writelane_b32 v254, s5, 5
	v_writelane_b32 v254, s6, 6
	v_writelane_b32 v254, s7, 7
	v_writelane_b32 v254, s8, 8
	v_writelane_b32 v254, s9, 9
	v_writelane_b32 v254, s10, 10
	v_writelane_b32 v254, s11, 11
	v_writelane_b32 v254, s12, 12
	v_writelane_b32 v254, s13, 13
	v_writelane_b32 v254, s14, 14
	v_writelane_b32 v254, s15, 15
	v_writelane_b32 v254, s16, 16
	v_writelane_b32 v254, s17, 17
	v_writelane_b32 v254, s18, 18
	v_writelane_b32 v254, s19, 19
	v_writelane_b32 v254, s20, 20
	v_writelane_b32 v254, s21, 21
	v_writelane_b32 v254, s22, 22
	v_writelane_b32 v254, s23, 23
	v_writelane_b32 v254, s24, 24
	v_writelane_b32 v254, s25, 25
	v_writelane_b32 v254, s26, 26
	v_writelane_b32 v254, s27, 27
	v_writelane_b32 v254, s28, 28
	v_writelane_b32 v254, s29, 29
	v_writelane_b32 v254, s30, 30
	v_writelane_b32 v254, s31, 31
	v_writelane_b32 v254, s32, 32
	v_writelane_b32 v254, s33, 33
	v_writelane_b32 v254, s34, 34
	v_writelane_b32 v254, s35, 35
	v_writelane_b32 v254, s36, 36
	v_writelane_b32 v254, s37, 37
	v_writelane_b32 v254, s38, 38
	v_writelane_b32 v254, s39, 39
	v_writelane_b32 v254, s40, 40
	v_writelane_b32 v254, s41, 41
	v_writelane_b32 v254, s42, 42
	v_writelane_b32 v254, s43, 43
	v_writelane_b32 v254, s44, 44
	v_writelane_b32 v254, s45, 45
	v_writelane_b32 v254, s46, 46
	v_writelane_b32 v254, s47, 47
	v_writelane_b32 v254, s48, 48
	v_writelane_b32 v254, s49, 49
	v_writelane_b32 v254, s50, 50
	v_writelane_b32 v254, s51, 51
	v_writelane_b32 v254, s52, 52
	v_writelane_b32 v254, s53, 53
	v_writelane_b32 v254, s54, 54
	v_writelane_b32 v254, s55, 55
	v_writelane_b32 v254, s56, 56
	v_writelane_b32 v254, s57, 57
	v_writelane_b32 v254, s58, 58
	v_writelane_b32 v254, s59, 59
	v_writelane_b32 v254, s60, 60
	v_writelane_b32 v254, s61, 61
	v_writelane_b32 v254, s62, 62
	v_writelane_b32 v254, s63, 63
	v_writelane_b32 v255, s64, 0
	v_writelane_b32 v255, s65, 1
	v_writelane_b32 v255, s66, 2
	v_writelane_b32 v255, s67, 3
	v_writelane_b32 v255, s68, 4
	v_writelane_b32 v255, s69, 5
	v_writelane_b32 v255, s70, 6
	v_writelane_b32 v255, s71, 7
	v_writelane_b32 v255, s72, 8
	v_writelane_b32 v255, s73, 9
	v_writelane_b32 v255, s74, 10
	v_writelane_b32 v255, s75, 11
	v_writelane_b32 v255, s76, 12
	v_writelane_b32 v255, s77, 13
	v_writelane_b32 v255, s78, 14
	v_writelane_b32 v255, s79, 15
	v_writelane_b32 v255, s80, 16
	v_writelane_b32 v255, s81, 17
	v_writelane_b32 v255, s82, 18
	v_writelane_b32 v255, s83, 19
	v_writelane_b32 v255, s84, 20
	v_writelane_b32 v255, s85, 21
	v_writelane_b32 v255, s86, 22
	v_writelane_b32 v255, s87, 23
	v_writelane_b32 v255, s88, 24
	v_writelane_b32 v255, s89, 25
	v_writelane_b32 v255, s90, 26
	v_writelane_b32 v255, s91, 27
	v_writelane_b32 v255, s92, 28
	v_writelane_b32 v255, s93, 29
	v_writelane_b32 v255, s94, 30
	v_writelane_b32 v255, s95, 31
	v_writelane_b32 v255, s96, 32
	v_writelane_b32 v255, s97, 33
	v_readlane_b32 s2, v253, 9
	s_nop 0
	v_writelane_b32 v255, s2, 40
	v_readlane_b32 s2, v253, 10
	s_nop 0
	v_writelane_b32 v255, s2, 41
	v_readlane_b32 s2, v253, 13
	s_nop 0
	v_writelane_b32 v255, s2, 42
	v_readlane_b32 s2, v253, 14
	s_nop 0
	v_writelane_b32 v255, s2, 43
	v_readlane_b32 s2, v253, 15
	s_nop 0
	v_writelane_b32 v255, s2, 44
	v_readlane_b32 s2, v253, 16
	s_nop 0
	v_writelane_b32 v255, s2, 45
	v_readlane_b32 s2, v253, 17
	s_nop 0
	v_writelane_b32 v255, s2, 46
	v_readlane_b32 s2, v253, 18
	s_nop 0
	v_writelane_b32 v255, s2, 47
	v_readlane_b32 s2, v255, 62
	v_readlane_b32 s3, v255, 63
	s_nop 4
	s_load_dwordx16 s[36:51], s[2:3], 0x80
	s_load_dwordx16 s[68:83], s[2:3], 0x0
	s_load_dwordx16 s[52:67], s[2:3], 0x40
	s_mov_b32 s4, -1
	s_nop 0
	v_writelane_b32 v253, s4, 9
	v_writelane_b32 v253, s4, 10
	v_writelane_b32 v253, s4, 13
	v_writelane_b32 v253, s4, 14
	s_waitcnt lgkmcnt(0)
	s_add_u32 s14, s50, 0x8000
	s_addc_u32 s15, s51, 0
	s_add_u32 s0, s50, 0x4600
	s_addc_u32 s1, s51, 0
	v_mov_b32_e32 v68, v202
	s_movk_i32 s6, 0x3000
	s_movk_i32 s94, 0x1400
	v_or_b32_sdwa v90, v68, s6 dst_sel:DWORD dst_unused:UNUSED_PAD src0_sel:BYTE_0 src1_sel:DWORD
	s_add_u32 s6, s42, 0x2c00000
	s_addc_u32 s7, s43, 0
	s_add_u32 s22, s50, 0xb5a0000
	s_addc_u32 s23, s51, 0
	s_add_u32 s28, s36, 0x5800000
	v_writelane_b32 v253, s6, 17
	s_addc_u32 s29, s37, 0
	v_and_b32_e32 v0, 63, v68
	v_writelane_b32 v253, s7, 18
	s_add_u32 s6, s50, 0x73a0000
	s_addc_u32 s7, s51, 0
	s_add_u32 s34, s62, 0x1000000
	s_addc_u32 s35, s63, 0
	s_add_u32 s36, s50, 0x3fa0000
	s_addc_u32 s37, s51, 0
	v_lshlrev_b32_e32 v83, 2, v0
	v_lshlrev_b32_e32 v2, 1, v68
	s_add_u32 s42, s56, 0x280000
	v_and_b32_e32 v1, 28, v83
	v_and_b32_e32 v2, 16, v2
	s_addc_u32 s43, s57, 0
	v_ashrrev_i32_e32 v82, 6, v68
	v_or_b32_e32 v3, v2, v1
	v_add3_u32 v2, v1, v2, 16
	v_cmp_gt_u32_e32 vcc, 16, v1
	s_add_u32 s56, s50, 0x3660000
	v_mul_lo_u32 v1, v82, s94
	v_cndmask_b32_e32 v87, v2, v3, vcc
	v_lshlrev_b32_e32 v2, 4, v0
	v_mov_b32_e32 v0, 2
	s_addc_u32 s57, s51, 0
	v_add3_u32 v88, 0, v1, v2
	v_lshlrev_b32_sdwa v0, v0, v68 dst_sel:DWORD dst_unused:UNUSED_PAD src0_sel:DWORD src1_sel:BYTE_0
	v_mov_b32_e32 v1, 0
	s_add_u32 s54, s54, 0x1e0000
	v_add_u32_e32 v89, 0, v0
	v_lshl_add_u64 v[70:71], s[14:15], 0, v[0:1]
	s_addc_u32 s55, s55, 0
	v_max_i32_e32 v0, 0x7f8, v82
	s_add_u32 s62, s50, 0x3420000
	v_sub_u32_e32 v0, v0, v82
	s_addc_u32 s63, s51, 0
	v_add_u32_e32 v0, 7, v0
	v_writelane_b32 v253, s6, 15
	s_add_u32 s80, s80, 0x2e80000
	v_lshrrev_b32_e32 v3, 3, v0
	s_mov_b32 s27, 0xc000
	v_writelane_b32 v253, s7, 16
	s_addc_u32 s81, s81, 0
	v_add_u32_e32 v3, 1, v3
	v_mad_i64_i32 v[4:5], s[6:7], v82, s27, 0
	s_add_u32 s84, s50, 0x1b20000
	v_and_b32_e32 v6, 7, v3
	v_mov_b32_e32 v3, v1
	v_or_b32_e32 v4, v4, v2
	s_movk_i32 s2, 0x2800
	s_movk_i32 s4, 0x800
	s_movk_i32 s97, 0x500
	s_addc_u32 s85, s51, 0
	v_and_b32_e32 v7, 56, v0
	v_ashrrev_i32_e32 v69, 31, v68
	v_lshl_add_u64 v[4:5], s[76:77], 0, v[4:5]
	s_mov_b64 s[6:7], 0x6000000
	v_lshl_add_u64 v[2:3], s[76:77], 0, v[2:3]
	s_add_i32 s20, 0, 0x22040
	v_and_b32_e32 v84, 0x7c, v83
	v_or_b32_e32 v85, 0xffff9c00, v83
	v_or_b32_e32 v86, 0xffffa000, v83
	v_cmp_gt_i32_e64 s[2:3], s2, v68
	v_cmp_gt_i32_e64 s[4:5], s4, v82
	s_mov_b32 s96, 0x40000000
	v_add_u32_e32 v91, 0xfffffe80, v82
	v_lshl_add_u32 v92, v68, 2, 0
	v_lshl_add_u64 v[72:73], v[68:69], 2, s[70:71]
	v_lshl_add_u32 v69, v82, 2, 0
	v_lshl_add_u64 v[74:75], v[4:5], 0, s[6:7]
	v_sub_u32_e32 v93, 0, v6
	v_lshl_add_u64 v[76:77], v[2:3], 0, s[6:7]
	v_mov_b32_e32 v94, s20
	v_mov_b32_e32 v95, 0xffffea00
	v_mov_b32_e32 v96, 0x80
	s_movk_i32 s21, 0x2000
	v_cmp_gt_i32_e64 s[6:7], s97, v68
	v_cmp_ne_u32_e64 s[8:9], 56, v7
	v_cmp_lt_u32_e64 s[10:11], 55, v0
	s_mov_b64 s[76:77], 0
	s_mov_b64 s[70:71], 0x300000
	s_branch .Ldq3_239

; #define G_STAGE(bufoff, gbase, voff) do { _Pragma("unroll") for (int _i = 0; _i < 2; ++_i) \
;         __builtin_amdgcn_global_load_lds((const unsigned*)((const char*)(gbase) + (voff)[_i]), (LAS unsigned*)(lds + (bufoff) + ldsw + _i * 8192), 16, 0, 0); } while (0)
; #define G_WAIT_V(n) asm volatile("s_waitcnt vmcnt(" #n ")" ::: "memory")
; #define G_BAR __builtin_amdgcn_s_barrier()
; template <class Epi, bool PERMROWS = false>
; DI void gemm_phase(LAS unsigned char* lds, const bf16_t* A, int lda, const bf16_t* Bt, int K, const Sched& S, const Epi& E) {
;     ...
;     G_STAGE(G_SB(0, 0), cB, voffB); G_STAGE(G_SA(0, 0), cA, voffA); G_STAGE(G_SB(0, 1), cB + hstepB, voffB); G_STAGE(G_SA(0, 1), cA + hstepA, voffA);
;     if (wr == 1) G_BAR;
;     G_WAIT_V(4); G_BAR;
;     G_STAGE(G_SB(1, 0), cB + kstep, voffB); G_STAGE(G_SA(1, 0), cA + kstep, voffA); G_STAGE(G_SB(1, 1), cB + hstepB + kstep, voffB);
;     G_WAIT_V(6); G_BAR;
;     for (;;) {
;         const bool has_next = S.next(ui + 1, nxt);
;         const char* nA = has_next ? (const char*)A + (size_t)nxt.pm * tstepA + (nxt.kq >= 0 ? nxt.kq * qstep : 0) : cA; const char* nB = has_next ? (const char*)Bt + (size_t)nxt.pn * tstepB + (nxt.kq >= 0 ? nxt.kq * qstep : 0) : cB;
.LBB0_2426:
	s_lshl_b32 s4, s4, 5
	s_mov_b64 s[14:15], 0x80
	s_and_b32 s37, s4, 0x60
	s_add_i32 m0, s31, 0x18000
	v_lshl_add_u64 v[6:7], v[6:7], 0, s[14:15]
	s_lshl_b32 s1, s3, 13
	s_lshl_b32 s16, s37, 7
	s_waitcnt vmcnt(4)
	s_barrier
	global_load_lds_dwordx4 v[6:7], off
	v_lshl_add_u64 v[4:5], v[4:5], 0, s[14:15]
	s_add_i32 m0, s31, 0x1a000
	s_add_i32 s54, s31, 0x8000
	s_add_i32 s70, s31, 0xa000
	global_load_lds_dwordx4 v[4:5], off
	v_lshl_add_u64 v[2:3], v[2:3], 0, s[14:15]
	s_mov_b32 m0, s54
	s_add_u32 s4, s10, 0x20080
	global_load_lds_dwordx4 v[2:3], off
	v_lshl_add_u64 v[0:1], v[0:1], 0, s[14:15]
	s_mov_b32 m0, s70
	s_addc_u32 s5, s11, 0
	global_load_lds_dwordx4 v[0:1], off
	s_add_i32 m0, s31, 0x1c000
	v_lshl_add_u64 v[0:1], s[4:5], 0, v[130:131]
	global_load_lds_dwordx4 v[0:1], off
	v_lshl_add_u64 v[0:1], s[4:5], 0, v[134:135]
	s_add_i32 m0, s31, 0x1e000
	v_bfe_u32 v2, v8, 4, 2
	global_load_lds_dwordx4 v[0:1], off
	v_and_b32_e32 v1, 15, v8
	v_lshlrev_b32_e32 v0, 4, v2
	v_lshlrev_b32_e32 v3, 2, v8
	v_lshl_or_b32 v139, s3, 6, v1
	v_lshl_or_b32 v1, v1, 6, v0
	v_and_b32_e32 v3, 32, v3
	v_lshlrev_b32_e32 v136, 3, v2
	v_bitop3_b32 v4, v1, s1, v3 bitop3:0xde
	v_bitop3_b32 v160, v1, s16, v3 bitop3:0xde
	v_lshlrev_b32_e32 v138, 2, v2
	v_lshl_add_u64 v[2:3], s[52:53], 0, v[136:137]
	s_mov_b64 s[4:5], 0x1a3a0000
	v_mov_b32_e32 v1, v137
	v_lshl_add_u64 v[140:141], v[2:3], 0, s[4:5]
	v_lshl_add_u64 v[0:1], s[52:53], 0, v[0:1]
	s_mov_b64 s[4:5], 0x200000
	s_mov_b32 s1, 0x18000
	v_lshl_add_u64 v[142:143], v[0:1], 0, s[4:5]
	v_lshrrev_b32_e32 v1, 1, v13
	v_mul_lo_u32 v0, v14, s2
	v_mad_u64_u32 v[0:1], s[4:5], v1, s1, v[0:1]
	v_or_b32_e32 v0, v0, v15
	v_add_lshl_u32 v136, v0, v16, 1
	v_lshrrev_b32_e32 v1, 1, v9
	v_mul_lo_u32 v0, v10, s2
	v_mad_u64_u32 v[0:1], s[2:3], v1, s1, v[0:1]
	s_waitcnt vmcnt(6)
	s_add_u32 s16, s52, 0x80000
	s_mov_b64 s[4:5], 0x180080
	v_or_b32_e32 v0, v0, v11
	s_addc_u32 s17, s53, 0
	v_lshl_add_u64 v[144:145], v[136:137], 0, s[4:5]
	v_add_lshl_u32 v136, v0, v12, 1
	s_add_i32 s71, 0, 0x10000
	s_add_i32 s72, 0, 0x14000
	v_lshl_add_u64 v[146:147], v[136:137], 0, s[4:5]
	v_mov_b64_e32 v[148:149], 0x90
	v_mov_b64_e32 v[150:151], 0x8f
	v_add_u32_e32 v161, s71, v160
	v_add_u32_e32 v162, 0, v4
	v_add_u32_e32 v163, s72, v160
	v_mbcnt_hi_u32_b32 v164, -1, v203
	s_movk_i32 s73, 0xff
	v_mov_b32_e32 v165, 0x358637bd
	s_mov_b32 s74, 0x800000
	s_movk_i32 s75, 0x780
	s_mov_b32 s76, 0
	s_barrier
	s_branch .LBB0_2429
.LBB0_2428:
	s_and_b64 vcc, exec, s[2:3]
	s_mov_b32 s0, s18
	s_mov_b32 s12, s77
	s_mov_b64 s[10:11], s[56:57]
	s_mov_b64 s[8:9], s[20:21]
	s_cbranch_vccnz .LBB0_2498

; #define G_STAGE(bufoff, gbase, voff) do { _Pragma("unroll") for (int _i = 0; _i < 2; ++_i) \
;         __builtin_amdgcn_global_load_lds((const unsigned*)((const char*)(gbase) + (voff)[_i]), (LAS unsigned*)(lds + (bufoff) + ldsw + _i * 8192), 16, 0, 0); } while (0)
; #define G_LDA(dst, b, h) do { _Pragma("unroll") for (int m = 0; m < 4; ++m) _Pragma("unroll") for (int k = 0; k < 2; ++k) dst[m][k] = *(const LAS bf16x8*)(lds + G_SA(b, h) + aoff + m * 2048 + k * 1024); } while (0)
; #define G_LDB(dst, b, h) do { _Pragma("unroll") for (int n = 0; n < 2; ++n) _Pragma("unroll") for (int k = 0; k < 2; ++k) dst[n][k] = *(const LAS bf16x8*)(lds + G_SB(b, h) + boff + n * 2048 + k * 1024); } while (0)
; #define G_MMA(ai, bj, At, Bt_) do { __builtin_amdgcn_s_setprio(1); _Pragma("unroll") for (int m = 0; m < 4; ++m) _Pragma("unroll") for (int n = 0; n < 2; ++n) _Pragma("unroll") for (int k = 0; k < 2; ++k) \
;         acc[ai][bj][m][n] = __builtin_amdgcn_mfma_f32_16x16x32_bf16(Bt_[n][k], At[m][k], acc[ai][bj][m][n], 0, 0, 0); __builtin_amdgcn_s_setprio(0); } while (0)
; #define G_WAIT_V(n) asm volatile("s_waitcnt vmcnt(" #n ")" ::: "memory")
; #define G_WAIT_L(n) asm volatile("s_waitcnt lgkmcnt(" #n ")" ::: "memory")
; #define G_BAR __builtin_amdgcn_s_barrier()
; #define G_SCHED __builtin_amdgcn_sched_barrier(0)
; template <class Epi, bool PERMROWS = false>
; DI void gemm_phase(LAS unsigned char* lds, const bf16_t* A, int lda, const bf16_t* Bt, int K, const Sched& S, const Epi& E) {
;     ...
;             G_LDB(B0, 0, 0); G_SCHED; G_LDA(At, 0, 0); G_STAGE(G_SA(1, 1), a1 + hstepA, voffA);
;             G_WAIT_L(8); G_BAR; G_WAIT_L(0); G_MMA(0, 0, At, B0); G_BAR; G_SCHED;
;             G_LDB(B1, 0, 1); G_STAGE(G_SB(0, 0), b2, voffB);
;             G_BAR; G_WAIT_L(0); G_MMA(0, 1, At, B1); G_BAR;
;             G_LDA(At, 0, 1); G_STAGE(G_SA(0, 0), a2, voffA);
;             G_BAR; G_WAIT_L(0); G_MMA(1, 0, At, B0); G_BAR; G_SCHED;
;             G_STAGE(G_SB(0, 1), b2 + hstepB, voffB);
;             G_WAIT_V(6); G_BAR; G_MMA(1, 1, At, B1); G_BAR;
.LBB0_2434:
	ds_read_b128 v[152:155], v161
	ds_read_b128 v[156:159], v161 offset:1024
	ds_read_b128 v[166:169], v161 offset:2048
	ds_read_b128 v[170:173], v161 offset:3072
	s_add_u32 s4, s8, 0x100
	s_addc_u32 s5, s9, 0
	s_cmp_eq_u32 s29, 4
	s_cselect_b32 s63, s21, s5
	s_cselect_b32 s62, s20, s4
	s_cselect_b32 s11, s1, s28
	s_cselect_b32 s10, s19, s42
	v_lshl_add_u64 v[208:209], s[8:9], 0, v[146:147]
	s_add_i32 m0, s31, 0xc000
	ds_read_b128 v[174:177], v162
	ds_read_b128 v[178:181], v162 offset:1024
	ds_read_b128 v[182:185], v162 offset:2048
	ds_read_b128 v[186:189], v162 offset:3072
	ds_read_b128 v[190:193], v162 offset:4096
	ds_read_b128 v[194:197], v162 offset:5120
	ds_read_b128 v[198:201], v162 offset:6144
	ds_read_b128 v[204:207], v162 offset:7168
	global_load_lds_dwordx4 v[208:209], off
	v_lshl_add_u64 v[208:209], s[8:9], 0, v[144:145]
	s_add_i32 m0, s31, 0xe000
	s_nop 0
	global_load_lds_dwordx4 v[208:209], off
	s_waitcnt lgkmcnt(8)
	s_barrier
	s_waitcnt lgkmcnt(0)
	s_setprio 1
	s_waitcnt lgkmcnt(0)
	v_mfma_f32_16x16x32_bf16 v[124:127], v[152:155], v[174:177], v[124:127]
	v_mfma_f32_16x16x32_bf16 v[120:123], v[166:169], v[174:177], v[120:123]
	v_mfma_f32_16x16x32_bf16 v[108:111], v[152:155], v[182:185], v[108:111]
	v_mfma_f32_16x16x32_bf16 v[104:107], v[166:169], v[182:185], v[104:107]
	v_mfma_f32_16x16x32_bf16 v[92:95], v[152:155], v[190:193], v[92:95]
	v_mfma_f32_16x16x32_bf16 v[88:91], v[166:169], v[190:193], v[88:91]
	v_mfma_f32_16x16x32_bf16 v[76:79], v[152:155], v[198:201], v[76:79]
	v_mfma_f32_16x16x32_bf16 v[72:75], v[166:169], v[198:201], v[72:75]
	v_mfma_f32_16x16x32_bf16 v[124:127], v[156:159], v[178:181], v[124:127]
	v_mfma_f32_16x16x32_bf16 v[120:123], v[170:173], v[178:181], v[120:123]
	v_mfma_f32_16x16x32_bf16 v[108:111], v[156:159], v[186:189], v[108:111]
	v_mfma_f32_16x16x32_bf16 v[104:107], v[170:173], v[186:189], v[104:107]
	v_mfma_f32_16x16x32_bf16 v[92:95], v[156:159], v[194:197], v[92:95]
	v_mfma_f32_16x16x32_bf16 v[88:91], v[170:173], v[194:197], v[88:91]
	v_mfma_f32_16x16x32_bf16 v[76:79], v[156:159], v[204:207], v[76:79]
	v_mfma_f32_16x16x32_bf16 v[72:75], v[170:173], v[204:207], v[72:75]
	s_setprio 0
	s_barrier
	s_add_i32 s8, s71, s30
	v_lshl_add_u64 v[224:225], s[10:11], 0, v[130:131]
	s_mov_b32 m0, s8
	ds_read_b128 v[208:211], v163
	ds_read_b128 v[212:215], v163 offset:1024
	ds_read_b128 v[216:219], v163 offset:2048
	ds_read_b128 v[220:223], v163 offset:3072
	global_load_lds_dwordx4 v[224:225], off
	v_lshl_add_u64 v[226:227], s[10:11], 0, v[134:135]
	s_add_i32 m0, s8, 0x2000
	s_nop 0
	global_load_lds_dwordx4 v[226:227], off
	s_barrier
	s_waitcnt lgkmcnt(0)
	s_setprio 1
	s_waitcnt lgkmcnt(0)
	v_mfma_f32_16x16x32_bf16 v[116:119], v[208:211], v[174:177], v[116:119]
	v_mfma_f32_16x16x32_bf16 v[112:115], v[216:219], v[174:177], v[112:115]
	v_mfma_f32_16x16x32_bf16 v[100:103], v[208:211], v[182:185], v[100:103]
	v_mfma_f32_16x16x32_bf16 v[96:99], v[216:219], v[182:185], v[96:99]
	v_mfma_f32_16x16x32_bf16 v[84:87], v[208:211], v[190:193], v[84:87]
	v_mfma_f32_16x16x32_bf16 v[80:83], v[216:219], v[190:193], v[80:83]
	v_mfma_f32_16x16x32_bf16 v[68:71], v[208:211], v[198:201], v[68:71]
	v_mfma_f32_16x16x32_bf16 v[64:67], v[216:219], v[198:201], v[64:67]
	v_mfma_f32_16x16x32_bf16 v[116:119], v[212:215], v[178:181], v[116:119]
	v_mfma_f32_16x16x32_bf16 v[112:115], v[220:223], v[178:181], v[112:115]
	v_mfma_f32_16x16x32_bf16 v[100:103], v[212:215], v[186:189], v[100:103]
	v_mfma_f32_16x16x32_bf16 v[96:99], v[220:223], v[186:189], v[96:99]
	v_mfma_f32_16x16x32_bf16 v[84:87], v[212:215], v[194:197], v[84:87]
	v_mfma_f32_16x16x32_bf16 v[80:83], v[220:223], v[194:197], v[80:83]
	v_mfma_f32_16x16x32_bf16 v[68:71], v[212:215], v[204:207], v[68:71]
	v_mfma_f32_16x16x32_bf16 v[64:67], v[220:223], v[204:207], v[64:67]
	s_setprio 0
	s_mov_b32 m0, s31
	v_lshl_add_u64 v[228:229], s[62:63], 0, v[128:129]
	s_barrier
	ds_read_b128 v[174:177], v162 offset:16384
	ds_read_b128 v[178:181], v162 offset:17408
	ds_read_b128 v[182:185], v162 offset:18432
	ds_read_b128 v[186:189], v162 offset:19456
	ds_read_b128 v[190:193], v162 offset:20480
	ds_read_b128 v[194:197], v162 offset:21504
	ds_read_b128 v[198:201], v162 offset:22528
	ds_read_b128 v[204:207], v162 offset:23552
	global_load_lds_dwordx4 v[228:229], off
	v_lshl_add_u64 v[230:231], s[62:63], 0, v[132:133]
	s_mov_b32 m0, s34
	s_nop 0
	global_load_lds_dwordx4 v[230:231], off
	s_barrier
	s_waitcnt lgkmcnt(0)
	s_setprio 1
	s_waitcnt lgkmcnt(0)
	v_mfma_f32_16x16x32_bf16 v[60:63], v[152:155], v[174:177], v[60:63]
	v_mfma_f32_16x16x32_bf16 v[56:59], v[166:169], v[174:177], v[56:59]
	v_mfma_f32_16x16x32_bf16 v[44:47], v[152:155], v[182:185], v[44:47]
	v_mfma_f32_16x16x32_bf16 v[40:43], v[166:169], v[182:185], v[40:43]
	v_mfma_f32_16x16x32_bf16 v[28:31], v[152:155], v[190:193], v[28:31]
	v_mfma_f32_16x16x32_bf16 v[24:27], v[166:169], v[190:193], v[24:27]
	v_mfma_f32_16x16x32_bf16 v[12:15], v[152:155], v[198:201], v[12:15]
	v_mfma_f32_16x16x32_bf16 v[8:11], v[166:169], v[198:201], v[8:11]
	v_mfma_f32_16x16x32_bf16 v[60:63], v[156:159], v[178:181], v[60:63]
	v_mfma_f32_16x16x32_bf16 v[56:59], v[170:173], v[178:181], v[56:59]
	v_mfma_f32_16x16x32_bf16 v[44:47], v[156:159], v[186:189], v[44:47]
	v_mfma_f32_16x16x32_bf16 v[40:43], v[170:173], v[186:189], v[40:43]
	v_mfma_f32_16x16x32_bf16 v[28:31], v[156:159], v[194:197], v[28:31]
	v_mfma_f32_16x16x32_bf16 v[24:27], v[170:173], v[194:197], v[24:27]
	v_mfma_f32_16x16x32_bf16 v[12:15], v[156:159], v[204:207], v[12:15]
	v_mfma_f32_16x16x32_bf16 v[8:11], v[170:173], v[204:207], v[8:11]
	s_setprio 0
	s_barrier
; #define G_STAGE(bufoff, gbase, voff) do { _Pragma("unroll") for (int _i = 0; _i < 2; ++_i) \
;         __builtin_amdgcn_global_load_lds((const unsigned*)((const char*)(gbase) + (voff)[_i]), (LAS unsigned*)(lds + (bufoff) + ldsw + _i * 8192), 16, 0, 0); } while (0)
; #define G_LDA(dst, b, h) do { _Pragma("unroll") for (int m = 0; m < 4; ++m) _Pragma("unroll") for (int k = 0; k < 2; ++k) dst[m][k] = *(const LAS bf16x8*)(lds + G_SA(b, h) + aoff + m * 2048 + k * 1024); } while (0)
; #define G_LDB(dst, b, h) do { _Pragma("unroll") for (int n = 0; n < 2; ++n) _Pragma("unroll") for (int k = 0; k < 2; ++k) dst[n][k] = *(const LAS bf16x8*)(lds + G_SB(b, h) + boff + n * 2048 + k * 1024); } while (0)
; #define G_MMA(ai, bj, At, Bt_) do { __builtin_amdgcn_s_setprio(1); _Pragma("unroll") for (int m = 0; m < 4; ++m) _Pragma("unroll") for (int n = 0; n < 2; ++n) _Pragma("unroll") for (int k = 0; k < 2; ++k) \
;         acc[ai][bj][m][n] = __builtin_amdgcn_mfma_f32_16x16x32_bf16(Bt_[n][k], At[m][k], acc[ai][bj][m][n], 0, 0, 0); __builtin_amdgcn_s_setprio(0); } while (0)
; #define G_WAIT_V(n) asm volatile("s_waitcnt vmcnt(" #n ")" ::: "memory")
; #define G_WAIT_L(n) asm volatile("s_waitcnt lgkmcnt(" #n ")" ::: "memory")
; #define G_BAR __builtin_amdgcn_s_barrier()
; #define G_SCHED __builtin_amdgcn_sched_barrier(0)
; template <class Epi, bool PERMROWS = false>
; DI void gemm_phase(LAS unsigned char* lds, const bf16_t* A, int lda, const bf16_t* Bt, int K, const Sched& S, const Epi& E) {
;     ...
;             G_STAGE(G_SB(0, 1), b2 + hstepB, voffB);
;             G_WAIT_V(6); G_BAR; G_MMA(1, 1, At, B1); G_BAR;
;             G_LDB(B0, 1, 0); G_SCHED; G_LDA(At, 1, 0); G_STAGE(G_SA(0, 1), a2 + hstepA, voffA);
;             G_WAIT_L(8); G_BAR; G_WAIT_L(0); G_MMA(0, 0, At, B0); G_BAR; G_SCHED;
;             G_LDB(B1, 1, 1); G_STAGE(G_SB(1, 0), b3, voffB);
;             G_BAR; G_WAIT_L(0); G_MMA(0, 1, At, B1); G_BAR;
;             G_LDA(At, 1, 1); G_STAGE(G_SA(1, 0), a3, voffA);
;             G_BAR; G_WAIT_L(0); G_MMA(1, 0, At, B0); G_BAR; G_SCHED;
;             G_STAGE(G_SB(1, 1), b3 + hstepB, voffB);
;             G_WAIT_V(6); G_BAR; G_MMA(1, 1, At, B1); G_BAR;
	s_add_u32 s8, s10, 0x20000
	s_addc_u32 s9, s11, 0
	s_add_i32 s43, s72, s30
	v_lshl_add_u64 v[152:153], s[8:9], 0, v[130:131]
	s_mov_b32 m0, s43
	s_nop 0
	global_load_lds_dwordx4 v[152:153], off
	v_lshl_add_u64 v[152:153], s[8:9], 0, v[134:135]
	s_add_i32 m0, s43, 0x2000
	s_nop 0
	global_load_lds_dwordx4 v[152:153], off
	s_waitcnt vmcnt(6)
	s_barrier
	s_setprio 1
	v_mfma_f32_16x16x32_bf16 v[52:55], v[208:211], v[174:177], v[52:55]
	v_mfma_f32_16x16x32_bf16 v[48:51], v[216:219], v[174:177], v[48:51]
	v_mfma_f32_16x16x32_bf16 v[36:39], v[208:211], v[182:185], v[36:39]
	v_mfma_f32_16x16x32_bf16 v[32:35], v[216:219], v[182:185], v[32:35]
	v_mfma_f32_16x16x32_bf16 v[20:23], v[208:211], v[190:193], v[20:23]
	v_mfma_f32_16x16x32_bf16 v[16:19], v[216:219], v[190:193], v[16:19]
	v_mfma_f32_16x16x32_bf16 v[4:7], v[208:211], v[198:201], v[4:7]
	v_mfma_f32_16x16x32_bf16 v[0:3], v[216:219], v[198:201], v[0:3]
	v_mfma_f32_16x16x32_bf16 v[52:55], v[212:215], v[178:181], v[52:55]
	v_mfma_f32_16x16x32_bf16 v[48:51], v[220:223], v[178:181], v[48:51]
	v_mfma_f32_16x16x32_bf16 v[36:39], v[212:215], v[186:189], v[36:39]
	v_mfma_f32_16x16x32_bf16 v[32:35], v[220:223], v[186:189], v[32:35]
	v_mfma_f32_16x16x32_bf16 v[20:23], v[212:215], v[194:197], v[20:23]
	v_mfma_f32_16x16x32_bf16 v[16:19], v[220:223], v[194:197], v[16:19]
	v_mfma_f32_16x16x32_bf16 v[4:7], v[212:215], v[204:207], v[4:7]
	v_mfma_f32_16x16x32_bf16 v[0:3], v[220:223], v[204:207], v[0:3]
	s_setprio 0
	s_add_i32 s43, 0, 0x18000
	v_add_u32_e32 v136, s43, v160
	s_barrier
	ds_read_b128 v[152:155], v136
	ds_read_b128 v[156:159], v136 offset:1024
	ds_read_b128 v[166:169], v136 offset:2048
	ds_read_b128 v[170:173], v136 offset:3072
	s_add_u32 s8, s62, 0x180000
	s_addc_u32 s9, s63, 0
	s_mov_b32 m0, s35
	v_lshl_add_u64 v[208:209], s[8:9], 0, v[128:129]
	ds_read_b128 v[174:177], v162 offset:32768
	ds_read_b128 v[178:181], v162 offset:33792
	ds_read_b128 v[182:185], v162 offset:34816
	ds_read_b128 v[186:189], v162 offset:35840
	ds_read_b128 v[190:193], v162 offset:36864
	ds_read_b128 v[194:197], v162 offset:37888
	ds_read_b128 v[198:201], v162 offset:38912
	ds_read_b128 v[204:207], v162 offset:39936
	global_load_lds_dwordx4 v[208:209], off
	v_lshl_add_u64 v[208:209], s[8:9], 0, v[132:133]
	s_mov_b32 m0, s36
	s_nop 0
	global_load_lds_dwordx4 v[208:209], off
	s_waitcnt lgkmcnt(8)
	s_barrier
	s_waitcnt lgkmcnt(0)
	s_setprio 1
	s_waitcnt lgkmcnt(0)
	v_mfma_f32_16x16x32_bf16 v[124:127], v[152:155], v[174:177], v[124:127]
	v_mfma_f32_16x16x32_bf16 v[120:123], v[166:169], v[174:177], v[120:123]
	v_mfma_f32_16x16x32_bf16 v[108:111], v[152:155], v[182:185], v[108:111]
	v_mfma_f32_16x16x32_bf16 v[104:107], v[166:169], v[182:185], v[104:107]
	v_mfma_f32_16x16x32_bf16 v[92:95], v[152:155], v[190:193], v[92:95]
	v_mfma_f32_16x16x32_bf16 v[88:91], v[166:169], v[190:193], v[88:91]
	v_mfma_f32_16x16x32_bf16 v[76:79], v[152:155], v[198:201], v[76:79]
	v_mfma_f32_16x16x32_bf16 v[72:75], v[166:169], v[198:201], v[72:75]
	v_mfma_f32_16x16x32_bf16 v[124:127], v[156:159], v[178:181], v[124:127]
	v_mfma_f32_16x16x32_bf16 v[120:123], v[170:173], v[178:181], v[120:123]
	v_mfma_f32_16x16x32_bf16 v[108:111], v[156:159], v[186:189], v[108:111]
	v_mfma_f32_16x16x32_bf16 v[104:107], v[170:173], v[186:189], v[104:107]
	v_mfma_f32_16x16x32_bf16 v[92:95], v[156:159], v[194:197], v[92:95]
	v_mfma_f32_16x16x32_bf16 v[88:91], v[170:173], v[194:197], v[88:91]
	v_mfma_f32_16x16x32_bf16 v[76:79], v[156:159], v[204:207], v[76:79]
	v_mfma_f32_16x16x32_bf16 v[72:75], v[170:173], v[204:207], v[72:75]
	s_setprio 0
	s_barrier
	s_add_i32 s62, 0, 0x1c000
	s_add_i32 s8, s43, s30
	v_add_u32_e32 v136, s62, v160
	v_lshl_add_u64 v[224:225], v[224:225], 0, s[14:15]
	s_mov_b32 m0, s8
	ds_read_b128 v[208:211], v136
	ds_read_b128 v[212:215], v136 offset:1024
	ds_read_b128 v[216:219], v136 offset:2048
	ds_read_b128 v[220:223], v136 offset:3072
	global_load_lds_dwordx4 v[224:225], off
	v_lshl_add_u64 v[224:225], v[226:227], 0, s[14:15]
	s_add_i32 m0, s8, 0x2000
	s_nop 0
	global_load_lds_dwordx4 v[224:225], off
	s_barrier
	s_waitcnt lgkmcnt(0)
	s_setprio 1
	s_waitcnt lgkmcnt(0)
	v_mfma_f32_16x16x32_bf16 v[116:119], v[208:211], v[174:177], v[116:119]
	v_mfma_f32_16x16x32_bf16 v[112:115], v[216:219], v[174:177], v[112:115]
	v_mfma_f32_16x16x32_bf16 v[100:103], v[208:211], v[182:185], v[100:103]
	v_mfma_f32_16x16x32_bf16 v[96:99], v[216:219], v[182:185], v[96:99]
	v_mfma_f32_16x16x32_bf16 v[84:87], v[208:211], v[190:193], v[84:87]
	v_mfma_f32_16x16x32_bf16 v[80:83], v[216:219], v[190:193], v[80:83]
	v_mfma_f32_16x16x32_bf16 v[68:71], v[208:211], v[198:201], v[68:71]
	v_mfma_f32_16x16x32_bf16 v[64:67], v[216:219], v[198:201], v[64:67]
	v_mfma_f32_16x16x32_bf16 v[116:119], v[212:215], v[178:181], v[116:119]
	v_mfma_f32_16x16x32_bf16 v[112:115], v[220:223], v[178:181], v[112:115]
	v_mfma_f32_16x16x32_bf16 v[100:103], v[212:215], v[186:189], v[100:103]
	v_mfma_f32_16x16x32_bf16 v[96:99], v[220:223], v[186:189], v[96:99]
	v_mfma_f32_16x16x32_bf16 v[84:87], v[212:215], v[194:197], v[84:87]
	v_mfma_f32_16x16x32_bf16 v[80:83], v[220:223], v[194:197], v[80:83]
	v_mfma_f32_16x16x32_bf16 v[68:71], v[212:215], v[204:207], v[68:71]
	v_mfma_f32_16x16x32_bf16 v[64:67], v[220:223], v[204:207], v[64:67]
	s_setprio 0
	s_mov_b32 m0, s54
	v_lshl_add_u64 v[224:225], v[228:229], 0, s[14:15]
	s_barrier
; #define G_STAGE(bufoff, gbase, voff) do { _Pragma("unroll") for (int _i = 0; _i < 2; ++_i) \
;         __builtin_amdgcn_global_load_lds((const unsigned*)((const char*)(gbase) + (voff)[_i]), (LAS unsigned*)(lds + (bufoff) + ldsw + _i * 8192), 16, 0, 0); } while (0)
; #define G_MMA(ai, bj, At, Bt_) do { __builtin_amdgcn_s_setprio(1); _Pragma("unroll") for (int m = 0; m < 4; ++m) _Pragma("unroll") for (int n = 0; n < 2; ++n) _Pragma("unroll") for (int k = 0; k < 2; ++k) \
;         acc[ai][bj][m][n] = __builtin_amdgcn_mfma_f32_16x16x32_bf16(Bt_[n][k], At[m][k], acc[ai][bj][m][n], 0, 0, 0); __builtin_amdgcn_s_setprio(0); } while (0)
; #define G_WAIT_V(n) asm volatile("s_waitcnt vmcnt(" #n ")" ::: "memory")
; template <class Epi, bool PERMROWS = false>
; DI void gemm_phase(LAS unsigned char* lds, const bf16_t* A, int lda, const bf16_t* Bt, int K, const Sched& S, const Epi& E) {
;     ...
;             G_STAGE(G_SB(1, 1), b3 + hstepB, voffB);
;             G_WAIT_V(6); G_BAR; G_MMA(1, 1, At, B1); G_BAR;
; DI float row_rstd(const unsigned char* ws, int row, int which, int fq) {
;     const f32x4 s4 = *(const f32x4*)((const float*)(ws + WS_SSQ) + (size_t)row * 32 + which * 16 + fq * 4);
;     float ss = s4[0] + s4[1] + s4[2] + s4[3];
;     ss += __shfl_xor(ss, 16); ss += __shfl_xor(ss, 32);
;     return rsqrtf(ss * (1.f / 512.f) + 1e-6f);
; }
;     DI void operator()(const f32x4 (&acc)[2][2][4][2], const Unit& u, int wr, int wc, int fr, int fq) const {
;         bf16_t* Q = (bf16_t*)(ws + WS_QM);
;         const int b = u.pm / 9;
; #pragma unroll
;         for (int ai = 0; ai < 2; ++ai)
; #pragma unroll
;             for (int m = 0; m < 4; ++m) {
;                 const int row = u.pm * BM + ai * HALF + wr * 64 + m * 16 + fr;
;                 const int r = row - b * RB; const bool lat = r >= CL; const int t = r - CL;
;                 const float rs = row_rstd(ws, row, 0, fq);
; #pragma unroll
;                 for (int bj = 0; bj < 2; ++bj) {
;                     const int colg = u.pn * BM + bj * HALF + wc * 32;
;                     if (colg >= 960) continue;
;                     f32x4 v0 = acc[ai][bj][m][0] * rs, v1 = acc[ai][bj][m][1] * rs;
;                     const int hc = colg % 192;
;                     if (hc >= 128 && lat) rope4(v0, v1, (const float*)(ws + WS_TABM) + ((size_t)t * 32 + ((hc - 128) >> 5) * 16 + 4 * fq) * 2);
	ds_read_b128 v[174:177], v162 offset:49152
	ds_read_b128 v[178:181], v162 offset:50176
	ds_read_b128 v[182:185], v162 offset:51200
	ds_read_b128 v[186:189], v162 offset:52224
	ds_read_b128 v[190:193], v162 offset:53248
	ds_read_b128 v[194:197], v162 offset:54272
	ds_read_b128 v[198:201], v162 offset:55296
	ds_read_b128 v[204:207], v162 offset:56320
	global_load_lds_dwordx4 v[224:225], off
	v_lshl_add_u64 v[224:225], v[230:231], 0, s[14:15]
	s_mov_b32 m0, s70
	s_nop 0
	global_load_lds_dwordx4 v[224:225], off
	s_barrier
	s_waitcnt lgkmcnt(0)
	s_setprio 1
	s_waitcnt lgkmcnt(0)
	v_mfma_f32_16x16x32_bf16 v[60:63], v[152:155], v[174:177], v[60:63]
	v_mfma_f32_16x16x32_bf16 v[56:59], v[166:169], v[174:177], v[56:59]
	v_mfma_f32_16x16x32_bf16 v[44:47], v[152:155], v[182:185], v[44:47]
	v_mfma_f32_16x16x32_bf16 v[40:43], v[166:169], v[182:185], v[40:43]
	v_mfma_f32_16x16x32_bf16 v[28:31], v[152:155], v[190:193], v[28:31]
	v_mfma_f32_16x16x32_bf16 v[24:27], v[166:169], v[190:193], v[24:27]
	v_mfma_f32_16x16x32_bf16 v[12:15], v[152:155], v[198:201], v[12:15]
	v_mfma_f32_16x16x32_bf16 v[8:11], v[166:169], v[198:201], v[8:11]
	v_mfma_f32_16x16x32_bf16 v[60:63], v[156:159], v[178:181], v[60:63]
	v_mfma_f32_16x16x32_bf16 v[56:59], v[170:173], v[178:181], v[56:59]
	v_mfma_f32_16x16x32_bf16 v[44:47], v[156:159], v[186:189], v[44:47]
	v_mfma_f32_16x16x32_bf16 v[40:43], v[170:173], v[186:189], v[40:43]
	v_mfma_f32_16x16x32_bf16 v[28:31], v[156:159], v[194:197], v[28:31]
	v_mfma_f32_16x16x32_bf16 v[24:27], v[170:173], v[194:197], v[24:27]
	v_mfma_f32_16x16x32_bf16 v[12:15], v[156:159], v[204:207], v[12:15]
	v_mfma_f32_16x16x32_bf16 v[8:11], v[170:173], v[204:207], v[8:11]
	s_setprio 0
	s_barrier
	s_add_u32 s8, s10, 0x20080
	s_addc_u32 s9, s11, 0
	s_add_i32 s10, s62, s30
	v_lshl_add_u64 v[152:153], s[8:9], 0, v[130:131]
	s_mov_b32 m0, s10
	s_nop 0
	global_load_lds_dwordx4 v[152:153], off
	v_lshl_add_u64 v[152:153], s[8:9], 0, v[134:135]
	s_add_i32 m0, s10, 0x2000
	s_nop 0
	global_load_lds_dwordx4 v[152:153], off
	s_waitcnt vmcnt(6)
	s_barrier
	s_setprio 1
	v_mfma_f32_16x16x32_bf16 v[52:55], v[208:211], v[174:177], v[52:55]
	v_mfma_f32_16x16x32_bf16 v[48:51], v[216:219], v[174:177], v[48:51]
	v_mfma_f32_16x16x32_bf16 v[36:39], v[208:211], v[182:185], v[36:39]
	v_mfma_f32_16x16x32_bf16 v[32:35], v[216:219], v[182:185], v[32:35]
	v_mfma_f32_16x16x32_bf16 v[20:23], v[208:211], v[190:193], v[20:23]
	v_mfma_f32_16x16x32_bf16 v[16:19], v[216:219], v[190:193], v[16:19]
	v_mfma_f32_16x16x32_bf16 v[4:7], v[208:211], v[198:201], v[4:7]
	v_mfma_f32_16x16x32_bf16 v[0:3], v[216:219], v[198:201], v[0:3]
	v_mfma_f32_16x16x32_bf16 v[52:55], v[212:215], v[178:181], v[52:55]
	v_mfma_f32_16x16x32_bf16 v[48:51], v[220:223], v[178:181], v[48:51]
	v_mfma_f32_16x16x32_bf16 v[36:39], v[212:215], v[186:189], v[36:39]
	v_mfma_f32_16x16x32_bf16 v[32:35], v[220:223], v[186:189], v[32:35]
	v_mfma_f32_16x16x32_bf16 v[20:23], v[212:215], v[194:197], v[20:23]
	v_mfma_f32_16x16x32_bf16 v[16:19], v[220:223], v[194:197], v[16:19]
	v_mfma_f32_16x16x32_bf16 v[4:7], v[212:215], v[204:207], v[4:7]
	v_mfma_f32_16x16x32_bf16 v[0:3], v[220:223], v[204:207], v[0:3]
	s_setprio 0
	s_add_i32 s29, s29, 2
	s_add_u32 s42, s42, 0x100
	s_addc_u32 s28, s28, 0
	s_cmp_gt_u32 s29, 5
	s_mov_b64 s[8:9], s[4:5]
	s_barrier
	s_cbranch_scc0 .LBB0_2434
	v_and_b32_e32 v156, 15, v202
	v_bfe_u32 v157, v202, 8, 1
	v_lshl_add_u32 v252, v157, 6, v156
	v_bfe_u32 v136, v202, 4, 2
	v_bfe_u32 v157, v202, 6, 2
	v_and_b32_e32 v156, 63, v202
	v_readfirstlane_b32 s32, v157
	v_xor_b32_e32 v158, 16, v156
	v_xor_b32_e32 v159, 32, v156
	v_lshlrev_b32_e32 v158, 2, v158
	v_lshlrev_b32_e32 v159, 2, v159
	v_lshlrev_b32_e32 v156, 4, v136
	v_lshl_add_u32 v182, v252, 7, v156
	v_add_u32_e32 v183, 0x800, v182
	v_add_u32_e32 v184, 0x1000, v182
	v_add_u32_e32 v185, 0x1800, v182
	v_add_u32_e32 v186, 0x4000, v182
	v_add_u32_e32 v187, 0x4800, v182
	v_add_u32_e32 v188, 0x5000, v182
	v_add_u32_e32 v189, 0x5800, v182
	s_lshl_b32 s1, s12, 15
	s_add_u32 s8, s50, 0x200000
	s_addc_u32 s9, s51, 0
	s_add_u32 s8, s8, s1
	s_addc_u32 s9, s9, 0
	global_load_dwordx4 v[204:207], v182, s[8:9]
	global_load_dwordx4 v[208:211], v183, s[8:9]
	global_load_dwordx4 v[212:215], v184, s[8:9]
	global_load_dwordx4 v[216:219], v185, s[8:9]
	global_load_dwordx4 v[220:223], v186, s[8:9]
	global_load_dwordx4 v[224:227], v187, s[8:9]
	global_load_dwordx4 v[228:231], v188, s[8:9]
	global_load_dwordx4 v[232:235], v189, s[8:9]
	s_mul_i32 s1, s12, 57
	s_lshr_b32 s1, s1, 9
	s_mul_i32 s1, s1, 9
	s_sub_u32 s81, s12, s1
	s_lshl_b32 s1, s0, 8
	s_lshl_b32 s29, s32, 5
	s_add_u32 s1, s1, s29
	s_mov_b32 s82, -1
	s_mul_i32 s29, s1, 0xaaab
	s_lshr_b32 s29, s29, 23
	s_mul_i32 s29, s29, 0xc0
	s_sub_u32 s29, s1, s29
	s_cmpk_lt_u32 s29, 0x80
	s_cbranch_scc1 .Lqu1_nr0
	s_mov_b32 s82, 0
	s_sub_u32 s83, s29, 0x80
	s_lshr_b32 s83, s83, 5

; DI float row_rstd(const unsigned char* ws, int row, int which, int fq) {
;     const f32x4 s4 = *(const f32x4*)((const float*)(ws + WS_SSQ) + (size_t)row * 32 + which * 16 + fq * 4);
;     float ss = s4[0] + s4[1] + s4[2] + s4[3];
;     ss += __shfl_xor(ss, 16); ss += __shfl_xor(ss, 32);
;     return rsqrtf(ss * (1.f / 512.f) + 1e-6f);
;     DI void operator()(const f32x4 (&acc)[2][2][4][2], const Unit& u, int wr, int wc, int fr, int fq) const {
;     ...
;                 const float rs = row_rstd(ws, row, 0, fq);
; #pragma unroll
;                 for (int bj = 0; bj < 2; ++bj) {
;                     const int colg = u.pn * BM + bj * HALF + wc * 32;
;                     if (colg >= 960) continue;
;                     f32x4 v0 = acc[ai][bj][m][0] * rs, v1 = acc[ai][bj][m][1] * rs;
.Lqu1_ssq:
	v_add_f32_e32 v204, v204, v205
	v_add_f32_e32 v206, v206, v207
	v_add_f32_e32 v204, v204, v206
	v_add_f32_e32 v208, v208, v209
	v_add_f32_e32 v210, v210, v211
	v_add_f32_e32 v208, v208, v210
	v_add_f32_e32 v212, v212, v213
	v_add_f32_e32 v214, v214, v215
	v_add_f32_e32 v212, v212, v214
	v_add_f32_e32 v216, v216, v217
	v_add_f32_e32 v218, v218, v219
	v_add_f32_e32 v216, v216, v218
	v_add_f32_e32 v220, v220, v221
	v_add_f32_e32 v222, v222, v223
	v_add_f32_e32 v220, v220, v222
	v_add_f32_e32 v224, v224, v225
	v_add_f32_e32 v226, v226, v227
	v_add_f32_e32 v224, v224, v226
	v_add_f32_e32 v228, v228, v229
	v_add_f32_e32 v230, v230, v231
	v_add_f32_e32 v228, v228, v230
	v_add_f32_e32 v232, v232, v233
	v_add_f32_e32 v234, v234, v235
	v_add_f32_e32 v232, v232, v234
	ds_bpermute_b32 v205, v158, v204
	ds_bpermute_b32 v209, v158, v208
	ds_bpermute_b32 v213, v158, v212
	ds_bpermute_b32 v217, v158, v216
	ds_bpermute_b32 v221, v158, v220
	ds_bpermute_b32 v225, v158, v224
	ds_bpermute_b32 v229, v158, v228
	ds_bpermute_b32 v233, v158, v232
	s_waitcnt lgkmcnt(0)
	v_add_f32_e32 v204, v204, v205
	v_add_f32_e32 v208, v208, v209
	v_add_f32_e32 v212, v212, v213
	v_add_f32_e32 v216, v216, v217
	v_add_f32_e32 v220, v220, v221
	v_add_f32_e32 v224, v224, v225
	v_add_f32_e32 v228, v228, v229
	v_add_f32_e32 v232, v232, v233
	ds_bpermute_b32 v205, v159, v204
	ds_bpermute_b32 v209, v159, v208
	ds_bpermute_b32 v213, v159, v212
	ds_bpermute_b32 v217, v159, v216
	ds_bpermute_b32 v221, v159, v220
	ds_bpermute_b32 v225, v159, v224
	ds_bpermute_b32 v229, v159, v228
	ds_bpermute_b32 v233, v159, v232
	s_waitcnt lgkmcnt(0)
	s_mov_b32 s29, 0x3b000000
	v_mov_b32_e32 v156, 0x358637bd
	v_add_f32_e32 v204, v204, v205
	v_fma_f32 v204, v204, s29, v156
	v_add_f32_e32 v208, v208, v209
	v_fma_f32 v208, v208, s29, v156
	v_add_f32_e32 v212, v212, v213
	v_fma_f32 v212, v212, s29, v156
	v_add_f32_e32 v216, v216, v217
	v_fma_f32 v216, v216, s29, v156
	v_add_f32_e32 v220, v220, v221
	v_fma_f32 v220, v220, s29, v156
	v_add_f32_e32 v224, v224, v225
	v_fma_f32 v224, v224, s29, v156
	v_add_f32_e32 v228, v228, v229
	v_fma_f32 v228, v228, s29, v156
	v_add_f32_e32 v232, v232, v233
	v_fma_f32 v232, v232, s29, v156
	v_rsq_f32_e32 v182, v204
	v_rsq_f32_e32 v183, v208
	v_rsq_f32_e32 v184, v212
	v_rsq_f32_e32 v185, v216
	v_rsq_f32_e32 v186, v220
	v_rsq_f32_e32 v187, v224
	v_rsq_f32_e32 v188, v228
	v_rsq_f32_e32 v189, v232
	s_nop 0
	v_mul_f32_e32 v124, v124, v182
	v_mul_f32_e32 v125, v125, v182
	v_mul_f32_e32 v126, v126, v182
	v_mul_f32_e32 v127, v127, v182
	v_mul_f32_e32 v120, v120, v182
	v_mul_f32_e32 v121, v121, v182
	v_mul_f32_e32 v122, v122, v182
	v_mul_f32_e32 v123, v123, v182
	v_mul_f32_e32 v116, v116, v182
	v_mul_f32_e32 v117, v117, v182
	v_mul_f32_e32 v118, v118, v182
	v_mul_f32_e32 v119, v119, v182
	v_mul_f32_e32 v112, v112, v182
	v_mul_f32_e32 v113, v113, v182
	v_mul_f32_e32 v114, v114, v182
	v_mul_f32_e32 v115, v115, v182
	v_mul_f32_e32 v108, v108, v183
	v_mul_f32_e32 v109, v109, v183
	v_mul_f32_e32 v110, v110, v183
	v_mul_f32_e32 v111, v111, v183
	v_mul_f32_e32 v104, v104, v183
	v_mul_f32_e32 v105, v105, v183
	v_mul_f32_e32 v106, v106, v183
	v_mul_f32_e32 v107, v107, v183
	v_mul_f32_e32 v100, v100, v183
	v_mul_f32_e32 v101, v101, v183
	v_mul_f32_e32 v102, v102, v183
	v_mul_f32_e32 v103, v103, v183
	v_mul_f32_e32 v96, v96, v183
	v_mul_f32_e32 v97, v97, v183
	v_mul_f32_e32 v98, v98, v183
	v_mul_f32_e32 v99, v99, v183
	v_mul_f32_e32 v92, v92, v184
	v_mul_f32_e32 v93, v93, v184
	v_mul_f32_e32 v94, v94, v184
	v_mul_f32_e32 v95, v95, v184
	v_mul_f32_e32 v88, v88, v184
	v_mul_f32_e32 v89, v89, v184
	v_mul_f32_e32 v90, v90, v184
	v_mul_f32_e32 v91, v91, v184
	v_mul_f32_e32 v84, v84, v184
	v_mul_f32_e32 v85, v85, v184
	v_mul_f32_e32 v86, v86, v184
	v_mul_f32_e32 v87, v87, v184
	v_mul_f32_e32 v80, v80, v184
	v_mul_f32_e32 v81, v81, v184
	v_mul_f32_e32 v82, v82, v184
	v_mul_f32_e32 v83, v83, v184
	v_mul_f32_e32 v76, v76, v185
	v_mul_f32_e32 v77, v77, v185
	v_mul_f32_e32 v78, v78, v185
	v_mul_f32_e32 v79, v79, v185
	v_mul_f32_e32 v72, v72, v185
	v_mul_f32_e32 v73, v73, v185
	v_mul_f32_e32 v74, v74, v185
	v_mul_f32_e32 v75, v75, v185
	v_mul_f32_e32 v68, v68, v185
	v_mul_f32_e32 v69, v69, v185
	v_mul_f32_e32 v70, v70, v185
	v_mul_f32_e32 v71, v71, v185
	v_mul_f32_e32 v64, v64, v185
	v_mul_f32_e32 v65, v65, v185
	v_mul_f32_e32 v66, v66, v185
	v_mul_f32_e32 v67, v67, v185
	v_mul_f32_e32 v60, v60, v186
	v_mul_f32_e32 v61, v61, v186
	v_mul_f32_e32 v62, v62, v186
	v_mul_f32_e32 v63, v63, v186
	v_mul_f32_e32 v56, v56, v186
	v_mul_f32_e32 v57, v57, v186
	v_mul_f32_e32 v58, v58, v186
	v_mul_f32_e32 v59, v59, v186
	v_mul_f32_e32 v52, v52, v186
	v_mul_f32_e32 v53, v53, v186
	v_mul_f32_e32 v54, v54, v186
	v_mul_f32_e32 v55, v55, v186
	v_mul_f32_e32 v48, v48, v186
	v_mul_f32_e32 v49, v49, v186
	v_mul_f32_e32 v50, v50, v186
	v_mul_f32_e32 v51, v51, v186
	v_mul_f32_e32 v44, v44, v187
	v_mul_f32_e32 v45, v45, v187
	v_mul_f32_e32 v46, v46, v187
	v_mul_f32_e32 v47, v47, v187
	v_mul_f32_e32 v40, v40, v187
	v_mul_f32_e32 v41, v41, v187
	v_mul_f32_e32 v42, v42, v187
	v_mul_f32_e32 v43, v43, v187
	v_mul_f32_e32 v36, v36, v187
	v_mul_f32_e32 v37, v37, v187
	v_mul_f32_e32 v38, v38, v187
	v_mul_f32_e32 v39, v39, v187
	v_mul_f32_e32 v32, v32, v187
	v_mul_f32_e32 v33, v33, v187
	v_mul_f32_e32 v34, v34, v187
	v_mul_f32_e32 v35, v35, v187
	v_mul_f32_e32 v28, v28, v188
	v_mul_f32_e32 v29, v29, v188
	v_mul_f32_e32 v30, v30, v188
	v_mul_f32_e32 v31, v31, v188
	v_mul_f32_e32 v24, v24, v188
	v_mul_f32_e32 v25, v25, v188
	v_mul_f32_e32 v26, v26, v188
	v_mul_f32_e32 v27, v27, v188
	v_mul_f32_e32 v20, v20, v188
	v_mul_f32_e32 v21, v21, v188
	v_mul_f32_e32 v22, v22, v188
	v_mul_f32_e32 v23, v23, v188
	v_mul_f32_e32 v16, v16, v188
	v_mul_f32_e32 v17, v17, v188
	v_mul_f32_e32 v18, v18, v188
	v_mul_f32_e32 v19, v19, v188
	v_mul_f32_e32 v12, v12, v189
	v_mul_f32_e32 v13, v13, v189
	v_mul_f32_e32 v14, v14, v189
	v_mul_f32_e32 v15, v15, v189
	v_mul_f32_e32 v8, v8, v189
	v_mul_f32_e32 v9, v9, v189
	v_mul_f32_e32 v10, v10, v189
	v_mul_f32_e32 v11, v11, v189
	v_mul_f32_e32 v4, v4, v189
	v_mul_f32_e32 v5, v5, v189
	v_mul_f32_e32 v6, v6, v189
	v_mul_f32_e32 v7, v7, v189
	v_mul_f32_e32 v0, v0, v189
	v_mul_f32_e32 v1, v1, v189
	v_mul_f32_e32 v2, v2, v189
	v_mul_f32_e32 v3, v3, v189
	s_add_u32 s8, s50, 0x1a3a0000
	s_addc_u32 s9, s51, 0
	s_lshl_b32 s29, s12, 8
	s_mul_i32 s29, s29, 0x780
	s_add_u32 s8, s8, s29
	s_addc_u32 s9, s9, 0
	s_cmp_eq_u32 s82, 0
	s_cbranch_scc0 .Lqu1_nrp0
; DI void rope4(f32x4& v0, f32x4& v1, const float* tab  ) {
;     const f32x4 t0 = *(const f32x4*)tab, t1 = *(const f32x4*)(tab + 4);
;     const float c[4] = {t0[0], t0[2], t1[0], t1[2]}, s[4] = {t0[1], t0[3], t1[1], t1[3]};
; #pragma unroll
;     for (int j = 0; j < 4; ++j) { const float a = v0[j], b = v1[j]; v0[j] = a * c[j] - b * s[j]; v1[j] = b * c[j] + a * s[j]; }
; }
;     DI void operator()(const f32x4 (&acc)[2][2][4][2], const Unit& u, int wr, int wc, int fr, int fq) const {
;     ...
;                     if (hc >= 128 && lat) rope4(v0, v1, (const float*)(ws + WS_TABM) + ((size_t)t * 32 + ((hc - 128) >> 5) * 16 + 4 * fq) * 2);
	global_load_dwordx4 v[204:207], v194, s[10:11]
	global_load_dwordx4 v[208:211], v194, s[10:11] offset:16
	global_load_dwordx4 v[212:215], v195, s[10:11]
	global_load_dwordx4 v[216:219], v195, s[10:11] offset:16
	global_load_dwordx4 v[220:223], v196, s[10:11]
	global_load_dwordx4 v[224:227], v196, s[10:11] offset:16
	global_load_dwordx4 v[228:231], v197, s[10:11]
	global_load_dwordx4 v[232:235], v197, s[10:11] offset:16
	s_waitcnt vmcnt(8)
	v_mul_f32_e32 v156, v124, v237
	v_mul_f32_e32 v124, v124, v236
	v_fma_f32 v124, -v120, v237, v124
	v_fma_f32 v120, v120, v236, v156
	v_mul_f32_e32 v156, v125, v239
	v_mul_f32_e32 v125, v125, v238
	v_fma_f32 v125, -v121, v239, v125
	v_fma_f32 v121, v121, v238, v156
	v_mul_f32_e32 v156, v126, v241
	v_mul_f32_e32 v126, v126, v240
	v_fma_f32 v126, -v122, v241, v126
	v_fma_f32 v122, v122, v240, v156
	v_mul_f32_e32 v156, v127, v243
	v_mul_f32_e32 v127, v127, v242
	v_fma_f32 v127, -v123, v243, v127
	v_fma_f32 v123, v123, v242, v156
	v_mul_f32_e32 v156, v108, v245
	v_mul_f32_e32 v108, v108, v244
	v_fma_f32 v108, -v104, v245, v108
	v_fma_f32 v104, v104, v244, v156
	v_mul_f32_e32 v156, v109, v247
	v_mul_f32_e32 v109, v109, v246
	v_fma_f32 v109, -v105, v247, v109
	v_fma_f32 v105, v105, v246, v156
	v_mul_f32_e32 v156, v110, v249
	v_mul_f32_e32 v110, v110, v248
	v_fma_f32 v110, -v106, v249, v110
	v_fma_f32 v106, v106, v248, v156
	v_mul_f32_e32 v156, v111, v251
	v_mul_f32_e32 v111, v111, v250
	v_fma_f32 v111, -v107, v251, v111
	v_fma_f32 v107, v107, v250, v156
	v_mul_f32_e32 v156, v92, v167
	v_mul_f32_e32 v92, v92, v166
	v_fma_f32 v92, -v88, v167, v92
	v_fma_f32 v88, v88, v166, v156
	v_mul_f32_e32 v156, v93, v169
	v_mul_f32_e32 v93, v93, v168
	v_fma_f32 v93, -v89, v169, v93
	v_fma_f32 v89, v89, v168, v156
	v_mul_f32_e32 v156, v94, v171
	v_mul_f32_e32 v94, v94, v170
	v_fma_f32 v94, -v90, v171, v94
	v_fma_f32 v90, v90, v170, v156
	v_mul_f32_e32 v156, v95, v173
	v_mul_f32_e32 v95, v95, v172
	v_fma_f32 v95, -v91, v173, v95
	v_fma_f32 v91, v91, v172, v156
	v_mul_f32_e32 v156, v76, v175
	v_mul_f32_e32 v76, v76, v174
	v_fma_f32 v76, -v72, v175, v76
	v_fma_f32 v72, v72, v174, v156
	v_mul_f32_e32 v156, v77, v177
	v_mul_f32_e32 v77, v77, v176
	v_fma_f32 v77, -v73, v177, v77
	v_fma_f32 v73, v73, v176, v156
	v_mul_f32_e32 v156, v78, v179
	v_mul_f32_e32 v78, v78, v178
	v_fma_f32 v78, -v74, v179, v78
	v_fma_f32 v74, v74, v178, v156
	v_mul_f32_e32 v156, v79, v181
	v_mul_f32_e32 v79, v79, v180
	v_fma_f32 v79, -v75, v181, v79
	v_fma_f32 v75, v75, v180, v156
	s_waitcnt vmcnt(0)
	v_mul_f32_e32 v156, v60, v205
	v_mul_f32_e32 v60, v60, v204
	v_fma_f32 v60, -v56, v205, v60
	v_fma_f32 v56, v56, v204, v156
	v_mul_f32_e32 v156, v61, v207
	v_mul_f32_e32 v61, v61, v206
	v_fma_f32 v61, -v57, v207, v61
	v_fma_f32 v57, v57, v206, v156
	v_mul_f32_e32 v156, v62, v209
	v_mul_f32_e32 v62, v62, v208
	v_fma_f32 v62, -v58, v209, v62
	v_fma_f32 v58, v58, v208, v156
	v_mul_f32_e32 v156, v63, v211
	v_mul_f32_e32 v63, v63, v210
	v_fma_f32 v63, -v59, v211, v63
	v_fma_f32 v59, v59, v210, v156
	v_mul_f32_e32 v156, v44, v213
	v_mul_f32_e32 v44, v44, v212
	v_fma_f32 v44, -v40, v213, v44
	v_fma_f32 v40, v40, v212, v156
	v_mul_f32_e32 v156, v45, v215
	v_mul_f32_e32 v45, v45, v214
	v_fma_f32 v45, -v41, v215, v45
	v_fma_f32 v41, v41, v214, v156
	v_mul_f32_e32 v156, v46, v217
	v_mul_f32_e32 v46, v46, v216
	v_fma_f32 v46, -v42, v217, v46
	v_fma_f32 v42, v42, v216, v156
	v_mul_f32_e32 v156, v47, v219
	v_mul_f32_e32 v47, v47, v218
	v_fma_f32 v47, -v43, v219, v47
	v_fma_f32 v43, v43, v218, v156
	v_mul_f32_e32 v156, v28, v221
	v_mul_f32_e32 v28, v28, v220
	v_fma_f32 v28, -v24, v221, v28
	v_fma_f32 v24, v24, v220, v156
	v_mul_f32_e32 v156, v29, v223
	v_mul_f32_e32 v29, v29, v222
	v_fma_f32 v29, -v25, v223, v29
	v_fma_f32 v25, v25, v222, v156
	v_mul_f32_e32 v156, v30, v225
	v_mul_f32_e32 v30, v30, v224
	v_fma_f32 v30, -v26, v225, v30
	v_fma_f32 v26, v26, v224, v156
	v_mul_f32_e32 v156, v31, v227
	v_mul_f32_e32 v31, v31, v226
	v_fma_f32 v31, -v27, v227, v31
	v_fma_f32 v27, v27, v226, v156
	v_mul_f32_e32 v156, v12, v229
	v_mul_f32_e32 v12, v12, v228
	v_fma_f32 v12, -v8, v229, v12
	v_fma_f32 v8, v8, v228, v156
	v_mul_f32_e32 v156, v13, v231
	v_mul_f32_e32 v13, v13, v230
	v_fma_f32 v13, -v9, v231, v13
	v_fma_f32 v9, v9, v230, v156
	v_mul_f32_e32 v156, v14, v233
	v_mul_f32_e32 v14, v14, v232
	v_fma_f32 v14, -v10, v233, v14
	v_fma_f32 v10, v10, v232, v156
	v_mul_f32_e32 v156, v15, v235
	v_mul_f32_e32 v15, v15, v234
	v_fma_f32 v15, -v11, v235, v15
	v_fma_f32 v11, v11, v234, v156

; #define G_WAIT_V(n) asm volatile("s_waitcnt vmcnt(" #n ")" ::: "memory")
; #define G_BAR __builtin_amdgcn_s_barrier()
; template <class Epi, bool PERMROWS = false>
; DI void gemm_phase(LAS unsigned char* lds, const bf16_t* A, int lda, const bf16_t* Bt, int K, const Sched& S, const Epi& E) {
;     ...
;         E(acc, cur, wr, wc, fr, fq);
;         if (!has_next) break;
; #pragma unroll
;         for (int a = 0; a < 2; ++a)
; #pragma unroll
;             for (int b = 0; b < 2; ++b)
; #pragma unroll
;                 for (int m = 0; m < 4; ++m)
; #pragma unroll
;                     for (int n = 0; n < 2; ++n) acc[a][b][m][n] = (f32x4){0.f, 0.f, 0.f, 0.f};
;         cur = nxt; cA = nA; cB = nB; ++ui; nt = cur.kq >= 0 ? ntQ : ntF;
;     }
;     G_WAIT_V(0);
;     if (wr == 0) G_BAR;
;     G_BAR;
.Lqu1_nst1:
	s_branch .LBB0_2428
.LBB0_2498:
	s_waitcnt vmcnt(0)
	s_cmpk_gt_u32 s6, 0xff
	s_cbranch_scc1 .LBB0_2500
	s_barrier

;     DI bool next(int i, Unit& u) const {
;         const long L = (long)i * G + c;
;         u.kq = -1;
;         if (split && L >= nwg) {
;             const int q = (int)(L - nwg); if (q >= 128) return false;
;             const int cu = q >> 2; u.kq = q & 3; u.pm = (cu >> 3) * 9; u.pn = cu & 7; return true;
;         }
;         if (L >= nwg) return false;
;         int wgid = (int)L; { const int q = nwg / NXCD, r = nwg % NXCD, xcd = wgid % NXCD, off = wgid / NXCD; wgid = (xcd < r ? xcd * (q + 1) : r * (q + 1) + (xcd - r) * q) + off; }
;         const int nig = WGM * nN, gid = wgid / nig, fm = gid * WGM, gsz = (nM - fm) < WGM ? (nM - fm) : WGM;
;         int pm = fm + ((wgid % nig) % gsz); u.pn = (wgid % nig) / gsz;
.LBB0_2501:
	v_readlane_b32 s0, v253, 19
	v_mov_b32_e32 v8, v202
	v_readlane_b32 s1, v253, 20
	s_andn2_b64 vcc, exec, s[0:1]
	v_readfirstlane_b32 s6, v8
	s_cbranch_vccnz .LBB0_2523
	s_lshr_b32 s0, s85, 29
	s_add_u32 s89, s26, 180
	s_and_b32 s89, s89, 0xff
	s_cmpk_eq_u32 s33, 0x100
	s_cselect_b32 s89, s89, s26
	s_add_i32 s2, s89, s0
	s_and_b32 s0, s2, -8
	s_sub_i32 s3, s89, s0
	s_cmp_gt_i32 s3, 3
	s_cbranch_scc0 .LBB0_2504
	s_mul_i32 s0, s3, 22
	s_add_i32 s4, s0, 4
	s_cbranch_execz .LBB0_2505
	s_branch .LBB0_2506

;     DI bool next(int i, Unit& u) const {
;         const long L = (long)i * G + c;
;         u.kq = -1;
;         if (split && L >= nwg) {
;             const int q = (int)(L - nwg); if (q >= 128) return false;
;             const int cu = q >> 2; u.kq = q & 3; u.pm = (cu >> 3) * 9; u.pn = cu & 7; return true;
;         }
;         if (L >= nwg) return false;
;         int wgid = (int)L; { const int q = nwg / NXCD, r = nwg % NXCD, xcd = wgid % NXCD, off = wgid / NXCD; wgid = (xcd < r ? xcd * (q + 1) : r * (q + 1) + (xcd - r) * q) + off; }
;         const int nig = WGM * nN, gid = wgid / nig, fm = gid * WGM, gsz = (nM - fm) < WGM ? (nM - fm) : WGM;
;         int pm = fm + ((wgid % nig) % gsz); u.pn = (wgid % nig) / gsz;
.LBB0_2509:
	s_add_i32 s42, s42, 1
	s_mul_i32 s0, s42, s84
	s_mul_hi_u32 s1, s42, s33
	s_add_i32 s1, s1, s0
	s_mul_i32 s0, s42, s33
	s_add_u32 s89, s26, 180
	s_and_b32 s89, s89, 0xff
	s_cmpk_eq_u32 s33, 0x100
	s_cselect_b32 s89, s89, s26
	s_add_u32 s0, s0, s89
	s_addc_u32 s1, s1, s85
	v_cmp_gt_i64_e64 s[2:3], s[0:1], v[148:149]
	v_cmp_lt_i64_e64 s[4:5], s[0:1], v[146:147]
	s_and_b64 vcc, exec, s[2:3]
	s_cbranch_vccnz .LBB0_2515
	s_ashr_i32 s1, s0, 31
	s_lshr_b32 s1, s1, 29
	s_add_i32 s12, s0, s1
	s_and_b32 s1, s12, -8
	s_sub_i32 s13, s0, s1
	s_cmp_gt_i32 s13, 3
	s_mov_b64 s[0:1], -1
	s_cbranch_scc0 .LBB0_2512
	s_mul_i32 s0, s13, 22
	s_add_i32 s14, s0, 4
	s_mov_b64 s[0:1], 0

; #define LAS __attribute__((address_space(3)))
; DI float ret_lg2(const Params& p, int l, int dir, int h) { return log1pf(-exp2f(p.in[12][(l * 2 + dir) * 5 + h])) * 1.4426950408889634f; }
; DI void phase_ret_scan(const Params& p, int l, LAS unsigned char* lds) {
;     ...
;         const int it = next_item(ctr, slot);
;         if (it >= 320) break;
;         const int dvb = it & 7, dir = (it >> 3) & 1, h = (it >> 4) % 5, b = it / 80, dkb = wid;
;         {
;             const bf16_t* vsrc = (const bf16_t*)(ws + WS_VTR) + ((size_t)b * 640 + h * 128 + dvb * 16) * RB;
;             u32x4 t[9];
; #pragma unroll
;             for (int i = 0; i < 9; ++i) { const int cid = tid + i * 512, rr = cid / 288, cc = cid % 288; t[i] = *(const u32x4*)(vsrc + (size_t)rr * RB + cc * 8); }
; #pragma unroll
;             for (int i = 0; i < 9; ++i) { const int cid = tid + i * 512, rr = cid / 288, cc = cid % 288; *(LAS u32x4*)(lds + rr * VRS + cc * 16) = t[i]; }
;         }
;         const float lg = ret_lg2(p, l, dir, h), gL = exp2f(lg * 128.f);
;         float wt[4][8];
; #pragma unroll
;         for (int ks = 0; ks < 4; ++ks)
; #pragma unroll
;             for (int e = 0; e < 8; ++e) { const int pp = ks * 32 + q4 * 8 + e; wt[ks][e] = exp2f(lg * (float)(dir == 0 ? 127 - pp : pp)); }
.LBB0_2529:
	s_or_b64 exec, exec, s[0:1]
	s_waitcnt vmcnt(0)
	v_mov_b32_e32 v0, s7
	s_waitcnt lgkmcnt(0)
	s_barrier
	ds_read_b32 v0, v0
	s_mov_b64 s[0:1], -1
	s_waitcnt lgkmcnt(0)
	v_cmp_lt_i32_e32 vcc, s12, v0
	v_readfirstlane_b32 s8, v0
	s_cbranch_vccnz .LBB0_2524
	s_ashr_i32 s0, s8, 4
	s_mul_hi_i32 s1, s0, 0x66666667
	s_lshr_b32 s2, s1, 31
	s_ashr_i32 s1, s1, 1
	s_add_i32 s1, s1, s2
	s_mul_i32 s1, s1, 5
	s_sub_i32 s2, s0, s1
	s_mul_hi_i32 s0, s8, 0x66666667
	s_lshr_b32 s1, s0, 31
	s_ashr_i32 s3, s0, 5
	s_add_i32 s3, s3, s1
	s_lshl_b32 s10, s2, 7
	s_mul_i32 s0, s3, 0x280
	s_ashr_i32 s11, s10, 31
	s_mul_hi_i32 s1, s3, 0x280
	s_add_u32 s0, s0, s10
	s_addc_u32 s1, s1, s11
	s_lshl_b32 s10, s8, 4
	s_and_b32 s17, s10, 0x70
	s_or_b32 s10, s0, s17
	s_mul_i32 s11, s1, 0x1200
	s_mul_hi_u32 s18, s10, 0x1200
	s_add_i32 s18, s18, s11
	s_mulk_i32 s10, 0x1200
	s_add_u32 s10, s87, s10
	s_addc_u32 s11, s91, s18
	s_bfe_u32 s18, s8, 0x10003
	v_lshl_add_u64 v[0:1], s[10:11], 0, v[44:45]
	v_lshl_add_u64 v[2:3], s[10:11], 0, v[48:49]
	v_lshl_add_u64 v[8:9], s[10:11], 0, v[52:53]
	s_mul_i32 s8, s18, 5
	v_lshl_add_u64 v[0:1], v[46:47], 1, v[0:1]
	v_lshl_add_u64 v[4:5], v[50:51], 1, v[2:3]
	v_lshl_add_u64 v[8:9], v[54:55], 1, v[8:9]
	v_lshl_add_u64 v[10:11], s[10:11], 0, v[56:57]
	s_add_i32 s8, s2, s8
	global_load_dwordx4 v[0:3], v[0:1], off
	s_nop 0
	global_load_dwordx4 v[4:7], v[4:5], off
	v_lshl_add_u64 v[10:11], v[58:59], 1, v[10:11]
	global_load_dwordx4 v[12:15], v[8:9], off
	global_load_dwordx4 v[16:19], v[10:11], off
	v_lshl_add_u64 v[8:9], s[10:11], 0, v[60:61]
	s_add_i32 s8, s8, 10
	v_lshl_add_u64 v[8:9], v[62:63], 1, v[8:9]
	v_lshl_add_u64 v[10:11], s[10:11], 0, v[64:65]
	s_lshl_b64 s[20:21], s[8:9], 2
	v_lshl_add_u64 v[10:11], v[66:67], 1, v[10:11]
	global_load_dwordx4 v[20:23], v[8:9], off
	global_load_dwordx4 v[24:27], v[10:11], off
	v_lshl_add_u64 v[8:9], s[10:11], 0, v[68:69]
	s_add_u32 s20, s60, s20
	v_lshl_add_u64 v[8:9], v[70:71], 1, v[8:9]
	v_lshl_add_u64 v[10:11], s[10:11], 0, v[72:73]
	s_addc_u32 s21, s61, s21
	v_lshl_add_u64 v[10:11], v[74:75], 1, v[10:11]
	global_load_dwordx4 v[28:31], v[8:9], off
	global_load_dwordx4 v[32:35], v[10:11], off
	global_load_dword v81, v41, s[20:21]
	v_lshl_add_u64 v[8:9], s[10:11], 0, v[76:77]
	v_lshl_add_u64 v[8:9], v[78:79], 1, v[8:9]
	global_load_dwordx4 v[8:11], v[8:9], off
	v_lshl_add_u64 v[166:167], v[38:39], 0, s[0:1]
	v_mad_u64_u32 v[84:85], s[0:1], v166, s6, v[42:43]
	v_mov_b32_e32 v40, v85
	v_mad_u64_u32 v[166:167], s[0:1], v167, s6, v[40:41]
	s_mul_i32 s3, s3, 5
	v_mov_b32_e32 v85, v166
	s_waitcnt vmcnt(0)
	ds_write_b128 v152, v[0:3]
	ds_write_b128 v153, v[4:7]
	ds_write_b128 v154, v[12:15]
	ds_write_b128 v155, v[16:19]
	ds_write_b128 v156, v[20:23]
	ds_write_b128 v157, v[24:27]
	ds_write_b128 v158, v[28:31]
	ds_write_b128 v159, v[32:35]
	v_cmp_gt_f32_e32 vcc, s13, v81
	s_and_b64 s[0:1], vcc, exec
	s_cselect_b32 s0, 0xffffffc0, 0
	v_cndmask_b32_e32 v0, 0, v162, vcc
	v_add_f32_e32 v0, v81, v0
	v_exp_f32_e32 v0, v0
	s_cmp_eq_u32 s18, 0
	s_cselect_b64 vcc, -1, 0
	s_add_i32 s3, s3, s2
	s_lshl_b32 s1, s3, 1
	s_or_b32 s1, s1, s18
	v_ldexp_f32 v22, v0, s0
	s_mul_hi_i32 s0, s1, 0x90000
	s_mul_i32 s1, s1, 0x90000
	v_sub_f32_e32 v6, 1.0, v22
	s_add_u32 s10, s92, s1
	v_add_f32_e32 v2, -1.0, v6
	v_frexp_mant_f32_e32 v7, v6
	v_cvt_f64_f32_e32 v[0:1], v6
	s_addc_u32 s11, s93, s0
	v_sub_f32_e32 v12, v2, v6
	v_frexp_exp_i32_f64_e32 v14, v[0:1]
	v_cmp_gt_f32_e64 s[0:1], s14, v7
	v_sub_f32_e64 v13, -v22, v2
	ds_write_b128 v160, v[8:11]
	v_add_f32_e32 v8, 1.0, v12
	v_subbrev_co_u32_e64 v14, s[0:1], 0, v14, s[0:1]
	v_add_f32_e32 v7, v13, v8
	v_sub_u32_e32 v8, 0, v14
	v_ldexp_f32 v6, v6, v8
	v_ldexp_f32 v7, v7, v8
	v_add_f32_e32 v8, -1.0, v6
	v_add_f32_e32 v9, 1.0, v6
	v_add_f32_e32 v10, 1.0, v8
	v_add_f32_e32 v11, -1.0, v9
	v_sub_f32_e32 v10, v6, v10
	v_sub_f32_e32 v6, v6, v11
	v_add_f32_e32 v6, v7, v6
	v_add_f32_e32 v15, v9, v6
	v_rcp_f32_e32 v17, v15
	v_add_f32_e32 v10, v7, v10
	v_sub_f32_e32 v7, v15, v9
	v_sub_f32_e32 v16, v6, v7
	v_add_f32_e32 v7, v8, v10
	v_mul_f32_e32 v19, v7, v17
	v_sub_f32_e32 v6, v7, v8
	v_mul_f32_e32 v8, v15, v19
	v_sub_f32_e32 v18, v10, v6
	v_fma_f32 v10, v19, v15, -v8
	v_fmac_f32_e32 v10, v19, v16
	v_add_f32_e32 v6, v8, v10
	v_sub_f32_e32 v9, v7, v6
	v_pk_add_f32 v[12:13], v[6:7], v[8:9] neg_lo:[0,1] neg_hi:[0,1]
	v_mov_b32_e32 v11, v6
	v_pk_add_f32 v[6:7], v[12:13], v[10:11] neg_lo:[0,1] neg_hi:[0,1]
	v_cmp_nlt_f32_e64 s[0:1], 1.0, v22
	v_add_f32_e32 v7, v18, v7
	v_add_f32_e32 v6, v6, v7
	v_add_f32_e32 v7, v9, v6
	v_mul_f32_e32 v18, v17, v7
	v_mul_f32_e32 v8, v15, v18
	v_fma_f32 v10, v18, v15, -v8
	v_fmac_f32_e32 v10, v18, v16
	v_sub_f32_e32 v9, v9, v7
	v_add_f32_e32 v15, v6, v9
	v_add_f32_e32 v6, v8, v10
	v_sub_f32_e32 v9, v7, v6
	v_pk_add_f32 v[12:13], v[6:7], v[8:9] neg_lo:[0,1] neg_hi:[0,1]
	v_mov_b32_e32 v11, v6
	v_pk_add_f32 v[6:7], v[12:13], v[10:11] neg_lo:[0,1] neg_hi:[0,1]
	s_lshl_b32 s8, s18, 8
	v_add_f32_e32 v7, v15, v7
	v_add_f32_e32 v6, v6, v7
	v_add_f32_e32 v7, v19, v18
	v_add_f32_e32 v6, v9, v6
	v_sub_f32_e32 v8, v7, v19
	v_mul_f32_e32 v6, v17, v6
	v_sub_f32_e32 v8, v18, v8
	v_add_f32_e32 v8, v8, v6
	v_add_f32_e32 v10, v7, v8
	v_mul_f32_e32 v11, v10, v10
	v_fmamk_f32 v6, v11, 0x3e9b6dac, v161
	v_fmaak_f32 v83, v11, v6, 0x3f2aaada
	v_cvt_f32_i32_e32 v6, v14
	v_sub_f32_e32 v7, v10, v7
	v_sub_f32_e32 v7, v8, v7
	v_ldexp_f32 v12, v7, 1
	v_mul_f32_e32 v7, v10, v11
	v_ldexp_f32 v9, v10, 1
	v_pk_mul_f32 v[10:11], v[6:7], v[82:83]
	v_lshl_add_u64 v[4:5], v[84:85], 0, s[8:9]
	v_fma_f32 v8, v6, s15, -v10
	v_fmac_f32_e32 v8, 0xb102e308, v6
	v_pk_add_f32 v[6:7], v[10:11], v[8:9]
; #define LAS __attribute__((address_space(3)))
; DI float ret_lg2(const Params& p, int l, int dir, int h) { return log1pf(-exp2f(p.in[12][(l * 2 + dir) * 5 + h])) * 1.4426950408889634f; }
; DI void phase_ret_scan(const Params& p, int l, LAS unsigned char* lds) {
;     ...
;         const float lg = ret_lg2(p, l, dir, h), gL = exp2f(lg * 128.f);
;         float wt[4][8];
; #pragma unroll
;         for (int ks = 0; ks < 4; ++ks)
; #pragma unroll
;             for (int e = 0; e < 8; ++e) { const int pp = ks * 32 + q4 * 8 + e; wt[ks][e] = exp2f(lg * (float)(dir == 0 ? 127 - pp : pp)); }
;         const bf16_t* kt = (const bf16_t*)(ws + WS_KTR) + ((size_t)b * 640 + h * 128 + dkb * 16 + r16) * RB + q4 * 8;
;         const LAS unsigned char* vl = lds + r16 * VRS + q4 * 16;
;         bf16_t* sb = (bf16_t*)(ws + WS_S) + ((size_t)((b * 5 + h) * 2 + dir) * 18) * 16384 + (dvb * 16 + r16) * 128 + dkb * 16 + q4 * 4;
;         f32x4 st = (f32x4){0.f, 0.f, 0.f, 0.f};
;         bf16x8 ca[4];
;         { const int c0 = dir == 0 ? 0 : 1;
; #pragma unroll
;           for (int ks = 0; ks < 4; ++ks) ca[ks] = *(const bf16x8*)(kt + c0 * 128 + ks * 32); }
	global_load_dwordx4 v[0:3], v[4:5], off
	v_sub_f32_e32 v9, v7, v9
	v_sub_f32_e32 v9, v11, v9
	v_add_f32_e32 v13, v12, v9
	v_mov_b32_e32 v12, v10
	v_pk_add_f32 v[10:11], v[6:7], v[10:11] neg_lo:[0,1] neg_hi:[0,1]
	v_pk_add_f32 v[14:15], v[6:7], v[12:13]
	v_mov_b32_e32 v9, v6
	v_mov_b32_e32 v11, v15
	v_pk_add_f32 v[16:17], v[8:9], v[10:11] neg_lo:[0,1] neg_hi:[0,1]
	v_pk_add_f32 v[8:9], v[8:9], v[10:11]
	v_mov_b32_e32 v20, v7
	v_pk_add_f32 v[10:11], v[8:9], v[6:7] op_sel:[1,0] op_sel_hi:[0,1] neg_lo:[0,1] neg_hi:[0,1]
	v_pk_add_f32 v[18:19], v[14:15], v[10:11] op_sel_hi:[1,0] neg_lo:[0,1] neg_hi:[0,1]
	v_mov_b32_e32 v14, v15
	v_mov_b32_e32 v15, v9
	v_mov_b32_e32 v21, v10
	v_pk_add_f32 v[10:11], v[14:15], v[20:21] neg_lo:[0,1] neg_hi:[0,1]
	v_mov_b32_e32 v12, v13
	v_mov_b32_e32 v13, v6
	v_pk_add_f32 v[6:7], v[12:13], v[10:11] neg_lo:[0,1] neg_hi:[0,1]
	v_mov_b32_e32 v18, v16
	v_pk_add_f32 v[10:11], v[18:19], v[6:7]
	v_mov_b32_e32 v17, v9
	v_pk_add_f32 v[12:13], v[10:11], v[10:11] op_sel:[0,1] op_sel_hi:[1,0]
	v_mov_b32_e32 v81, v41
	v_pk_add_f32 v[8:9], v[8:9], v[12:13] op_sel:[1,0] op_sel_hi:[0,1]
	v_mov_b32_e32 v11, v8
	v_pk_add_f32 v[14:15], v[10:11], v[16:17] neg_lo:[0,1] neg_hi:[0,1]
	v_mov_b32_e32 v7, v12
	v_sub_f32_e32 v9, v10, v14
	v_pk_add_f32 v[6:7], v[6:7], v[14:15] neg_lo:[0,1] neg_hi:[0,1]
	v_sub_f32_e32 v9, v16, v9
	v_add_f32_e32 v6, v6, v9
	v_add_f32_e32 v6, v6, v7
	v_add_f32_e32 v6, v8, v6
	v_cndmask_b32_e64 v6, v163, v6, s[0:1]
	v_cmp_neq_f32_e64 s[0:1], 1.0, v22
	s_mov_b32 s8, 0
	s_nop 0
	v_cndmask_b32_e64 v6, v164, v6, s[0:1]
	v_cmp_lt_f32_e64 s[0:1], |v22|, s16
	s_nop 1
	v_cndmask_b32_e64 v6, v6, -v22, s[0:1]
	v_mul_f32_e32 v18, 0x3fb8aa3b, v6
	v_cndmask_b32_e32 v6, v87, v89, vcc
	v_cvt_f32_ubyte0_e32 v6, v6
	v_mul_f32_e32 v7, v18, v6
	v_cmp_gt_f32_e64 s[0:1], s13, v7
	v_mul_f32_e32 v19, 0x43000000, v18
	v_mov_b32_e32 v22, 0
	v_cndmask_b32_e64 v7, 0, v162, s[0:1]
	v_fmac_f32_e32 v7, v18, v6
	v_exp_f32_e32 v6, v7
	v_cndmask_b32_e64 v7, 0, v165, s[0:1]
	v_mov_b32_e32 v23, v22
	v_mov_b32_e32 v24, v22
	v_ldexp_f32 v26, v6, v7
	v_cndmask_b32_e32 v6, v90, v91, vcc
	v_cvt_f32_ubyte0_e32 v6, v6
	v_mul_f32_e32 v7, v18, v6
	v_cmp_gt_f32_e64 s[0:1], s13, v7
	v_mov_b32_e32 v25, v22
	s_nop 0
	v_cndmask_b32_e64 v7, 0, v162, s[0:1]
	v_fmac_f32_e32 v7, v18, v6
	v_exp_f32_e32 v6, v7
	v_cndmask_b32_e32 v7, v92, v93, vcc
	v_cvt_f32_ubyte0_e32 v7, v7
	v_mul_f32_e32 v8, v18, v7
	v_cmp_gt_f32_e64 s[2:3], s13, v8
	s_nop 1
	v_cndmask_b32_e64 v8, 0, v162, s[2:3]
	v_fmac_f32_e32 v8, v18, v7
	v_exp_f32_e32 v7, v8
	v_cndmask_b32_e64 v8, 0, v165, s[0:1]
	v_ldexp_f32 v27, v6, v8
	v_cndmask_b32_e64 v6, 0, v165, s[2:3]
	v_ldexp_f32 v28, v7, v6
	v_cndmask_b32_e32 v6, v94, v95, vcc
	v_cvt_f32_ubyte0_e32 v6, v6
	v_mul_f32_e32 v7, v18, v6
	v_cmp_gt_f32_e64 s[0:1], s13, v7
	s_nop 1
	v_cndmask_b32_e64 v7, 0, v162, s[0:1]
	v_fmac_f32_e32 v7, v18, v6
	v_exp_f32_e32 v6, v7
	v_cndmask_b32_e32 v7, v96, v97, vcc
	v_cvt_f32_ubyte0_e32 v7, v7
	v_mul_f32_e32 v8, v18, v7
	v_cmp_gt_f32_e64 s[2:3], s13, v8
	s_nop 1
	v_cndmask_b32_e64 v8, 0, v162, s[2:3]
	v_fmac_f32_e32 v8, v18, v7
	v_exp_f32_e32 v7, v8
	v_cndmask_b32_e64 v8, 0, v165, s[0:1]
	v_ldexp_f32 v29, v6, v8
	v_cndmask_b32_e64 v6, 0, v165, s[2:3]
	v_ldexp_f32 v30, v7, v6
	v_cndmask_b32_e32 v6, v98, v99, vcc
	v_cvt_f32_ubyte0_e32 v6, v6
	v_mul_f32_e32 v7, v18, v6
	v_cmp_gt_f32_e64 s[0:1], s13, v7
	s_nop 1
	v_cndmask_b32_e64 v7, 0, v162, s[0:1]
	v_fmac_f32_e32 v7, v18, v6
	v_exp_f32_e32 v6, v7
	v_cndmask_b32_e32 v7, v100, v101, vcc
	v_cvt_f32_ubyte0_e32 v7, v7
	v_mul_f32_e32 v8, v18, v7
	v_cmp_gt_f32_e64 s[2:3], s13, v8
	s_nop 1
	v_cndmask_b32_e64 v8, 0, v162, s[2:3]
	v_fmac_f32_e32 v8, v18, v7
	v_exp_f32_e32 v7, v8
	v_cndmask_b32_e64 v8, 0, v165, s[0:1]
	v_ldexp_f32 v31, v6, v8
	v_cndmask_b32_e64 v6, 0, v165, s[2:3]
	v_ldexp_f32 v32, v7, v6
	v_cndmask_b32_e32 v6, v102, v103, vcc
	v_cvt_f32_ubyte0_e32 v6, v6
	v_mul_f32_e32 v7, v18, v6
	v_cmp_gt_f32_e64 s[0:1], s13, v7
	s_nop 1
	v_cndmask_b32_e64 v7, 0, v162, s[0:1]
	v_fmac_f32_e32 v7, v18, v6
	v_exp_f32_e32 v6, v7
	v_cndmask_b32_e32 v7, v104, v105, vcc
	v_cvt_f32_ubyte0_e32 v7, v7
	v_mul_f32_e32 v8, v18, v7
	v_cmp_gt_f32_e64 s[2:3], s13, v8
	s_nop 1
	v_cndmask_b32_e64 v8, 0, v162, s[2:3]
	v_fmac_f32_e32 v8, v18, v7
	v_exp_f32_e32 v7, v8
	v_cndmask_b32_e64 v8, 0, v165, s[0:1]
	v_ldexp_f32 v33, v6, v8
	v_cndmask_b32_e64 v6, 0, v165, s[2:3]
	v_ldexp_f32 v34, v7, v6
	v_cndmask_b32_e32 v6, v106, v107, vcc
	v_cvt_f32_ubyte0_e32 v6, v6
	v_mul_f32_e32 v7, v18, v6
	v_cmp_gt_f32_e64 s[0:1], s13, v7
	s_nop 1
	v_cndmask_b32_e64 v7, 0, v162, s[0:1]
	v_fmac_f32_e32 v7, v18, v6
	v_exp_f32_e32 v6, v7
	v_cndmask_b32_e32 v7, v108, v109, vcc
	v_cvt_f32_ubyte0_e32 v7, v7
	v_mul_f32_e32 v8, v18, v7
	v_cmp_gt_f32_e64 s[2:3], s13, v8
	s_nop 1
	v_cndmask_b32_e64 v8, 0, v162, s[2:3]
	v_fmac_f32_e32 v8, v18, v7
	v_exp_f32_e32 v7, v8
	v_cndmask_b32_e64 v8, 0, v165, s[0:1]
	v_ldexp_f32 v35, v6, v8
	v_cndmask_b32_e64 v6, 0, v165, s[2:3]
	v_ldexp_f32 v83, v7, v6
	v_cndmask_b32_e32 v6, v110, v111, vcc
	v_cvt_f32_ubyte0_e32 v6, v6
	v_mul_f32_e32 v7, v18, v6
	v_cmp_gt_f32_e64 s[0:1], s13, v7
	s_nop 1
	v_cndmask_b32_e64 v7, 0, v162, s[0:1]
	v_fmac_f32_e32 v7, v18, v6
	v_exp_f32_e32 v6, v7
	v_cndmask_b32_e32 v7, v112, v113, vcc
	v_cvt_f32_ubyte0_e32 v7, v7
	v_mul_f32_e32 v8, v18, v7
	v_cmp_gt_f32_e64 s[2:3], s13, v8
	s_nop 1
	v_cndmask_b32_e64 v8, 0, v162, s[2:3]
	v_fmac_f32_e32 v8, v18, v7
	v_exp_f32_e32 v7, v8
	v_cndmask_b32_e64 v8, 0, v165, s[0:1]
	v_ldexp_f32 v166, v6, v8
	v_cndmask_b32_e64 v6, 0, v165, s[2:3]
	v_ldexp_f32 v167, v7, v6
	v_cndmask_b32_e32 v6, v114, v115, vcc
	v_cvt_f32_ubyte0_e32 v6, v6
; #define LAS __attribute__((address_space(3)))
; DI float ret_lg2(const Params& p, int l, int dir, int h) { return log1pf(-exp2f(p.in[12][(l * 2 + dir) * 5 + h])) * 1.4426950408889634f; }
; DI void phase_ret_scan(const Params& p, int l, LAS unsigned char* lds) {
;     ...
;         const float lg = ret_lg2(p, l, dir, h), gL = exp2f(lg * 128.f);
;         float wt[4][8];
; #pragma unroll
;         for (int ks = 0; ks < 4; ++ks)
; #pragma unroll
;             for (int e = 0; e < 8; ++e) { const int pp = ks * 32 + q4 * 8 + e; wt[ks][e] = exp2f(lg * (float)(dir == 0 ? 127 - pp : pp)); }
;         const bf16_t* kt = (const bf16_t*)(ws + WS_KTR) + ((size_t)b * 640 + h * 128 + dkb * 16 + r16) * RB + q4 * 8;
;         const LAS unsigned char* vl = lds + r16 * VRS + q4 * 16;
;         bf16_t* sb = (bf16_t*)(ws + WS_S) + ((size_t)((b * 5 + h) * 2 + dir) * 18) * 16384 + (dvb * 16 + r16) * 128 + dkb * 16 + q4 * 4;
;         f32x4 st = (f32x4){0.f, 0.f, 0.f, 0.f};
;         bf16x8 ca[4];
;         { const int c0 = dir == 0 ? 0 : 1;
; #pragma unroll
;           for (int ks = 0; ks < 4; ++ks) ca[ks] = *(const bf16x8*)(kt + c0 * 128 + ks * 32); }
;         __syncthreads();
; #pragma unroll 2
	v_mul_f32_e32 v7, v18, v6
	v_cmp_gt_f32_e64 s[0:1], s13, v7
	s_nop 1
	v_cndmask_b32_e64 v7, 0, v162, s[0:1]
	v_fmac_f32_e32 v7, v18, v6
	v_exp_f32_e32 v6, v7
	v_cndmask_b32_e32 v7, v116, v117, vcc
	v_cvt_f32_ubyte0_e32 v7, v7
	v_mul_f32_e32 v8, v18, v7
	v_cmp_gt_f32_e64 s[2:3], s13, v8
	s_nop 1
	v_cndmask_b32_e64 v8, 0, v162, s[2:3]
	v_fmac_f32_e32 v8, v18, v7
	v_exp_f32_e32 v7, v8
	v_cndmask_b32_e64 v8, 0, v165, s[0:1]
	v_ldexp_f32 v168, v6, v8
	v_cndmask_b32_e64 v6, 0, v165, s[2:3]
	v_ldexp_f32 v169, v7, v6
	v_cndmask_b32_e32 v6, v118, v119, vcc
	v_cvt_f32_ubyte0_e32 v6, v6
	v_mul_f32_e32 v7, v18, v6
	v_cmp_gt_f32_e64 s[0:1], s13, v7
	s_nop 1
	v_cndmask_b32_e64 v7, 0, v162, s[0:1]
	v_fmac_f32_e32 v7, v18, v6
	v_exp_f32_e32 v6, v7
	v_cndmask_b32_e32 v7, v120, v121, vcc
	v_cvt_f32_ubyte0_e32 v7, v7
	v_mul_f32_e32 v8, v18, v7
	v_cmp_gt_f32_e64 s[2:3], s13, v8
	s_nop 1
	v_cndmask_b32_e64 v8, 0, v162, s[2:3]
	v_fmac_f32_e32 v8, v18, v7
	v_exp_f32_e32 v7, v8
	v_cndmask_b32_e64 v8, 0, v165, s[0:1]
	v_ldexp_f32 v170, v6, v8
	v_cndmask_b32_e64 v6, 0, v165, s[2:3]
	v_ldexp_f32 v171, v7, v6
	v_cndmask_b32_e32 v6, v122, v123, vcc
	v_cvt_f32_ubyte0_e32 v6, v6
	v_mul_f32_e32 v7, v18, v6
	v_cmp_gt_f32_e64 s[0:1], s13, v7
	s_nop 1
	v_cndmask_b32_e64 v7, 0, v162, s[0:1]
	v_fmac_f32_e32 v7, v18, v6
	v_exp_f32_e32 v6, v7
	v_cndmask_b32_e32 v7, v124, v125, vcc
	v_cvt_f32_ubyte0_e32 v7, v7
	v_mul_f32_e32 v8, v18, v7
	v_cmp_gt_f32_e64 s[2:3], s13, v8
	s_nop 1
	v_cndmask_b32_e64 v8, 0, v162, s[2:3]
	v_fmac_f32_e32 v8, v18, v7
	v_exp_f32_e32 v7, v8
	v_cndmask_b32_e64 v8, 0, v165, s[0:1]
	v_ldexp_f32 v172, v6, v8
	v_cndmask_b32_e64 v6, 0, v165, s[2:3]
	v_ldexp_f32 v173, v7, v6
	v_cndmask_b32_e32 v6, v126, v127, vcc
	v_cvt_f32_ubyte0_e32 v6, v6
	v_mul_f32_e32 v7, v18, v6
	v_cmp_gt_f32_e64 s[0:1], s13, v7
	s_nop 1
	v_cndmask_b32_e64 v7, 0, v162, s[0:1]
	v_fmac_f32_e32 v7, v18, v6
	v_exp_f32_e32 v6, v7
	v_cndmask_b32_e32 v7, v128, v129, vcc
	v_cvt_f32_ubyte0_e32 v7, v7
	v_mul_f32_e32 v8, v18, v7
	v_cmp_gt_f32_e64 s[2:3], s13, v8
	s_nop 1
	v_cndmask_b32_e64 v8, 0, v162, s[2:3]
	v_fmac_f32_e32 v8, v18, v7
	v_exp_f32_e32 v7, v8
	v_cndmask_b32_e64 v8, 0, v165, s[0:1]
	v_ldexp_f32 v174, v6, v8
	v_cndmask_b32_e64 v6, 0, v165, s[2:3]
	v_ldexp_f32 v175, v7, v6
	v_cndmask_b32_e32 v6, v130, v131, vcc
	v_cvt_f32_ubyte0_e32 v6, v6
	v_mul_f32_e32 v7, v18, v6
	v_cmp_gt_f32_e64 s[0:1], s13, v7
	s_nop 1
	v_cndmask_b32_e64 v7, 0, v162, s[0:1]
	v_fmac_f32_e32 v7, v18, v6
	v_exp_f32_e32 v6, v7
	v_cndmask_b32_e32 v7, v132, v133, vcc
	v_cvt_f32_ubyte0_e32 v7, v7
	v_mul_f32_e32 v8, v18, v7
	v_cmp_gt_f32_e64 s[2:3], s13, v8
	s_nop 1
	v_cndmask_b32_e64 v8, 0, v162, s[2:3]
	v_fmac_f32_e32 v8, v18, v7
	v_exp_f32_e32 v7, v8
	v_cndmask_b32_e64 v8, 0, v165, s[0:1]
	v_ldexp_f32 v176, v6, v8
	v_cndmask_b32_e64 v6, 0, v165, s[2:3]
	v_ldexp_f32 v177, v7, v6
	v_cndmask_b32_e32 v6, v134, v135, vcc
	v_cvt_f32_ubyte0_e32 v6, v6
	v_mul_f32_e32 v7, v18, v6
	v_cmp_gt_f32_e64 s[0:1], s13, v7
	s_nop 1
	v_cndmask_b32_e64 v7, 0, v162, s[0:1]
	v_fmac_f32_e32 v7, v18, v6
	v_exp_f32_e32 v6, v7
	v_cndmask_b32_e32 v7, v136, v137, vcc
	v_cvt_f32_ubyte0_e32 v7, v7
	v_mul_f32_e32 v8, v18, v7
	v_cmp_gt_f32_e64 s[2:3], s13, v8
	s_nop 1
	v_cndmask_b32_e64 v8, 0, v162, s[2:3]
	v_fmac_f32_e32 v8, v18, v7
	v_exp_f32_e32 v7, v8
	v_cndmask_b32_e64 v8, 0, v165, s[0:1]
	v_ldexp_f32 v178, v6, v8
	v_cndmask_b32_e64 v6, 0, v165, s[2:3]
	v_ldexp_f32 v179, v7, v6
	v_cndmask_b32_e32 v6, v138, v139, vcc
	v_cvt_f32_ubyte0_e32 v6, v6
	v_mul_f32_e32 v7, v18, v6
	v_cmp_gt_f32_e64 s[0:1], s13, v7
	s_nop 1
	v_cndmask_b32_e64 v7, 0, v162, s[0:1]
	v_fmac_f32_e32 v7, v18, v6
	v_exp_f32_e32 v16, v7
	global_load_dwordx4 v[12:15], v[4:5], off offset:64
	global_load_dwordx4 v[8:11], v[4:5], off offset:128
	s_nop 0
	global_load_dwordx4 v[4:7], v[4:5], off offset:192
	v_cndmask_b32_e64 v17, 0, v165, s[0:1]
	s_waitcnt lgkmcnt(0)
	v_ldexp_f32 v180, v16, v17
	v_cndmask_b32_e32 v16, v140, v141, vcc
	v_cvt_f32_ubyte0_e32 v16, v16
	v_mul_f32_e32 v17, v18, v16
	v_cmp_gt_f32_e64 s[0:1], s13, v17
	s_barrier
	s_nop 0
	v_cndmask_b32_e64 v17, 0, v162, s[0:1]
	v_fmac_f32_e32 v17, v18, v16
	v_exp_f32_e32 v16, v17
	v_cndmask_b32_e32 v17, v142, v143, vcc
	v_cvt_f32_ubyte0_e32 v17, v17
	v_mul_f32_e32 v20, v18, v17
	v_cmp_gt_f32_e64 s[2:3], s13, v20
	s_nop 1
	v_cndmask_b32_e64 v20, 0, v162, s[2:3]
	v_fmac_f32_e32 v20, v18, v17
	v_exp_f32_e32 v17, v20
	v_cndmask_b32_e64 v20, 0, v165, s[0:1]
	v_ldexp_f32 v181, v16, v20
	v_cndmask_b32_e64 v16, 0, v165, s[2:3]
	v_ldexp_f32 v182, v17, v16
	v_cndmask_b32_e32 v16, v144, v145, vcc
	v_cvt_f32_ubyte0_e32 v16, v16
	v_mul_f32_e32 v17, v18, v16
	v_cmp_gt_f32_e64 s[0:1], s13, v17
	s_nop 1
	v_cndmask_b32_e64 v17, 0, v162, s[0:1]
	v_fmac_f32_e32 v17, v18, v16
	v_exp_f32_e32 v16, v17
	v_cndmask_b32_e32 v17, v146, v147, vcc
	v_cvt_f32_ubyte0_e32 v17, v17
	v_mul_f32_e32 v20, v18, v17
	v_cmp_gt_f32_e64 s[2:3], s13, v20
	s_nop 1
	v_cndmask_b32_e64 v20, 0, v162, s[2:3]
	v_fmac_f32_e32 v20, v18, v17
	v_exp_f32_e32 v17, v20
	v_cndmask_b32_e64 v20, 0, v165, s[0:1]
	v_ldexp_f32 v183, v16, v20
	v_cndmask_b32_e64 v16, 0, v165, s[2:3]
	v_ldexp_f32 v184, v17, v16
	v_cndmask_b32_e32 v16, v148, v149, vcc
	v_cvt_f32_ubyte0_e32 v16, v16
	v_mul_f32_e32 v17, v18, v16
	v_cmp_gt_f32_e64 s[0:1], s13, v17
	s_nop 1
	v_cndmask_b32_e64 v17, 0, v162, s[0:1]
	v_fmac_f32_e32 v17, v18, v16
	v_exp_f32_e32 v16, v17
	v_cndmask_b32_e32 v17, v150, v151, vcc
	v_cvt_f32_ubyte0_e32 v17, v17
	v_mul_f32_e32 v20, v18, v17
	v_cmp_gt_f32_e64 s[2:3], s13, v20
	s_nop 1
	v_cndmask_b32_e64 v20, 0, v162, s[2:3]
	v_fmac_f32_e32 v20, v18, v17
	v_exp_f32_e32 v17, v20
	v_cndmask_b32_e64 v20, 0, v165, s[0:1]
	v_cmp_gt_f32_e64 s[0:1], s13, v19
	v_ldexp_f32 v185, v16, v20
	v_cndmask_b32_e64 v16, 0, v165, s[2:3]
	v_cndmask_b32_e64 v19, 0, v162, s[0:1]
	v_fmac_f32_e32 v19, 0x43000000, v18
	v_exp_f32_e32 v18, v19
	v_ldexp_f32 v186, v17, v16
	v_or_b32_e32 v16, s17, v86
	v_lshlrev_b32_e32 v40, 8, v16
	s_and_b64 s[0:1], s[0:1], exec
	v_lshl_add_u64 v[16:17], s[10:11], 0, v[40:41]
	s_cselect_b32 s0, 0xffffffc0, 0
	v_lshl_add_u64 v[16:17], v[36:37], 1, v[16:17]
	v_ldexp_f32 v18, v18, s0
	v_lshl_add_u64 v[16:17], v[16:17], 0, v[80:81]
	v_mov_b32_e32 v20, v18
	v_mov_b32_e32 v21, v18
	s_mov_b32 s0, 0
	s_waitcnt vmcnt(0)
; #define LAS __attribute__((address_space(3)))
; DI void st_bf16x4(bf16_t* p, f32x4 v) { u32x2 w; w.x = cvt_pk_bf16(v[0], v[1]); w.y = cvt_pk_bf16(v[2], v[3]); *(u32x2*)p = w; }
; #define MFMA16(a, b, c) __builtin_amdgcn_mfma_f32_16x16x32_bf16((a), (b), (c), 0, 0, 0)
; DI void phase_ret_scan(const Params& p, int l, LAS unsigned char* lds) {
;     ...
;         for (int step = 0; step < 18; ++step) {
;             const int c = dir == 0 ? step : (step < 2 ? 1 - step : 19 - step);
;             const int sn = step < 17 ? step + 1 : 17;
;             const int cn = dir == 0 ? sn : (sn < 2 ? 1 - sn : 19 - sn);
;             bf16x8 na_[4];
; #pragma unroll
;             for (int ks = 0; ks < 4; ++ks) na_[ks] = *(const bf16x8*)(kt + cn * 128 + ks * 32);
;             st_bf16x4(sb + (size_t)c * 16384, st);
;             f32x4 u = (f32x4){0.f, 0.f, 0.f, 0.f};
; #pragma unroll
;             for (int ks = 0; ks < 4; ++ks) u = MFMA16(scale_bf16x8(ca[ks], wt[ks]), *(const LAS bf16x8*)(vl + (c * 128 + ks * 32) * 2), u);
;             st = st * gL + u;
; #pragma unroll
;             for (int ks = 0; ks < 4; ++ks) ca[ks] = na_[ks];
;         }
.LBB0_2531:
	s_cmp_eq_u32 s8, 0
	s_cselect_b32 s1, 1, 19
	s_add_i32 s1, s1, s8
	s_or_b32 s10, s0, 1
	s_add_i32 s11, s1, -1
	s_and_b64 s[2:3], vcc, exec
	s_cselect_b32 s2, s10, s11
	s_lshl_b32 s10, s2, 7
	s_waitcnt vmcnt(4)
	v_lshlrev_b32_e32 v40, 16, v0
	v_and_b32_e32 v0, 0xffff0000, v0
	v_lshlrev_b32_e32 v81, 16, v1
	v_and_b32_e32 v1, 0xffff0000, v1
	s_ashr_i32 s11, s10, 31
	v_lshlrev_b32_e32 v188, 16, v3
	s_waitcnt vmcnt(3)
	v_lshlrev_b32_e32 v189, 16, v12
	v_lshlrev_b32_e32 v190, 16, v13
	v_lshlrev_b32_e32 v191, 16, v14
	v_lshlrev_b32_e32 v192, 16, v15
	s_waitcnt vmcnt(2)
	v_lshlrev_b32_e32 v193, 16, v8
	v_lshlrev_b32_e32 v194, 16, v9
	v_lshlrev_b32_e32 v195, 16, v10
	v_lshlrev_b32_e32 v196, 16, v11
	s_waitcnt vmcnt(1)
	v_lshlrev_b32_e32 v197, 16, v4
	v_lshlrev_b32_e32 v198, 16, v5
	v_lshlrev_b32_e32 v199, 16, v6
	v_mul_f32_e32 v201, v27, v0
	v_mul_f32_e32 v208, v29, v1
	v_lshl_add_u64 v[0:1], s[10:11], 1, v[84:85]
	v_mul_f32_e32 v210, v32, v188
	v_mul_f32_e32 v212, v34, v189
	v_mul_f32_e32 v213, v83, v190
	v_mul_f32_e32 v214, v167, v191
	v_mul_f32_e32 v215, v169, v192
	v_mul_f32_e32 v216, v171, v193
	v_mul_f32_e32 v218, v173, v194
	v_mul_f32_e32 v220, v175, v195
	v_mul_f32_e32 v222, v177, v196
	v_mul_f32_e32 v224, v179, v197
	v_mul_f32_e32 v226, v181, v198
	v_mul_f32_e32 v228, v183, v199
	global_load_dwordx4 v[188:191], v[0:1], off
	global_load_dwordx4 v[192:195], v[0:1], off offset:64
	global_load_dwordx4 v[196:199], v[0:1], off offset:128
	s_and_b64 s[10:11], vcc, exec
	s_cselect_b32 s10, s0, s1
	s_ashr_i32 s11, s10, 31
	v_lshlrev_b32_e32 v187, 16, v2
	v_and_b32_e32 v2, 0xffff0000, v2
	v_and_b32_e32 v3, 0xffff0000, v3
	global_load_dwordx4 v[204:207], v[0:1], off offset:192
	v_lshl_add_u32 v232, s10, 8, v88
	s_lshl_b64 s[10:11], s[10:11], 15
	v_and_b32_e32 v4, 0xffff0000, v4
	v_and_b32_e32 v5, 0xffff0000, v5
	v_and_b32_e32 v6, 0xffff0000, v6
	v_lshlrev_b32_e32 v200, 16, v7
	v_and_b32_e32 v7, 0xffff0000, v7
	v_mul_f32_e32 v209, v31, v2
	v_mul_f32_e32 v211, v33, v3
	v_cvt_pk_bf16_f32 v0, v22, v23
	v_cvt_pk_bf16_f32 v1, v24, v25
	v_lshl_add_u64 v[2:3], v[16:17], 0, s[10:11]
	v_mul_f32_e32 v40, v26, v40
	v_mul_f32_e32 v81, v28, v81
	v_mul_f32_e32 v187, v30, v187
	v_mul_f32_e32 v225, v180, v4
	v_mul_f32_e32 v227, v182, v5
	v_mul_f32_e32 v229, v184, v6
	v_mul_f32_e32 v230, v186, v7
	global_store_dwordx2 v[2:3], v[0:1], off
	v_cvt_pk_bf16_f32 v0, v40, v201
	v_cvt_pk_bf16_f32 v1, v81, v208
	v_cvt_pk_bf16_f32 v2, v187, v209
	v_cvt_pk_bf16_f32 v3, v210, v211
	ds_read_b128 v[4:7], v232
	v_and_b32_e32 v12, 0xffff0000, v12
	v_and_b32_e32 v13, 0xffff0000, v13
	v_and_b32_e32 v14, 0xffff0000, v14
	v_and_b32_e32 v15, 0xffff0000, v15
	s_add_i32 s1, s0, 2
	v_and_b32_e32 v8, 0xffff0000, v8
	v_and_b32_e32 v9, 0xffff0000, v9
	v_and_b32_e32 v10, 0xffff0000, v10
	v_and_b32_e32 v11, 0xffff0000, v11
	v_mul_f32_e32 v12, v35, v12
	v_mul_f32_e32 v13, v166, v13
	v_mul_f32_e32 v14, v168, v14
	v_mul_f32_e32 v15, v170, v15
	s_cmp_lg_u32 s0, 16
	v_mul_f32_e32 v217, v172, v8
	v_mul_f32_e32 v219, v174, v9
	v_mul_f32_e32 v221, v176, v10
	v_mul_f32_e32 v223, v178, v11
	v_cvt_pk_bf16_f32 v8, v212, v12
	v_cvt_pk_bf16_f32 v9, v213, v13
	v_cvt_pk_bf16_f32 v10, v214, v14
	v_cvt_pk_bf16_f32 v11, v215, v15
	ds_read_b128 v[12:15], v232 offset:64
	s_cselect_b32 s0, s1, 17
	s_cmp_gt_u32 s0, 1
	s_waitcnt lgkmcnt(1)
	v_mfma_f32_16x16x32_bf16 v[0:3], v[0:3], v[4:7], 0
	s_cselect_b32 s3, 19, 1
	s_sub_i32 s3, s3, s0
	v_cvt_pk_bf16_f32 v208, v216, v217
	v_cvt_pk_bf16_f32 v209, v218, v219
	v_cvt_pk_bf16_f32 v210, v220, v221
	v_cvt_pk_bf16_f32 v211, v222, v223
	ds_read_b128 v[212:215], v232 offset:128
	s_and_b64 s[10:11], vcc, exec
	s_cselect_b32 s0, s0, s3
	s_waitcnt lgkmcnt(1)
	v_mfma_f32_16x16x32_bf16 v[4:7], v[8:11], v[12:15], v[0:3]
	s_lshl_b32 s10, s0, 7
	s_ashr_i32 s11, s10, 31
	v_cvt_pk_bf16_f32 v216, v224, v225
	v_lshl_add_u64 v[224:225], s[10:11], 1, v[84:85]
	v_mul_f32_e32 v200, v185, v200
	v_cvt_pk_bf16_f32 v217, v226, v227
	v_cvt_pk_bf16_f32 v218, v228, v229
	v_cvt_pk_bf16_f32 v219, v200, v230
	ds_read_b128 v[220:223], v232 offset:192
	global_load_dwordx4 v[0:3], v[224:225], off
	s_waitcnt lgkmcnt(1)
; #define LAS __attribute__((address_space(3)))
; DI void st_bf16x4(bf16_t* p, f32x4 v) { u32x2 w; w.x = cvt_pk_bf16(v[0], v[1]); w.y = cvt_pk_bf16(v[2], v[3]); *(u32x2*)p = w; }
; #define MFMA16(a, b, c) __builtin_amdgcn_mfma_f32_16x16x32_bf16((a), (b), (c), 0, 0, 0)
; DI void phase_ret_scan(const Params& p, int l, LAS unsigned char* lds) {
;     ...
;         for (int step = 0; step < 18; ++step) {
;             const int c = dir == 0 ? step : (step < 2 ? 1 - step : 19 - step);
;             const int sn = step < 17 ? step + 1 : 17;
;             const int cn = dir == 0 ? sn : (sn < 2 ? 1 - sn : 19 - sn);
;             bf16x8 na_[4];
; #pragma unroll
;             for (int ks = 0; ks < 4; ++ks) na_[ks] = *(const bf16x8*)(kt + cn * 128 + ks * 32);
;             st_bf16x4(sb + (size_t)c * 16384, st);
;             f32x4 u = (f32x4){0.f, 0.f, 0.f, 0.f};
; #pragma unroll
;             for (int ks = 0; ks < 4; ++ks) u = MFMA16(scale_bf16x8(ca[ks], wt[ks]), *(const LAS bf16x8*)(vl + (c * 128 + ks * 32) * 2), u);
;             st = st * gL + u;
; #pragma unroll
;             for (int ks = 0; ks < 4; ++ks) ca[ks] = na_[ks];
;         }
	v_mfma_f32_16x16x32_bf16 v[208:211], v[208:211], v[212:215], v[4:7]
	global_load_dwordx4 v[12:15], v[224:225], off offset:64
	global_load_dwordx4 v[8:11], v[224:225], off offset:128
	s_nop 0
	global_load_dwordx4 v[4:7], v[224:225], off offset:192
	s_ashr_i32 s3, s2, 31
	v_mov_b32_e32 v19, v18
	s_waitcnt lgkmcnt(0)
	v_mfma_f32_16x16x32_bf16 v[208:211], v[216:219], v[220:223], v[208:211]
	v_lshl_add_u32 v231, s2, 8, v88
	s_lshl_b64 s[2:3], s[2:3], 15
	v_lshl_add_u64 v[200:201], v[16:17], 0, s[2:3]
	s_waitcnt vmcnt(8)
	v_lshlrev_b32_e32 v40, 16, v190
	v_and_b32_e32 v81, 0xffff0000, v190
	s_nop 1
	v_pk_fma_f32 v[212:213], v[18:19], v[24:25], v[210:211]
	v_pk_fma_f32 v[214:215], v[20:21], v[22:23], v[208:209]
	v_lshlrev_b32_e32 v24, 16, v189
	v_cvt_pk_bf16_f32 v22, v214, v215
	v_cvt_pk_bf16_f32 v23, v212, v213
	global_store_dwordx2 v[200:201], v[22:23], off
	v_lshlrev_b32_e32 v22, 16, v188
	v_and_b32_e32 v23, 0xffff0000, v188
	v_and_b32_e32 v25, 0xffff0000, v189
	v_and_b32_e32 v188, 0xffff0000, v191
	v_lshlrev_b32_e32 v187, 16, v191
	s_waitcnt vmcnt(8)
	v_lshlrev_b32_e32 v189, 16, v192
	v_and_b32_e32 v190, 0xffff0000, v192
	v_lshlrev_b32_e32 v191, 16, v193
	v_mul_f32_e32 v22, v26, v22
	v_mul_f32_e32 v23, v27, v23
	v_mul_f32_e32 v24, v28, v24
	v_mul_f32_e32 v25, v29, v25
	v_mul_f32_e32 v188, v33, v188
	v_mul_f32_e32 v40, v30, v40
	v_mul_f32_e32 v81, v31, v81
	v_mul_f32_e32 v187, v32, v187
	v_mul_f32_e32 v219, v34, v189
	v_mul_f32_e32 v220, v35, v190
	v_mul_f32_e32 v221, v83, v191
	v_cvt_pk_bf16_f32 v22, v22, v23
	v_cvt_pk_bf16_f32 v23, v24, v25
	v_cvt_pk_bf16_f32 v24, v40, v81
	v_cvt_pk_bf16_f32 v25, v187, v188
	ds_read_b128 v[188:191], v231
	v_and_b32_e32 v192, 0xffff0000, v193
	v_lshlrev_b32_e32 v193, 16, v194
	v_and_b32_e32 v194, 0xffff0000, v194
	v_lshlrev_b32_e32 v200, 16, v195
	v_and_b32_e32 v195, 0xffff0000, v195
	s_waitcnt vmcnt(7)
	v_lshlrev_b32_e32 v201, 16, v196
	v_and_b32_e32 v196, 0xffff0000, v196
	v_lshlrev_b32_e32 v208, 16, v197
	v_and_b32_e32 v197, 0xffff0000, v197
	v_lshlrev_b32_e32 v209, 16, v198
	v_and_b32_e32 v198, 0xffff0000, v198
	v_lshlrev_b32_e32 v210, 16, v199
	v_and_b32_e32 v199, 0xffff0000, v199
	v_mul_f32_e32 v194, v168, v194
	v_mul_f32_e32 v195, v170, v195
	v_mul_f32_e32 v222, v166, v192
	v_mul_f32_e32 v223, v167, v193
	v_mul_f32_e32 v200, v169, v200
	v_mul_f32_e32 v224, v172, v196
	v_mul_f32_e32 v225, v174, v197
	v_mul_f32_e32 v226, v176, v198
	v_mul_f32_e32 v227, v178, v199
	v_cvt_pk_bf16_f32 v192, v219, v220
	v_cvt_pk_bf16_f32 v193, v221, v222
	v_cvt_pk_bf16_f32 v194, v223, v194
	v_cvt_pk_bf16_f32 v195, v200, v195
	ds_read_b128 v[196:199], v231 offset:64
	s_waitcnt lgkmcnt(1)
	v_mfma_f32_16x16x32_bf16 v[22:25], v[22:25], v[188:191], 0
	s_waitcnt vmcnt(6)
	v_lshlrev_b32_e32 v211, 16, v204
	v_and_b32_e32 v204, 0xffff0000, v204
	v_lshlrev_b32_e32 v216, 16, v205
	v_and_b32_e32 v205, 0xffff0000, v205
	v_lshlrev_b32_e32 v217, 16, v206
	v_and_b32_e32 v206, 0xffff0000, v206
	v_lshlrev_b32_e32 v218, 16, v207
	v_and_b32_e32 v207, 0xffff0000, v207
	v_mul_f32_e32 v201, v171, v201
	v_mul_f32_e32 v208, v173, v208
	v_mul_f32_e32 v209, v175, v209
	v_mul_f32_e32 v210, v177, v210
	v_mul_f32_e32 v228, v180, v204
	v_mul_f32_e32 v229, v182, v205
	v_mul_f32_e32 v230, v184, v206
	v_mul_f32_e32 v232, v186, v207
	v_cvt_pk_bf16_f32 v204, v201, v224
	v_cvt_pk_bf16_f32 v205, v208, v225
	v_cvt_pk_bf16_f32 v206, v209, v226
	v_cvt_pk_bf16_f32 v207, v210, v227
	ds_read_b128 v[188:191], v231 offset:128
	s_waitcnt lgkmcnt(1)
	v_mfma_f32_16x16x32_bf16 v[22:25], v[192:195], v[196:199], v[22:25]
	v_mul_f32_e32 v211, v179, v211
	v_mul_f32_e32 v216, v181, v216
	v_mul_f32_e32 v217, v183, v217
	v_mul_f32_e32 v218, v185, v218
	v_cvt_pk_bf16_f32 v208, v211, v228
	v_cvt_pk_bf16_f32 v209, v216, v229
	v_cvt_pk_bf16_f32 v210, v217, v230
	v_cvt_pk_bf16_f32 v211, v218, v232
	s_waitcnt lgkmcnt(0)
	v_mfma_f32_16x16x32_bf16 v[22:25], v[204:207], v[188:191], v[22:25]
	ds_read_b128 v[188:191], v231 offset:192
	s_add_i32 s8, s8, -2
	s_mov_b32 s0, s1
	s_waitcnt lgkmcnt(0)
	v_mfma_f32_16x16x32_bf16 v[22:25], v[208:211], v[188:191], v[22:25]
	s_cmp_eq_u32 s1, 18
	s_nop 6
	v_pk_fma_f32 v[24:25], v[18:19], v[212:213], v[24:25]
	v_pk_fma_f32 v[22:23], v[20:21], v[214:215], v[22:23]
	s_cbranch_scc0 .LBB0_2531
	s_mov_b64 s[0:1], 0
	s_branch .LBB0_2524
